# background weight-conversion stores made write-through (sc1) so converted weights do not displace activations in L2; on top of v23
# speedup vs baseline: 1.0152x; 1.0152x over previous
.LBB0_804:
	s_cmp_gt_i32 s2, 0x83ff
	s_mov_b64 s[8:9], -1
	s_cbranch_scc0 .LBB0_838
	s_cmpk_gt_u32 s2, 0x89ff
	s_cbranch_scc0 .LBB0_835
	s_cmpk_gt_u32 s2, 0x8bff
	s_cbranch_scc0 .LBB0_832
	s_cmpk_gt_u32 s2, 0x8dff
	s_cbranch_scc0 .LBB0_829
	s_cmpk_gt_u32 s2, 0x8fff
	s_cbranch_scc0 .LBB0_826
	s_cmpk_gt_u32 s2, 0x93ff
	s_cbranch_scc0 .LBB0_823
	s_cmpk_gt_u32 s2, 0x95ff
	s_cbranch_scc0 .LBB0_820
	s_cmpk_gt_u32 s2, 0x9bff
	s_cbranch_scc0 .LBB0_817
	s_cmpk_gt_u32 s2, 0x9dff
	s_cbranch_scc0 .LBB0_814
	s_add_i32 s8, s2, 0xffff6200
	s_lshr_b32 s62, s8, 8
	s_load_dwordx2 s[8:9], s[60:61], 0x30
	s_lshl_b64 s[10:11], s[62:63], 21
	v_lshlrev_b32_e32 v0, 2, v2
	s_waitcnt lgkmcnt(0)
	s_add_u32 s10, s8, s10
	s_addc_u32 s11, s9, s11
	s_lshl_b64 s[8:9], s[62:63], 20
	s_add_u32 s20, s12, s8
	s_addc_u32 s9, s13, s9
	s_and_b32 s8, s18, 0x3e0
	s_and_b32 s21, s16, 0x1c0
	s_lshl_b32 s22, s8, 2
	v_add_u32_e32 v22, s21, v3
	s_add_u32 s10, s10, s22
	s_addc_u32 s11, s11, 0
	v_ashrrev_i32_e32 v23, 31, v22
	v_lshl_add_u64 v[36:37], s[10:11], 0, v[0:1]
	v_lshlrev_b64 v[22:23], 12, v[22:23]
	v_lshl_add_u64 v[22:23], v[36:37], 0, v[22:23]
	s_mov_b32 s10, 0x8000
	v_add_co_u32_e32 v40, vcc, s10, v22
	s_mov_b32 s10, 0x10000
	s_nop 0
	v_addc_co_u32_e32 v41, vcc, 0, v23, vcc
	global_load_dwordx4 v[36:39], v[22:23], off nt
	v_add_co_u32_e32 v44, vcc, s10, v22
	global_load_dwordx4 v[40:43], v[40:41], off nt
	s_nop 0
	v_addc_co_u32_e32 v45, vcc, 0, v23, vcc
	global_load_dwordx4 v[44:47], v[44:45], off nt
	v_add_co_u32_e32 v48, vcc, s41, v22
	s_mov_b32 s10, 0x30000
	s_nop 0
	v_addc_co_u32_e32 v49, vcc, 0, v23, vcc
	global_load_dwordx4 v[48:51], v[48:49], off nt
	v_add_co_u32_e32 v52, vcc, s82, v22
	v_add_u32_e32 v0, v29, v5
	s_nop 0
	v_addc_co_u32_e32 v53, vcc, 0, v23, vcc
	global_load_dwordx4 v[52:55], v[52:53], off nt
	v_add_co_u32_e32 v56, vcc, s44, v22
	s_nop 1
	v_addc_co_u32_e32 v57, vcc, 0, v23, vcc
	global_load_dwordx4 v[56:59], v[56:57], off nt
	v_add_co_u32_e32 v60, vcc, s10, v22
	s_mov_b32 s10, 0x38000
	s_nop 0
	v_addc_co_u32_e32 v61, vcc, 0, v23, vcc
	global_load_dwordx4 v[60:63], v[60:61], off nt
	v_add_co_u32_e32 v22, vcc, s10, v22
	s_lshl_b32 s10, s21, 1
	s_nop 0
	v_addc_co_u32_e32 v23, vcc, 0, v23, vcc
	global_load_dwordx4 v[64:67], v[22:23], off nt
	v_add_u32_e32 v22, 0x420, v0
	s_add_u32 s10, s20, s10
	s_addc_u32 s11, s9, 0
	s_waitcnt vmcnt(7)
	ds_write2_b32 v0, v36, v37 offset1:1
	ds_write2_b32 v0, v38, v39 offset0:2 offset1:3
	s_waitcnt vmcnt(6)
	ds_write2_b32 v22, v40, v41 offset1:1
	v_add_u32_e32 v22, 0x428, v0
	ds_write2_b32 v22, v42, v43 offset1:1
	v_add_u32_e32 v22, 0x840, v0
	s_waitcnt vmcnt(5)
	ds_write2_b32 v22, v44, v45 offset1:1
	v_add_u32_e32 v22, 0x848, v0
	ds_write2_b32 v22, v46, v47 offset1:1
	v_add_u32_e32 v22, 0xc60, v0
	v_add_u32_e32 v40, s8, v3
	s_waitcnt vmcnt(4)
	ds_write2_b32 v22, v48, v49 offset1:1
	v_add_u32_e32 v22, 0xc68, v0
	ds_write2_b32 v22, v50, v51 offset1:1
	v_add_u32_e32 v22, 0x1080, v0
	v_ashrrev_i32_e32 v41, 31, v40
	v_lshlrev_b64 v[40:41], 10, v[40:41]
	s_waitcnt vmcnt(3)
	ds_write2_b32 v22, v52, v53 offset1:1
	v_add_u32_e32 v22, 0x1088, v0
	ds_write2_b32 v22, v54, v55 offset1:1
	v_add_u32_e32 v22, 0x14a0, v0
	s_waitcnt vmcnt(2)
	ds_write2_b32 v22, v56, v57 offset1:1
	v_add_u32_e32 v22, 0x14a8, v0
	ds_write2_b32 v22, v58, v59 offset1:1
	v_add_u32_e32 v22, 0x18c0, v0
	s_waitcnt vmcnt(1)
	ds_write2_b32 v22, v60, v61 offset1:1
	v_add_u32_e32 v22, 0x18c8, v0
	ds_write2_b32 v22, v62, v63 offset1:1
	v_add_u32_e32 v22, 0x1ce0, v0
	v_add_u32_e32 v0, 0x1ce8, v0
	s_waitcnt vmcnt(0)
	ds_write2_b32 v22, v64, v65 offset1:1
	ds_write2_b32 v0, v66, v67 offset1:1
	s_waitcnt lgkmcnt(0)
	ds_read2_b32 v[42:43], v30 offset0:33 offset1:41
	ds_read2_b32 v[44:45], v30 offset1:8
	ds_read2_b32 v[46:47], v30 offset0:66 offset1:74
	ds_read2_b32 v[48:49], v30 offset0:99 offset1:107
	ds_read2_b32 v[50:51], v30 offset0:132 offset1:140
	ds_read2_b32 v[52:53], v30 offset0:165 offset1:173
	ds_read2_b32 v[54:55], v30 offset0:198 offset1:206
	ds_read2_b32 v[56:57], v30 offset0:231 offset1:239
	v_lshlrev_b32_e32 v0, 1, v4
	v_lshl_add_u64 v[22:23], s[10:11], 0, v[0:1]
	s_waitcnt lgkmcnt(6)
	v_cvt_pk_bf16_f32 v36, v44, v42
	s_waitcnt lgkmcnt(4)
	v_cvt_pk_bf16_f32 v37, v46, v48
	s_waitcnt lgkmcnt(2)
	v_cvt_pk_bf16_f32 v38, v50, v52
	s_waitcnt lgkmcnt(0)
	v_cvt_pk_bf16_f32 v39, v54, v56
	v_lshl_add_u64 v[40:41], v[22:23], 0, v[40:41]
	global_store_dwordx4 v[40:41], v[36:39], off sc1
	v_add_u32_e32 v40, s8, v24
	v_ashrrev_i32_e32 v41, 31, v40
	v_lshlrev_b64 v[40:41], 10, v[40:41]
	v_cvt_pk_bf16_f32 v36, v45, v43
	v_cvt_pk_bf16_f32 v37, v47, v49
	v_cvt_pk_bf16_f32 v38, v51, v53
	v_cvt_pk_bf16_f32 v39, v55, v57
	v_lshl_add_u64 v[40:41], v[22:23], 0, v[40:41]
	global_store_dwordx4 v[40:41], v[36:39], off sc1
	ds_read2_b32 v[42:43], v30 offset0:49 offset1:57
	ds_read2_b32 v[44:45], v30 offset0:16 offset1:24
	ds_read2_b32 v[46:47], v30 offset0:82 offset1:90
	ds_read2_b32 v[48:49], v30 offset0:115 offset1:123
	ds_read2_b32 v[50:51], v30 offset0:148 offset1:156
	ds_read2_b32 v[52:53], v30 offset0:181 offset1:189
	ds_read2_b32 v[54:55], v30 offset0:214 offset1:222
	ds_read2_b32 v[56:57], v30 offset0:247 offset1:255
	v_add_u32_e32 v40, s8, v25
	v_ashrrev_i32_e32 v41, 31, v40
	v_lshlrev_b64 v[40:41], 10, v[40:41]
	s_waitcnt lgkmcnt(6)
	v_cvt_pk_bf16_f32 v36, v44, v42
	s_waitcnt lgkmcnt(4)
	v_cvt_pk_bf16_f32 v37, v46, v48
	s_waitcnt lgkmcnt(2)
	v_cvt_pk_bf16_f32 v38, v50, v52
	s_waitcnt lgkmcnt(0)
	v_cvt_pk_bf16_f32 v39, v54, v56
	v_lshl_add_u64 v[40:41], v[22:23], 0, v[40:41]
	global_store_dwordx4 v[40:41], v[36:39], off sc1
	v_add_u32_e32 v40, s8, v26
	v_ashrrev_i32_e32 v41, 31, v40
	v_lshlrev_b64 v[40:41], 10, v[40:41]
	v_cvt_pk_bf16_f32 v36, v45, v43
	v_cvt_pk_bf16_f32 v37, v47, v49
	v_cvt_pk_bf16_f32 v38, v51, v53
	v_cvt_pk_bf16_f32 v39, v55, v57
	v_lshl_add_u64 v[22:23], v[22:23], 0, v[40:41]
	global_store_dwordx4 v[22:23], v[36:39], off sc1
	s_waitcnt lgkmcnt(0)
	s_mov_b64 s[8:9], 0
.LBB0_814:
	s_andn2_b64 vcc, exec, s[8:9]
	s_cbranch_vccnz .LBB0_816
	s_load_dwordx2 s[10:11], s[60:61], 0xf8
	s_add_i32 s8, s16, 0xc800
	s_and_b32 s9, s8, 0x1ffc0
	s_and_b32 s8, s18, 0x3e0
	s_lshl_b32 s20, s8, 2
	v_add_u32_e32 v22, s9, v3
	s_waitcnt lgkmcnt(0)
	s_add_u32 s10, s10, s20
	s_addc_u32 s11, s11, 0
	v_lshlrev_b32_e32 v0, 2, v2
	v_ashrrev_i32_e32 v23, 31, v22
	v_lshl_add_u64 v[36:37], s[10:11], 0, v[0:1]
	v_lshlrev_b64 v[22:23], 12, v[22:23]
	v_lshl_add_u64 v[22:23], v[36:37], 0, v[22:23]
	s_mov_b32 s10, 0x8000
	v_add_co_u32_e32 v40, vcc, s10, v22
	s_mov_b32 s10, 0x10000
	s_nop 0
	v_addc_co_u32_e32 v41, vcc, 0, v23, vcc
	global_load_dwordx4 v[36:39], v[22:23], off nt
	v_add_co_u32_e32 v44, vcc, s10, v22
	global_load_dwordx4 v[40:43], v[40:41], off nt
	s_nop 0
	v_addc_co_u32_e32 v45, vcc, 0, v23, vcc
	global_load_dwordx4 v[44:47], v[44:45], off nt
	v_add_co_u32_e32 v48, vcc, s41, v22
	s_mov_b32 s10, 0x30000
	s_nop 0
	v_addc_co_u32_e32 v49, vcc, 0, v23, vcc
	global_load_dwordx4 v[48:51], v[48:49], off nt
	v_add_co_u32_e32 v52, vcc, s82, v22
	v_add_u32_e32 v0, v29, v5
	s_nop 0
	v_addc_co_u32_e32 v53, vcc, 0, v23, vcc
	global_load_dwordx4 v[52:55], v[52:53], off nt
	v_add_co_u32_e32 v56, vcc, s44, v22
	s_lshl_b32 s62, s9, 1
	s_nop 0
	v_addc_co_u32_e32 v57, vcc, 0, v23, vcc
	global_load_dwordx4 v[56:59], v[56:57], off nt
	v_add_co_u32_e32 v60, vcc, s10, v22
	s_mov_b32 s10, 0x38000
	s_nop 0
	v_addc_co_u32_e32 v61, vcc, 0, v23, vcc
	global_load_dwordx4 v[60:63], v[60:61], off nt
	v_add_co_u32_e32 v22, vcc, s10, v22
	s_nop 1
	v_addc_co_u32_e32 v23, vcc, 0, v23, vcc
	global_load_dwordx4 v[64:67], v[22:23], off nt
	v_add_u32_e32 v22, 0x420, v0
	s_waitcnt vmcnt(7)
	ds_write2_b32 v0, v36, v37 offset1:1
	ds_write2_b32 v0, v38, v39 offset0:2 offset1:3
	s_waitcnt vmcnt(6)
	ds_write2_b32 v22, v40, v41 offset1:1
	v_add_u32_e32 v22, 0x428, v0
	ds_write2_b32 v22, v42, v43 offset1:1
	v_add_u32_e32 v22, 0x840, v0
	s_waitcnt vmcnt(5)
	ds_write2_b32 v22, v44, v45 offset1:1
	v_add_u32_e32 v22, 0x848, v0
	ds_write2_b32 v22, v46, v47 offset1:1
	v_add_u32_e32 v22, 0xc60, v0
	v_add_u32_e32 v40, s8, v3
	s_waitcnt vmcnt(4)
	ds_write2_b32 v22, v48, v49 offset1:1
	v_add_u32_e32 v22, 0xc68, v0
	ds_write2_b32 v22, v50, v51 offset1:1
	v_add_u32_e32 v22, 0x1080, v0
	v_ashrrev_i32_e32 v41, 31, v40
	v_lshlrev_b64 v[40:41], 11, v[40:41]
	s_waitcnt vmcnt(3)
	ds_write2_b32 v22, v52, v53 offset1:1
	v_add_u32_e32 v22, 0x1088, v0
	ds_write2_b32 v22, v54, v55 offset1:1
	v_add_u32_e32 v22, 0x14a0, v0
	s_waitcnt vmcnt(2)
	ds_write2_b32 v22, v56, v57 offset1:1
	v_add_u32_e32 v22, 0x14a8, v0
	ds_write2_b32 v22, v58, v59 offset1:1
	v_add_u32_e32 v22, 0x18c0, v0
	s_waitcnt vmcnt(1)
	ds_write2_b32 v22, v60, v61 offset1:1
	v_add_u32_e32 v22, 0x18c8, v0
	ds_write2_b32 v22, v62, v63 offset1:1
	v_add_u32_e32 v22, 0x1ce0, v0
	v_add_u32_e32 v0, 0x1ce8, v0
	s_waitcnt vmcnt(0)
	ds_write2_b32 v22, v64, v65 offset1:1
	ds_write2_b32 v0, v66, v67 offset1:1
	s_waitcnt lgkmcnt(0)
	ds_read2_b32 v[42:43], v30 offset0:33 offset1:41
	ds_read2_b32 v[44:45], v30 offset1:8
	ds_read2_b32 v[46:47], v30 offset0:66 offset1:74
	ds_read2_b32 v[48:49], v30 offset0:99 offset1:107
	ds_read2_b32 v[50:51], v30 offset0:132 offset1:140
	ds_read2_b32 v[52:53], v30 offset0:165 offset1:173
	ds_read2_b32 v[54:55], v30 offset0:198 offset1:206
	ds_read2_b32 v[56:57], v30 offset0:231 offset1:239
	v_lshl_add_u64 v[22:23], v[6:7], 0, s[62:63]
	s_waitcnt lgkmcnt(6)
	v_cvt_pk_bf16_f32 v36, v44, v42
	s_waitcnt lgkmcnt(4)
	v_cvt_pk_bf16_f32 v37, v46, v48
	s_waitcnt lgkmcnt(2)
	v_cvt_pk_bf16_f32 v38, v50, v52
	s_waitcnt lgkmcnt(0)
	v_cvt_pk_bf16_f32 v39, v54, v56
	v_lshl_add_u64 v[40:41], v[22:23], 0, v[40:41]
	global_store_dwordx4 v[40:41], v[36:39], off sc1
	v_add_u32_e32 v40, s8, v24
	v_ashrrev_i32_e32 v41, 31, v40
	v_lshlrev_b64 v[40:41], 11, v[40:41]
	v_cvt_pk_bf16_f32 v36, v45, v43
	v_cvt_pk_bf16_f32 v37, v47, v49
	v_cvt_pk_bf16_f32 v38, v51, v53
	v_cvt_pk_bf16_f32 v39, v55, v57
	v_lshl_add_u64 v[40:41], v[22:23], 0, v[40:41]
	global_store_dwordx4 v[40:41], v[36:39], off sc1
	ds_read2_b32 v[42:43], v30 offset0:49 offset1:57
	ds_read2_b32 v[44:45], v30 offset0:16 offset1:24
	ds_read2_b32 v[46:47], v30 offset0:82 offset1:90
	ds_read2_b32 v[48:49], v30 offset0:115 offset1:123
	ds_read2_b32 v[50:51], v30 offset0:148 offset1:156
	ds_read2_b32 v[52:53], v30 offset0:181 offset1:189
	ds_read2_b32 v[54:55], v30 offset0:214 offset1:222
	ds_read2_b32 v[56:57], v30 offset0:247 offset1:255
	v_add_u32_e32 v40, s8, v25
	v_ashrrev_i32_e32 v41, 31, v40
	v_lshlrev_b64 v[40:41], 11, v[40:41]
	s_waitcnt lgkmcnt(6)
	v_cvt_pk_bf16_f32 v36, v44, v42
	s_waitcnt lgkmcnt(4)
	v_cvt_pk_bf16_f32 v37, v46, v48
	s_waitcnt lgkmcnt(2)
	v_cvt_pk_bf16_f32 v38, v50, v52
	s_waitcnt lgkmcnt(0)
	v_cvt_pk_bf16_f32 v39, v54, v56
	v_lshl_add_u64 v[40:41], v[22:23], 0, v[40:41]
	global_store_dwordx4 v[40:41], v[36:39], off sc1
	v_add_u32_e32 v40, s8, v26
	v_ashrrev_i32_e32 v41, 31, v40
	v_lshlrev_b64 v[40:41], 11, v[40:41]
	v_cvt_pk_bf16_f32 v36, v45, v43
	v_cvt_pk_bf16_f32 v37, v47, v49
	v_cvt_pk_bf16_f32 v38, v51, v53
	v_cvt_pk_bf16_f32 v39, v55, v57
	v_lshl_add_u64 v[22:23], v[22:23], 0, v[40:41]
	global_store_dwordx4 v[22:23], v[36:39], off sc1
	s_waitcnt lgkmcnt(0)

.LBB0_817:
	s_andn2_b64 vcc, exec, s[8:9]
	s_cbranch_vccnz .LBB0_819
	s_add_i32 s8, s2, 0x6a00
	s_and_b32 s9, s8, 0xffff
	s_mul_i32 s9, s9, 0xaaab
	s_lshr_b32 s20, s9, 16
	s_lshr_b32 s9, s9, 22
	s_load_dwordx2 s[10:11], s[60:61], 0xf0
	s_mulk_i32 s9, 0x60
	s_sub_i32 s8, s8, s9
	s_lshl_b32 s8, s8, 5
	s_and_b32 s8, s8, 0xffe0
	s_and_b32 s9, s20, 0xffc0
	s_lshl_b32 s20, s8, 2
	s_waitcnt lgkmcnt(0)
	s_add_u32 s10, s10, s20
	v_add_u32_e32 v64, s9, v3
	s_addc_u32 s11, s11, 0
	v_lshlrev_b32_e32 v0, 2, v2
	v_lshl_add_u64 v[22:23], s[10:11], 0, v[0:1]
	v_add_u32_e32 v0, 8, v64
	v_mad_i64_i32 v[36:37], s[10:11], v64, s40, v[22:23]
	v_mad_i64_i32 v[40:41], s[10:11], v0, s40, v[22:23]
	global_load_dwordx4 v[36:39], v[36:37], off nt
	v_add_u32_e32 v0, 16, v64
	global_load_dwordx4 v[40:43], v[40:41], off nt
	v_mad_i64_i32 v[44:45], s[10:11], v0, s40, v[22:23]
	global_load_dwordx4 v[44:47], v[44:45], off nt
	v_add_u32_e32 v0, 24, v64
	v_mad_i64_i32 v[48:49], s[10:11], v0, s40, v[22:23]
	global_load_dwordx4 v[48:51], v[48:49], off nt
	v_add_u32_e32 v0, 32, v64
	v_mad_i64_i32 v[52:53], s[10:11], v0, s40, v[22:23]
	global_load_dwordx4 v[52:55], v[52:53], off nt
	v_add_u32_e32 v0, 40, v64
	v_mad_i64_i32 v[56:57], s[10:11], v0, s40, v[22:23]
	global_load_dwordx4 v[56:59], v[56:57], off nt
	v_add_u32_e32 v0, 48, v64
	v_mad_i64_i32 v[60:61], s[10:11], v0, s40, v[22:23]
	global_load_dwordx4 v[60:63], v[60:61], off nt
	v_add_u32_e32 v0, 56, v64
	v_mad_i64_i32 v[22:23], s[10:11], v0, s40, v[22:23]
	global_load_dwordx4 v[64:67], v[22:23], off nt
	v_add_u32_e32 v0, v29, v5
	v_add_u32_e32 v22, 0x420, v0
	s_lshl_b32 s62, s9, 1
	s_waitcnt vmcnt(7)
	ds_write2_b32 v0, v36, v37 offset1:1
	ds_write2_b32 v0, v38, v39 offset0:2 offset1:3
	s_waitcnt vmcnt(6)
	ds_write2_b32 v22, v40, v41 offset1:1
	v_add_u32_e32 v22, 0x428, v0
	ds_write2_b32 v22, v42, v43 offset1:1
	v_add_u32_e32 v22, 0x840, v0
	s_waitcnt vmcnt(5)
	ds_write2_b32 v22, v44, v45 offset1:1
	v_add_u32_e32 v22, 0x848, v0
	ds_write2_b32 v22, v46, v47 offset1:1
	v_add_u32_e32 v22, 0xc60, v0
	s_waitcnt vmcnt(4)
	ds_write2_b32 v22, v48, v49 offset1:1
	v_add_u32_e32 v22, 0xc68, v0
	ds_write2_b32 v22, v50, v51 offset1:1
	v_add_u32_e32 v22, 0x1080, v0
	s_waitcnt vmcnt(3)
	ds_write2_b32 v22, v52, v53 offset1:1
	v_add_u32_e32 v22, 0x1088, v0
	ds_write2_b32 v22, v54, v55 offset1:1
	v_add_u32_e32 v22, 0x14a0, v0
	s_waitcnt vmcnt(2)
	ds_write2_b32 v22, v56, v57 offset1:1
	v_add_u32_e32 v22, 0x14a8, v0
	ds_write2_b32 v22, v58, v59 offset1:1
	v_add_u32_e32 v22, 0x18c0, v0
	s_waitcnt vmcnt(1)
	ds_write2_b32 v22, v60, v61 offset1:1
	v_add_u32_e32 v22, 0x18c8, v0
	ds_write2_b32 v22, v62, v63 offset1:1
	v_add_u32_e32 v22, 0x1ce0, v0
	v_add_u32_e32 v0, 0x1ce8, v0
	s_waitcnt vmcnt(0)
	ds_write2_b32 v22, v64, v65 offset1:1
	ds_write2_b32 v0, v66, v67 offset1:1
	s_waitcnt lgkmcnt(0)
	ds_read2_b32 v[42:43], v30 offset0:33 offset1:41
	ds_read2_b32 v[44:45], v30 offset1:8
	ds_read2_b32 v[46:47], v30 offset0:66 offset1:74
	ds_read2_b32 v[48:49], v30 offset0:99 offset1:107
	ds_read2_b32 v[50:51], v30 offset0:132 offset1:140
	ds_read2_b32 v[52:53], v30 offset0:165 offset1:173
	ds_read2_b32 v[54:55], v30 offset0:198 offset1:206
	ds_read2_b32 v[56:57], v30 offset0:231 offset1:239
	v_add_u32_e32 v40, s8, v3
	v_ashrrev_i32_e32 v41, 31, v40
	v_lshl_add_u64 v[22:23], v[8:9], 0, s[62:63]
	v_lshlrev_b64 v[40:41], 11, v[40:41]
	s_waitcnt lgkmcnt(6)
	v_cvt_pk_bf16_f32 v36, v44, v42
	s_waitcnt lgkmcnt(4)
	v_cvt_pk_bf16_f32 v37, v46, v48
	s_waitcnt lgkmcnt(2)
	v_cvt_pk_bf16_f32 v38, v50, v52
	s_waitcnt lgkmcnt(0)
	v_cvt_pk_bf16_f32 v39, v54, v56
	v_lshl_add_u64 v[40:41], v[22:23], 0, v[40:41]
	global_store_dwordx4 v[40:41], v[36:39], off sc1
	v_add_u32_e32 v40, s8, v24
	v_ashrrev_i32_e32 v41, 31, v40
	v_lshlrev_b64 v[40:41], 11, v[40:41]
	v_cvt_pk_bf16_f32 v36, v45, v43
	v_cvt_pk_bf16_f32 v37, v47, v49
	v_cvt_pk_bf16_f32 v38, v51, v53
	v_cvt_pk_bf16_f32 v39, v55, v57
	v_lshl_add_u64 v[40:41], v[22:23], 0, v[40:41]
	global_store_dwordx4 v[40:41], v[36:39], off sc1
	ds_read2_b32 v[42:43], v30 offset0:49 offset1:57
	ds_read2_b32 v[44:45], v30 offset0:16 offset1:24
	ds_read2_b32 v[46:47], v30 offset0:82 offset1:90
	ds_read2_b32 v[48:49], v30 offset0:115 offset1:123
	ds_read2_b32 v[50:51], v30 offset0:148 offset1:156
	ds_read2_b32 v[52:53], v30 offset0:181 offset1:189
	ds_read2_b32 v[54:55], v30 offset0:214 offset1:222
	ds_read2_b32 v[56:57], v30 offset0:247 offset1:255
	v_add_u32_e32 v40, s8, v25
	v_ashrrev_i32_e32 v41, 31, v40
	v_lshlrev_b64 v[40:41], 11, v[40:41]
	s_waitcnt lgkmcnt(6)
	v_cvt_pk_bf16_f32 v36, v44, v42
	s_waitcnt lgkmcnt(4)
	v_cvt_pk_bf16_f32 v37, v46, v48
	s_waitcnt lgkmcnt(2)
	v_cvt_pk_bf16_f32 v38, v50, v52
	s_waitcnt lgkmcnt(0)
	v_cvt_pk_bf16_f32 v39, v54, v56
	v_lshl_add_u64 v[40:41], v[22:23], 0, v[40:41]
	global_store_dwordx4 v[40:41], v[36:39], off sc1
	v_add_u32_e32 v40, s8, v26
	v_ashrrev_i32_e32 v41, 31, v40
	v_lshlrev_b64 v[40:41], 11, v[40:41]
	v_cvt_pk_bf16_f32 v36, v45, v43
	v_cvt_pk_bf16_f32 v37, v47, v49
	v_cvt_pk_bf16_f32 v38, v51, v53
	v_cvt_pk_bf16_f32 v39, v55, v57
	v_lshl_add_u64 v[22:23], v[22:23], 0, v[40:41]
	global_store_dwordx4 v[22:23], v[36:39], off sc1
	s_waitcnt lgkmcnt(0)

.LBB0_820:
	s_andn2_b64 vcc, exec, s[8:9]
	s_cbranch_vccnz .LBB0_822
	s_load_dwordx2 s[10:11], s[60:61], 0xe8
	s_add_i32 s8, s16, 0xd800
	s_and_b32 s9, s8, 0x1ffc0
	s_and_b32 s8, s18, 0x3e0
	s_lshl_b32 s20, s8, 2
	v_add_u32_e32 v22, s9, v3
	s_waitcnt lgkmcnt(0)
	s_add_u32 s10, s10, s20
	s_addc_u32 s11, s11, 0
	v_lshlrev_b32_e32 v0, 2, v2
	v_ashrrev_i32_e32 v23, 31, v22
	v_lshl_add_u64 v[36:37], s[10:11], 0, v[0:1]
	v_lshlrev_b64 v[22:23], 12, v[22:23]
	v_lshl_add_u64 v[22:23], v[36:37], 0, v[22:23]
	s_mov_b32 s10, 0x8000
	v_add_co_u32_e32 v40, vcc, s10, v22
	s_mov_b32 s10, 0x10000
	s_nop 0
	v_addc_co_u32_e32 v41, vcc, 0, v23, vcc
	global_load_dwordx4 v[36:39], v[22:23], off nt
	v_add_co_u32_e32 v44, vcc, s10, v22
	global_load_dwordx4 v[40:43], v[40:41], off nt
	s_nop 0
	v_addc_co_u32_e32 v45, vcc, 0, v23, vcc
	global_load_dwordx4 v[44:47], v[44:45], off nt
	v_add_co_u32_e32 v48, vcc, s41, v22
	s_mov_b32 s10, 0x30000
	s_nop 0
	v_addc_co_u32_e32 v49, vcc, 0, v23, vcc
	global_load_dwordx4 v[48:51], v[48:49], off nt
	v_add_co_u32_e32 v52, vcc, s82, v22
	v_add_u32_e32 v0, v29, v5
	s_nop 0
	v_addc_co_u32_e32 v53, vcc, 0, v23, vcc
	global_load_dwordx4 v[52:55], v[52:53], off nt
	v_add_co_u32_e32 v56, vcc, s44, v22
	s_lshl_b32 s62, s9, 1
	s_nop 0
	v_addc_co_u32_e32 v57, vcc, 0, v23, vcc
	global_load_dwordx4 v[56:59], v[56:57], off nt
	v_add_co_u32_e32 v60, vcc, s10, v22
	s_mov_b32 s10, 0x38000
	s_nop 0
	v_addc_co_u32_e32 v61, vcc, 0, v23, vcc
	global_load_dwordx4 v[60:63], v[60:61], off nt
	v_add_co_u32_e32 v22, vcc, s10, v22
	s_nop 1
	v_addc_co_u32_e32 v23, vcc, 0, v23, vcc
	global_load_dwordx4 v[64:67], v[22:23], off nt
	v_add_u32_e32 v22, 0x420, v0
	s_waitcnt vmcnt(7)
	ds_write2_b32 v0, v36, v37 offset1:1
	ds_write2_b32 v0, v38, v39 offset0:2 offset1:3
	s_waitcnt vmcnt(6)
	ds_write2_b32 v22, v40, v41 offset1:1
	v_add_u32_e32 v22, 0x428, v0
	ds_write2_b32 v22, v42, v43 offset1:1
	v_add_u32_e32 v22, 0x840, v0
	s_waitcnt vmcnt(5)
	ds_write2_b32 v22, v44, v45 offset1:1
	v_add_u32_e32 v22, 0x848, v0
	ds_write2_b32 v22, v46, v47 offset1:1
	v_add_u32_e32 v22, 0xc60, v0
	v_add_u32_e32 v40, s8, v3
	s_waitcnt vmcnt(4)
	ds_write2_b32 v22, v48, v49 offset1:1
	v_add_u32_e32 v22, 0xc68, v0
	ds_write2_b32 v22, v50, v51 offset1:1
	v_add_u32_e32 v22, 0x1080, v0
	v_ashrrev_i32_e32 v41, 31, v40
	v_lshlrev_b64 v[40:41], 11, v[40:41]
	s_waitcnt vmcnt(3)
	ds_write2_b32 v22, v52, v53 offset1:1
	v_add_u32_e32 v22, 0x1088, v0
	ds_write2_b32 v22, v54, v55 offset1:1
	v_add_u32_e32 v22, 0x14a0, v0
	s_waitcnt vmcnt(2)
	ds_write2_b32 v22, v56, v57 offset1:1
	v_add_u32_e32 v22, 0x14a8, v0
	ds_write2_b32 v22, v58, v59 offset1:1
	v_add_u32_e32 v22, 0x18c0, v0
	s_waitcnt vmcnt(1)
	ds_write2_b32 v22, v60, v61 offset1:1
	v_add_u32_e32 v22, 0x18c8, v0
	ds_write2_b32 v22, v62, v63 offset1:1
	v_add_u32_e32 v22, 0x1ce0, v0
	v_add_u32_e32 v0, 0x1ce8, v0
	s_waitcnt vmcnt(0)
	ds_write2_b32 v22, v64, v65 offset1:1
	ds_write2_b32 v0, v66, v67 offset1:1
	s_waitcnt lgkmcnt(0)
	ds_read2_b32 v[42:43], v30 offset0:33 offset1:41
	ds_read2_b32 v[44:45], v30 offset1:8
	ds_read2_b32 v[46:47], v30 offset0:66 offset1:74
	ds_read2_b32 v[48:49], v30 offset0:99 offset1:107
	ds_read2_b32 v[50:51], v30 offset0:132 offset1:140
	ds_read2_b32 v[52:53], v30 offset0:165 offset1:173
	ds_read2_b32 v[54:55], v30 offset0:198 offset1:206
	ds_read2_b32 v[56:57], v30 offset0:231 offset1:239
	v_lshl_add_u64 v[22:23], v[10:11], 0, s[62:63]
	s_waitcnt lgkmcnt(6)
	v_cvt_pk_bf16_f32 v36, v44, v42
	s_waitcnt lgkmcnt(4)
	v_cvt_pk_bf16_f32 v37, v46, v48
	s_waitcnt lgkmcnt(2)
	v_cvt_pk_bf16_f32 v38, v50, v52
	s_waitcnt lgkmcnt(0)
	v_cvt_pk_bf16_f32 v39, v54, v56
	v_lshl_add_u64 v[40:41], v[22:23], 0, v[40:41]
	global_store_dwordx4 v[40:41], v[36:39], off sc1
	v_add_u32_e32 v40, s8, v24
	v_ashrrev_i32_e32 v41, 31, v40
	v_lshlrev_b64 v[40:41], 11, v[40:41]
	v_cvt_pk_bf16_f32 v36, v45, v43
	v_cvt_pk_bf16_f32 v37, v47, v49
	v_cvt_pk_bf16_f32 v38, v51, v53
	v_cvt_pk_bf16_f32 v39, v55, v57
	v_lshl_add_u64 v[40:41], v[22:23], 0, v[40:41]
	global_store_dwordx4 v[40:41], v[36:39], off sc1
	ds_read2_b32 v[42:43], v30 offset0:49 offset1:57
	ds_read2_b32 v[44:45], v30 offset0:16 offset1:24
	ds_read2_b32 v[46:47], v30 offset0:82 offset1:90
	ds_read2_b32 v[48:49], v30 offset0:115 offset1:123
	ds_read2_b32 v[50:51], v30 offset0:148 offset1:156
	ds_read2_b32 v[52:53], v30 offset0:181 offset1:189
	ds_read2_b32 v[54:55], v30 offset0:214 offset1:222
	ds_read2_b32 v[56:57], v30 offset0:247 offset1:255
	v_add_u32_e32 v40, s8, v25
	v_ashrrev_i32_e32 v41, 31, v40
	v_lshlrev_b64 v[40:41], 11, v[40:41]
	s_waitcnt lgkmcnt(6)
	v_cvt_pk_bf16_f32 v36, v44, v42
	s_waitcnt lgkmcnt(4)
	v_cvt_pk_bf16_f32 v37, v46, v48
	s_waitcnt lgkmcnt(2)
	v_cvt_pk_bf16_f32 v38, v50, v52
	s_waitcnt lgkmcnt(0)
	v_cvt_pk_bf16_f32 v39, v54, v56
	v_lshl_add_u64 v[40:41], v[22:23], 0, v[40:41]
	global_store_dwordx4 v[40:41], v[36:39], off sc1
	v_add_u32_e32 v40, s8, v26
	v_ashrrev_i32_e32 v41, 31, v40
	v_lshlrev_b64 v[40:41], 11, v[40:41]
	v_cvt_pk_bf16_f32 v36, v45, v43
	v_cvt_pk_bf16_f32 v37, v47, v49
	v_cvt_pk_bf16_f32 v38, v51, v53
	v_cvt_pk_bf16_f32 v39, v55, v57
	v_lshl_add_u64 v[22:23], v[22:23], 0, v[40:41]
	global_store_dwordx4 v[22:23], v[36:39], off sc1
	s_waitcnt lgkmcnt(0)

.LBB0_823:
	s_andn2_b64 vcc, exec, s[8:9]
	s_cbranch_vccnz .LBB0_825
	s_load_dwordx2 s[10:11], s[60:61], 0xc0
	s_add_i32 s8, s2, 0x7000
	s_and_b32 s9, s8, 0xffc0
	s_and_b32 s8, s18, 0x7e0
	s_lshl_b32 s20, s8, 2
	v_add_u32_e32 v22, s9, v3
	s_waitcnt lgkmcnt(0)
	s_add_u32 s10, s10, s20
	s_addc_u32 s11, s11, 0
	v_lshlrev_b32_e32 v0, 2, v2
	v_ashrrev_i32_e32 v23, 31, v22
	v_lshl_add_u64 v[36:37], s[10:11], 0, v[0:1]
	v_lshlrev_b64 v[22:23], 13, v[22:23]
	v_lshl_add_u64 v[22:23], v[36:37], 0, v[22:23]
	s_mov_b32 s10, 0x10000
	v_add_co_u32_e32 v40, vcc, s10, v22
	global_load_dwordx4 v[36:39], v[22:23], off nt
	s_nop 0
	v_addc_co_u32_e32 v41, vcc, 0, v23, vcc
	global_load_dwordx4 v[40:43], v[40:41], off nt
	v_add_co_u32_e32 v44, vcc, s82, v22
	s_mov_b32 s10, 0x30000
	s_nop 0
	v_addc_co_u32_e32 v45, vcc, 0, v23, vcc
	global_load_dwordx4 v[44:47], v[44:45], off nt
	v_add_co_u32_e32 v48, vcc, s10, v22
	s_mov_b32 s10, 0x50000
	s_nop 0
	v_addc_co_u32_e32 v49, vcc, 0, v23, vcc
	global_load_dwordx4 v[48:51], v[48:49], off nt
	v_add_co_u32_e32 v52, vcc, s83, v22
	v_add_u32_e32 v0, v29, v5
	s_nop 0
	v_addc_co_u32_e32 v53, vcc, 0, v23, vcc
	global_load_dwordx4 v[52:55], v[52:53], off nt
	v_add_co_u32_e32 v56, vcc, s10, v22
	s_mov_b32 s10, 0x70000
	s_nop 0
	v_addc_co_u32_e32 v57, vcc, 0, v23, vcc
	global_load_dwordx4 v[56:59], v[56:57], off nt
	v_add_co_u32_e32 v60, vcc, s88, v22
	s_lshl_b32 s62, s9, 1
	s_nop 0
	v_addc_co_u32_e32 v61, vcc, 0, v23, vcc
	global_load_dwordx4 v[60:63], v[60:61], off nt
	v_add_co_u32_e32 v22, vcc, s10, v22
	s_nop 1
	v_addc_co_u32_e32 v23, vcc, 0, v23, vcc
	global_load_dwordx4 v[64:67], v[22:23], off nt
	v_add_u32_e32 v22, 0x420, v0
	s_waitcnt vmcnt(7)
	ds_write2_b32 v0, v36, v37 offset1:1
	ds_write2_b32 v0, v38, v39 offset0:2 offset1:3
	s_waitcnt vmcnt(6)
	ds_write2_b32 v22, v40, v41 offset1:1
	v_add_u32_e32 v22, 0x428, v0
	ds_write2_b32 v22, v42, v43 offset1:1
	v_add_u32_e32 v22, 0x840, v0
	v_add_u32_e32 v40, s8, v3
	v_ashrrev_i32_e32 v41, 31, v40
	s_waitcnt vmcnt(5)
	ds_write2_b32 v22, v44, v45 offset1:1
	v_add_u32_e32 v22, 0x848, v0
	ds_write2_b32 v22, v46, v47 offset1:1
	v_add_u32_e32 v22, 0xc60, v0
	v_lshlrev_b64 v[40:41], 11, v[40:41]
	s_waitcnt vmcnt(4)
	ds_write2_b32 v22, v48, v49 offset1:1
	v_add_u32_e32 v22, 0xc68, v0
	ds_write2_b32 v22, v50, v51 offset1:1
	v_add_u32_e32 v22, 0x1080, v0
	s_waitcnt vmcnt(3)
	ds_write2_b32 v22, v52, v53 offset1:1
	v_add_u32_e32 v22, 0x1088, v0
	ds_write2_b32 v22, v54, v55 offset1:1
	v_add_u32_e32 v22, 0x14a0, v0
	s_waitcnt vmcnt(2)
	ds_write2_b32 v22, v56, v57 offset1:1
	v_add_u32_e32 v22, 0x14a8, v0
	ds_write2_b32 v22, v58, v59 offset1:1
	v_add_u32_e32 v22, 0x18c0, v0
	s_waitcnt vmcnt(1)
	ds_write2_b32 v22, v60, v61 offset1:1
	v_add_u32_e32 v22, 0x18c8, v0
	ds_write2_b32 v22, v62, v63 offset1:1
	v_add_u32_e32 v22, 0x1ce0, v0
	v_add_u32_e32 v0, 0x1ce8, v0
	s_waitcnt vmcnt(0)
	ds_write2_b32 v22, v64, v65 offset1:1
	ds_write2_b32 v0, v66, v67 offset1:1
	s_waitcnt lgkmcnt(0)
	ds_read2_b32 v[42:43], v30 offset0:33 offset1:41
	ds_read2_b32 v[44:45], v30 offset1:8
	ds_read2_b32 v[46:47], v30 offset0:66 offset1:74
	ds_read2_b32 v[48:49], v30 offset0:99 offset1:107
	ds_read2_b32 v[50:51], v30 offset0:132 offset1:140
	ds_read2_b32 v[52:53], v30 offset0:165 offset1:173
	ds_read2_b32 v[54:55], v30 offset0:198 offset1:206
	ds_read2_b32 v[56:57], v30 offset0:231 offset1:239
	v_lshl_add_u64 v[22:23], v[12:13], 0, s[62:63]
	s_waitcnt lgkmcnt(6)
	v_cvt_pk_bf16_f32 v36, v44, v42
	s_waitcnt lgkmcnt(4)
	v_cvt_pk_bf16_f32 v37, v46, v48
	s_waitcnt lgkmcnt(2)
	v_cvt_pk_bf16_f32 v38, v50, v52
	s_waitcnt lgkmcnt(0)
	v_cvt_pk_bf16_f32 v39, v54, v56
	v_lshl_add_u64 v[40:41], v[22:23], 0, v[40:41]
	global_store_dwordx4 v[40:41], v[36:39], off sc1
	v_add_u32_e32 v40, s8, v24
	v_ashrrev_i32_e32 v41, 31, v40
	v_lshlrev_b64 v[40:41], 11, v[40:41]
	v_cvt_pk_bf16_f32 v36, v45, v43
	v_cvt_pk_bf16_f32 v37, v47, v49
	v_cvt_pk_bf16_f32 v38, v51, v53
	v_cvt_pk_bf16_f32 v39, v55, v57
	v_lshl_add_u64 v[40:41], v[22:23], 0, v[40:41]
	global_store_dwordx4 v[40:41], v[36:39], off sc1
	ds_read2_b32 v[42:43], v30 offset0:49 offset1:57
	ds_read2_b32 v[44:45], v30 offset0:16 offset1:24
	ds_read2_b32 v[46:47], v30 offset0:82 offset1:90
	ds_read2_b32 v[48:49], v30 offset0:115 offset1:123
	ds_read2_b32 v[50:51], v30 offset0:148 offset1:156
	ds_read2_b32 v[52:53], v30 offset0:181 offset1:189
	ds_read2_b32 v[54:55], v30 offset0:214 offset1:222
	ds_read2_b32 v[56:57], v30 offset0:247 offset1:255
	v_add_u32_e32 v40, s8, v25
	v_ashrrev_i32_e32 v41, 31, v40
	v_lshlrev_b64 v[40:41], 11, v[40:41]
	s_waitcnt lgkmcnt(6)
	v_cvt_pk_bf16_f32 v36, v44, v42
	s_waitcnt lgkmcnt(4)
	v_cvt_pk_bf16_f32 v37, v46, v48
	s_waitcnt lgkmcnt(2)
	v_cvt_pk_bf16_f32 v38, v50, v52
	s_waitcnt lgkmcnt(0)
	v_cvt_pk_bf16_f32 v39, v54, v56
	v_lshl_add_u64 v[40:41], v[22:23], 0, v[40:41]
	global_store_dwordx4 v[40:41], v[36:39], off sc1
	v_add_u32_e32 v40, s8, v26
	v_ashrrev_i32_e32 v41, 31, v40
	v_lshlrev_b64 v[40:41], 11, v[40:41]
	v_cvt_pk_bf16_f32 v36, v45, v43
	v_cvt_pk_bf16_f32 v37, v47, v49
	v_cvt_pk_bf16_f32 v38, v51, v53
	v_cvt_pk_bf16_f32 v39, v55, v57
	v_lshl_add_u64 v[22:23], v[22:23], 0, v[40:41]
	global_store_dwordx4 v[22:23], v[36:39], off sc1
	s_waitcnt lgkmcnt(0)

.LBB0_826:
	s_andn2_b64 vcc, exec, s[8:9]
	s_cbranch_vccnz .LBB0_828
	s_load_dwordx2 s[10:11], s[60:61], 0xb0
	s_add_i32 s8, s16, 0xe400
	s_and_b32 s9, s8, 0x1ffc0
	s_and_b32 s8, s18, 0x3e0
	s_lshl_b32 s20, s8, 2
	v_add_u32_e32 v22, s9, v3
	s_waitcnt lgkmcnt(0)
	s_add_u32 s10, s10, s20
	s_addc_u32 s11, s11, 0
	v_lshlrev_b32_e32 v0, 2, v2
	v_ashrrev_i32_e32 v23, 31, v22
	v_lshl_add_u64 v[36:37], s[10:11], 0, v[0:1]
	v_lshlrev_b64 v[22:23], 12, v[22:23]
	v_lshl_add_u64 v[22:23], v[36:37], 0, v[22:23]
	s_mov_b32 s10, 0x8000
	v_add_co_u32_e32 v40, vcc, s10, v22
	s_mov_b32 s10, 0x10000
	s_nop 0
	v_addc_co_u32_e32 v41, vcc, 0, v23, vcc
	global_load_dwordx4 v[36:39], v[22:23], off nt
	v_add_co_u32_e32 v44, vcc, s10, v22
	global_load_dwordx4 v[40:43], v[40:41], off nt
	s_nop 0
	v_addc_co_u32_e32 v45, vcc, 0, v23, vcc
	global_load_dwordx4 v[44:47], v[44:45], off nt
	v_add_co_u32_e32 v48, vcc, s41, v22
	s_mov_b32 s10, 0x30000
	s_nop 0
	v_addc_co_u32_e32 v49, vcc, 0, v23, vcc
	global_load_dwordx4 v[48:51], v[48:49], off nt
	v_add_co_u32_e32 v52, vcc, s82, v22
	v_add_u32_e32 v0, v29, v5
	s_nop 0
	v_addc_co_u32_e32 v53, vcc, 0, v23, vcc
	global_load_dwordx4 v[52:55], v[52:53], off nt
	v_add_co_u32_e32 v56, vcc, s44, v22
	s_lshl_b32 s62, s9, 1
	s_nop 0
	v_addc_co_u32_e32 v57, vcc, 0, v23, vcc
	global_load_dwordx4 v[56:59], v[56:57], off nt
	v_add_co_u32_e32 v60, vcc, s10, v22
	s_mov_b32 s10, 0x38000
	s_nop 0
	v_addc_co_u32_e32 v61, vcc, 0, v23, vcc
	global_load_dwordx4 v[60:63], v[60:61], off nt
	v_add_co_u32_e32 v22, vcc, s10, v22
	s_nop 1
	v_addc_co_u32_e32 v23, vcc, 0, v23, vcc
	global_load_dwordx4 v[64:67], v[22:23], off nt
	v_add_u32_e32 v22, 0x420, v0
	s_waitcnt vmcnt(7)
	ds_write2_b32 v0, v36, v37 offset1:1
	ds_write2_b32 v0, v38, v39 offset0:2 offset1:3
	s_waitcnt vmcnt(6)
	ds_write2_b32 v22, v40, v41 offset1:1
	v_add_u32_e32 v22, 0x428, v0
	ds_write2_b32 v22, v42, v43 offset1:1
	v_add_u32_e32 v22, 0x840, v0
	s_waitcnt vmcnt(5)
	ds_write2_b32 v22, v44, v45 offset1:1
	v_add_u32_e32 v22, 0x848, v0
	ds_write2_b32 v22, v46, v47 offset1:1
	v_add_u32_e32 v22, 0xc60, v0
	v_add_u32_e32 v40, s8, v3
	s_waitcnt vmcnt(4)
	ds_write2_b32 v22, v48, v49 offset1:1
	v_add_u32_e32 v22, 0xc68, v0
	ds_write2_b32 v22, v50, v51 offset1:1
	v_add_u32_e32 v22, 0x1080, v0
	v_ashrrev_i32_e32 v41, 31, v40
	v_lshlrev_b64 v[40:41], 11, v[40:41]
	s_waitcnt vmcnt(3)
	ds_write2_b32 v22, v52, v53 offset1:1
	v_add_u32_e32 v22, 0x1088, v0
	ds_write2_b32 v22, v54, v55 offset1:1
	v_add_u32_e32 v22, 0x14a0, v0
	s_waitcnt vmcnt(2)
	ds_write2_b32 v22, v56, v57 offset1:1
	v_add_u32_e32 v22, 0x14a8, v0
	ds_write2_b32 v22, v58, v59 offset1:1
	v_add_u32_e32 v22, 0x18c0, v0
	s_waitcnt vmcnt(1)
	ds_write2_b32 v22, v60, v61 offset1:1
	v_add_u32_e32 v22, 0x18c8, v0
	ds_write2_b32 v22, v62, v63 offset1:1
	v_add_u32_e32 v22, 0x1ce0, v0
	v_add_u32_e32 v0, 0x1ce8, v0
	s_waitcnt vmcnt(0)
	ds_write2_b32 v22, v64, v65 offset1:1
	ds_write2_b32 v0, v66, v67 offset1:1
	s_waitcnt lgkmcnt(0)
	ds_read2_b32 v[42:43], v30 offset0:33 offset1:41
	ds_read2_b32 v[44:45], v30 offset1:8
	ds_read2_b32 v[46:47], v30 offset0:66 offset1:74
	ds_read2_b32 v[48:49], v30 offset0:99 offset1:107
	ds_read2_b32 v[50:51], v30 offset0:132 offset1:140
	ds_read2_b32 v[52:53], v30 offset0:165 offset1:173
	ds_read2_b32 v[54:55], v30 offset0:198 offset1:206
	ds_read2_b32 v[56:57], v30 offset0:231 offset1:239
	v_lshl_add_u64 v[22:23], v[14:15], 0, s[62:63]
	s_waitcnt lgkmcnt(6)
	v_cvt_pk_bf16_f32 v36, v44, v42
	s_waitcnt lgkmcnt(4)
	v_cvt_pk_bf16_f32 v37, v46, v48
	s_waitcnt lgkmcnt(2)
	v_cvt_pk_bf16_f32 v38, v50, v52
	s_waitcnt lgkmcnt(0)
	v_cvt_pk_bf16_f32 v39, v54, v56
	v_lshl_add_u64 v[40:41], v[22:23], 0, v[40:41]
	global_store_dwordx4 v[40:41], v[36:39], off sc1
	v_add_u32_e32 v40, s8, v24
	v_ashrrev_i32_e32 v41, 31, v40
	v_lshlrev_b64 v[40:41], 11, v[40:41]
	v_cvt_pk_bf16_f32 v36, v45, v43
	v_cvt_pk_bf16_f32 v37, v47, v49
	v_cvt_pk_bf16_f32 v38, v51, v53
	v_cvt_pk_bf16_f32 v39, v55, v57
	v_lshl_add_u64 v[40:41], v[22:23], 0, v[40:41]
	global_store_dwordx4 v[40:41], v[36:39], off sc1
	ds_read2_b32 v[42:43], v30 offset0:49 offset1:57
	ds_read2_b32 v[44:45], v30 offset0:16 offset1:24
	ds_read2_b32 v[46:47], v30 offset0:82 offset1:90
	ds_read2_b32 v[48:49], v30 offset0:115 offset1:123
	ds_read2_b32 v[50:51], v30 offset0:148 offset1:156
	ds_read2_b32 v[52:53], v30 offset0:181 offset1:189
	ds_read2_b32 v[54:55], v30 offset0:214 offset1:222
	ds_read2_b32 v[56:57], v30 offset0:247 offset1:255
	v_add_u32_e32 v40, s8, v25
	v_ashrrev_i32_e32 v41, 31, v40
	v_lshlrev_b64 v[40:41], 11, v[40:41]
	s_waitcnt lgkmcnt(6)
	v_cvt_pk_bf16_f32 v36, v44, v42
	s_waitcnt lgkmcnt(4)
	v_cvt_pk_bf16_f32 v37, v46, v48
	s_waitcnt lgkmcnt(2)
	v_cvt_pk_bf16_f32 v38, v50, v52
	s_waitcnt lgkmcnt(0)
	v_cvt_pk_bf16_f32 v39, v54, v56
	v_lshl_add_u64 v[40:41], v[22:23], 0, v[40:41]
	global_store_dwordx4 v[40:41], v[36:39], off sc1
	v_add_u32_e32 v40, s8, v26
	v_ashrrev_i32_e32 v41, 31, v40
	v_lshlrev_b64 v[40:41], 11, v[40:41]
	v_cvt_pk_bf16_f32 v36, v45, v43
	v_cvt_pk_bf16_f32 v37, v47, v49
	v_cvt_pk_bf16_f32 v38, v51, v53
	v_cvt_pk_bf16_f32 v39, v55, v57
	v_lshl_add_u64 v[22:23], v[22:23], 0, v[40:41]
	global_store_dwordx4 v[22:23], v[36:39], off sc1
	s_waitcnt lgkmcnt(0)

.LBB0_829:
	s_andn2_b64 vcc, exec, s[8:9]
	s_cbranch_vccnz .LBB0_831
	s_load_dwordx2 s[10:11], s[60:61], 0xa8
	s_add_i32 s8, s16, 0xe800
	s_and_b32 s9, s8, 0x1ffc0
	s_and_b32 s8, s18, 0x3e0
	s_lshl_b32 s20, s8, 2
	v_add_u32_e32 v22, s9, v3
	s_waitcnt lgkmcnt(0)
	s_add_u32 s10, s10, s20
	s_addc_u32 s11, s11, 0
	v_lshlrev_b32_e32 v0, 2, v2
	v_ashrrev_i32_e32 v23, 31, v22
	v_lshl_add_u64 v[36:37], s[10:11], 0, v[0:1]
	v_lshlrev_b64 v[22:23], 12, v[22:23]
	v_lshl_add_u64 v[22:23], v[36:37], 0, v[22:23]
	s_mov_b32 s10, 0x8000
	v_add_co_u32_e32 v40, vcc, s10, v22
	s_mov_b32 s10, 0x10000
	s_nop 0
	v_addc_co_u32_e32 v41, vcc, 0, v23, vcc
	global_load_dwordx4 v[36:39], v[22:23], off nt
	v_add_co_u32_e32 v44, vcc, s10, v22
	global_load_dwordx4 v[40:43], v[40:41], off nt
	s_nop 0
	v_addc_co_u32_e32 v45, vcc, 0, v23, vcc
	global_load_dwordx4 v[44:47], v[44:45], off nt
	v_add_co_u32_e32 v48, vcc, s41, v22
	s_mov_b32 s10, 0x30000
	s_nop 0
	v_addc_co_u32_e32 v49, vcc, 0, v23, vcc
	global_load_dwordx4 v[48:51], v[48:49], off nt
	v_add_co_u32_e32 v52, vcc, s82, v22
	v_add_u32_e32 v0, v29, v5
	s_nop 0
	v_addc_co_u32_e32 v53, vcc, 0, v23, vcc
	global_load_dwordx4 v[52:55], v[52:53], off nt
	v_add_co_u32_e32 v56, vcc, s44, v22
	s_lshl_b32 s62, s9, 1
	s_nop 0
	v_addc_co_u32_e32 v57, vcc, 0, v23, vcc
	global_load_dwordx4 v[56:59], v[56:57], off nt
	v_add_co_u32_e32 v60, vcc, s10, v22
	s_mov_b32 s10, 0x38000
	s_nop 0
	v_addc_co_u32_e32 v61, vcc, 0, v23, vcc
	global_load_dwordx4 v[60:63], v[60:61], off nt
	v_add_co_u32_e32 v22, vcc, s10, v22
	s_nop 1
	v_addc_co_u32_e32 v23, vcc, 0, v23, vcc
	global_load_dwordx4 v[64:67], v[22:23], off nt
	v_add_u32_e32 v22, 0x420, v0
	s_waitcnt vmcnt(7)
	ds_write2_b32 v0, v36, v37 offset1:1
	ds_write2_b32 v0, v38, v39 offset0:2 offset1:3
	s_waitcnt vmcnt(6)
	ds_write2_b32 v22, v40, v41 offset1:1
	v_add_u32_e32 v22, 0x428, v0
	ds_write2_b32 v22, v42, v43 offset1:1
	v_add_u32_e32 v22, 0x840, v0
	s_waitcnt vmcnt(5)
	ds_write2_b32 v22, v44, v45 offset1:1
	v_add_u32_e32 v22, 0x848, v0
	ds_write2_b32 v22, v46, v47 offset1:1
	v_add_u32_e32 v22, 0xc60, v0
	v_add_u32_e32 v40, s8, v3
	s_waitcnt vmcnt(4)
	ds_write2_b32 v22, v48, v49 offset1:1
	v_add_u32_e32 v22, 0xc68, v0
	ds_write2_b32 v22, v50, v51 offset1:1
	v_add_u32_e32 v22, 0x1080, v0
	v_ashrrev_i32_e32 v41, 31, v40
	v_lshlrev_b64 v[40:41], 11, v[40:41]
	s_waitcnt vmcnt(3)
	ds_write2_b32 v22, v52, v53 offset1:1
	v_add_u32_e32 v22, 0x1088, v0
	ds_write2_b32 v22, v54, v55 offset1:1
	v_add_u32_e32 v22, 0x14a0, v0
	s_waitcnt vmcnt(2)
	ds_write2_b32 v22, v56, v57 offset1:1
	v_add_u32_e32 v22, 0x14a8, v0
	ds_write2_b32 v22, v58, v59 offset1:1
	v_add_u32_e32 v22, 0x18c0, v0
	s_waitcnt vmcnt(1)
	ds_write2_b32 v22, v60, v61 offset1:1
	v_add_u32_e32 v22, 0x18c8, v0
	ds_write2_b32 v22, v62, v63 offset1:1
	v_add_u32_e32 v22, 0x1ce0, v0
	v_add_u32_e32 v0, 0x1ce8, v0
	s_waitcnt vmcnt(0)
	ds_write2_b32 v22, v64, v65 offset1:1
	ds_write2_b32 v0, v66, v67 offset1:1
	s_waitcnt lgkmcnt(0)
	ds_read2_b32 v[42:43], v30 offset0:33 offset1:41
	ds_read2_b32 v[44:45], v30 offset1:8
	ds_read2_b32 v[46:47], v30 offset0:66 offset1:74
	ds_read2_b32 v[48:49], v30 offset0:99 offset1:107
	ds_read2_b32 v[50:51], v30 offset0:132 offset1:140
	ds_read2_b32 v[52:53], v30 offset0:165 offset1:173
	ds_read2_b32 v[54:55], v30 offset0:198 offset1:206
	ds_read2_b32 v[56:57], v30 offset0:231 offset1:239
	v_lshl_add_u64 v[22:23], v[16:17], 0, s[62:63]
	s_waitcnt lgkmcnt(6)
	v_cvt_pk_bf16_f32 v36, v44, v42
	s_waitcnt lgkmcnt(4)
	v_cvt_pk_bf16_f32 v37, v46, v48
	s_waitcnt lgkmcnt(2)
	v_cvt_pk_bf16_f32 v38, v50, v52
	s_waitcnt lgkmcnt(0)
	v_cvt_pk_bf16_f32 v39, v54, v56
	v_lshl_add_u64 v[40:41], v[22:23], 0, v[40:41]
	global_store_dwordx4 v[40:41], v[36:39], off sc1
	v_add_u32_e32 v40, s8, v24
	v_ashrrev_i32_e32 v41, 31, v40
	v_lshlrev_b64 v[40:41], 11, v[40:41]
	v_cvt_pk_bf16_f32 v36, v45, v43
	v_cvt_pk_bf16_f32 v37, v47, v49
	v_cvt_pk_bf16_f32 v38, v51, v53
	v_cvt_pk_bf16_f32 v39, v55, v57
	v_lshl_add_u64 v[40:41], v[22:23], 0, v[40:41]
	global_store_dwordx4 v[40:41], v[36:39], off sc1
	ds_read2_b32 v[42:43], v30 offset0:49 offset1:57
	ds_read2_b32 v[44:45], v30 offset0:16 offset1:24
	ds_read2_b32 v[46:47], v30 offset0:82 offset1:90
	ds_read2_b32 v[48:49], v30 offset0:115 offset1:123
	ds_read2_b32 v[50:51], v30 offset0:148 offset1:156
	ds_read2_b32 v[52:53], v30 offset0:181 offset1:189
	ds_read2_b32 v[54:55], v30 offset0:214 offset1:222
	ds_read2_b32 v[56:57], v30 offset0:247 offset1:255
	v_add_u32_e32 v40, s8, v25
	v_ashrrev_i32_e32 v41, 31, v40
	v_lshlrev_b64 v[40:41], 11, v[40:41]
	s_waitcnt lgkmcnt(6)
	v_cvt_pk_bf16_f32 v36, v44, v42
	s_waitcnt lgkmcnt(4)
	v_cvt_pk_bf16_f32 v37, v46, v48
	s_waitcnt lgkmcnt(2)
	v_cvt_pk_bf16_f32 v38, v50, v52
	s_waitcnt lgkmcnt(0)
	v_cvt_pk_bf16_f32 v39, v54, v56
	v_lshl_add_u64 v[40:41], v[22:23], 0, v[40:41]
	global_store_dwordx4 v[40:41], v[36:39], off sc1
	v_add_u32_e32 v40, s8, v26
	v_ashrrev_i32_e32 v41, 31, v40
	v_lshlrev_b64 v[40:41], 11, v[40:41]
	v_cvt_pk_bf16_f32 v36, v45, v43
	v_cvt_pk_bf16_f32 v37, v47, v49
	v_cvt_pk_bf16_f32 v38, v51, v53
	v_cvt_pk_bf16_f32 v39, v55, v57
	v_lshl_add_u64 v[22:23], v[22:23], 0, v[40:41]
	global_store_dwordx4 v[22:23], v[36:39], off sc1
	s_waitcnt lgkmcnt(0)

.LBB0_832:
	s_andn2_b64 vcc, exec, s[8:9]
	s_cbranch_vccnz .LBB0_834
	s_load_dwordx2 s[10:11], s[60:61], 0x98
	s_add_i32 s8, s16, 0xec00
	s_and_b32 s9, s8, 0x1ffc0
	s_and_b32 s8, s18, 0x3e0
	s_lshl_b32 s20, s8, 2
	v_add_u32_e32 v22, s9, v3
	s_waitcnt lgkmcnt(0)
	s_add_u32 s10, s10, s20
	s_addc_u32 s11, s11, 0
	v_lshlrev_b32_e32 v0, 2, v2
	v_ashrrev_i32_e32 v23, 31, v22
	v_lshl_add_u64 v[36:37], s[10:11], 0, v[0:1]
	v_lshlrev_b64 v[22:23], 12, v[22:23]
	v_lshl_add_u64 v[22:23], v[36:37], 0, v[22:23]
	s_mov_b32 s10, 0x8000
	v_add_co_u32_e32 v40, vcc, s10, v22
	s_mov_b32 s10, 0x10000
	s_nop 0
	v_addc_co_u32_e32 v41, vcc, 0, v23, vcc
	global_load_dwordx4 v[36:39], v[22:23], off nt
	v_add_co_u32_e32 v44, vcc, s10, v22
	global_load_dwordx4 v[40:43], v[40:41], off nt
	s_nop 0
	v_addc_co_u32_e32 v45, vcc, 0, v23, vcc
	global_load_dwordx4 v[44:47], v[44:45], off nt
	v_add_co_u32_e32 v48, vcc, s41, v22
	s_mov_b32 s10, 0x30000
	s_nop 0
	v_addc_co_u32_e32 v49, vcc, 0, v23, vcc
	global_load_dwordx4 v[48:51], v[48:49], off nt
	v_add_co_u32_e32 v52, vcc, s82, v22
	v_add_u32_e32 v0, v29, v5
	s_nop 0
	v_addc_co_u32_e32 v53, vcc, 0, v23, vcc
	global_load_dwordx4 v[52:55], v[52:53], off nt
	v_add_co_u32_e32 v56, vcc, s44, v22
	s_lshl_b32 s62, s9, 1
	s_nop 0
	v_addc_co_u32_e32 v57, vcc, 0, v23, vcc
	global_load_dwordx4 v[56:59], v[56:57], off nt
	v_add_co_u32_e32 v60, vcc, s10, v22
	s_mov_b32 s10, 0x38000
	s_nop 0
	v_addc_co_u32_e32 v61, vcc, 0, v23, vcc
	global_load_dwordx4 v[60:63], v[60:61], off nt
	v_add_co_u32_e32 v22, vcc, s10, v22
	s_nop 1
	v_addc_co_u32_e32 v23, vcc, 0, v23, vcc
	global_load_dwordx4 v[64:67], v[22:23], off nt
	v_add_u32_e32 v22, 0x420, v0
	s_waitcnt vmcnt(7)
	ds_write2_b32 v0, v36, v37 offset1:1
	ds_write2_b32 v0, v38, v39 offset0:2 offset1:3
	s_waitcnt vmcnt(6)
	ds_write2_b32 v22, v40, v41 offset1:1
	v_add_u32_e32 v22, 0x428, v0
	ds_write2_b32 v22, v42, v43 offset1:1
	v_add_u32_e32 v22, 0x840, v0
	s_waitcnt vmcnt(5)
	ds_write2_b32 v22, v44, v45 offset1:1
	v_add_u32_e32 v22, 0x848, v0
	ds_write2_b32 v22, v46, v47 offset1:1
	v_add_u32_e32 v22, 0xc60, v0
	v_add_u32_e32 v40, s8, v3
	s_waitcnt vmcnt(4)
	ds_write2_b32 v22, v48, v49 offset1:1
	v_add_u32_e32 v22, 0xc68, v0
	ds_write2_b32 v22, v50, v51 offset1:1
	v_add_u32_e32 v22, 0x1080, v0
	v_ashrrev_i32_e32 v41, 31, v40
	v_lshlrev_b64 v[40:41], 11, v[40:41]
	s_waitcnt vmcnt(3)
	ds_write2_b32 v22, v52, v53 offset1:1
	v_add_u32_e32 v22, 0x1088, v0
	ds_write2_b32 v22, v54, v55 offset1:1
	v_add_u32_e32 v22, 0x14a0, v0
	s_waitcnt vmcnt(2)
	ds_write2_b32 v22, v56, v57 offset1:1
	v_add_u32_e32 v22, 0x14a8, v0
	ds_write2_b32 v22, v58, v59 offset1:1
	v_add_u32_e32 v22, 0x18c0, v0
	s_waitcnt vmcnt(1)
	ds_write2_b32 v22, v60, v61 offset1:1
	v_add_u32_e32 v22, 0x18c8, v0
	ds_write2_b32 v22, v62, v63 offset1:1
	v_add_u32_e32 v22, 0x1ce0, v0
	v_add_u32_e32 v0, 0x1ce8, v0
	s_waitcnt vmcnt(0)
	ds_write2_b32 v22, v64, v65 offset1:1
	ds_write2_b32 v0, v66, v67 offset1:1
	s_waitcnt lgkmcnt(0)
	ds_read2_b32 v[42:43], v30 offset0:33 offset1:41
	ds_read2_b32 v[44:45], v30 offset1:8
	ds_read2_b32 v[46:47], v30 offset0:66 offset1:74
	ds_read2_b32 v[48:49], v30 offset0:99 offset1:107
	ds_read2_b32 v[50:51], v30 offset0:132 offset1:140
	ds_read2_b32 v[52:53], v30 offset0:165 offset1:173
	ds_read2_b32 v[54:55], v30 offset0:198 offset1:206
	ds_read2_b32 v[56:57], v30 offset0:231 offset1:239
	v_lshl_add_u64 v[22:23], v[18:19], 0, s[62:63]
	s_waitcnt lgkmcnt(6)
	v_cvt_pk_bf16_f32 v36, v44, v42
	s_waitcnt lgkmcnt(4)
	v_cvt_pk_bf16_f32 v37, v46, v48
	s_waitcnt lgkmcnt(2)
	v_cvt_pk_bf16_f32 v38, v50, v52
	s_waitcnt lgkmcnt(0)
	v_cvt_pk_bf16_f32 v39, v54, v56
	v_lshl_add_u64 v[40:41], v[22:23], 0, v[40:41]
	global_store_dwordx4 v[40:41], v[36:39], off sc1
	v_add_u32_e32 v40, s8, v24
	v_ashrrev_i32_e32 v41, 31, v40
	v_lshlrev_b64 v[40:41], 11, v[40:41]
	v_cvt_pk_bf16_f32 v36, v45, v43
	v_cvt_pk_bf16_f32 v37, v47, v49
	v_cvt_pk_bf16_f32 v38, v51, v53
	v_cvt_pk_bf16_f32 v39, v55, v57
	v_lshl_add_u64 v[40:41], v[22:23], 0, v[40:41]
	global_store_dwordx4 v[40:41], v[36:39], off sc1
	ds_read2_b32 v[42:43], v30 offset0:49 offset1:57
	ds_read2_b32 v[44:45], v30 offset0:16 offset1:24
	ds_read2_b32 v[46:47], v30 offset0:82 offset1:90
	ds_read2_b32 v[48:49], v30 offset0:115 offset1:123
	ds_read2_b32 v[50:51], v30 offset0:148 offset1:156
	ds_read2_b32 v[52:53], v30 offset0:181 offset1:189
	ds_read2_b32 v[54:55], v30 offset0:214 offset1:222
	ds_read2_b32 v[56:57], v30 offset0:247 offset1:255
	v_add_u32_e32 v40, s8, v25
	v_ashrrev_i32_e32 v41, 31, v40
	v_lshlrev_b64 v[40:41], 11, v[40:41]
	s_waitcnt lgkmcnt(6)
	v_cvt_pk_bf16_f32 v36, v44, v42
	s_waitcnt lgkmcnt(4)
	v_cvt_pk_bf16_f32 v37, v46, v48
	s_waitcnt lgkmcnt(2)
	v_cvt_pk_bf16_f32 v38, v50, v52
	s_waitcnt lgkmcnt(0)
	v_cvt_pk_bf16_f32 v39, v54, v56
	v_lshl_add_u64 v[40:41], v[22:23], 0, v[40:41]
	global_store_dwordx4 v[40:41], v[36:39], off sc1
	v_add_u32_e32 v40, s8, v26
	v_ashrrev_i32_e32 v41, 31, v40
	v_lshlrev_b64 v[40:41], 11, v[40:41]
	v_cvt_pk_bf16_f32 v36, v45, v43
	v_cvt_pk_bf16_f32 v37, v47, v49
	v_cvt_pk_bf16_f32 v38, v51, v53
	v_cvt_pk_bf16_f32 v39, v55, v57
	v_lshl_add_u64 v[22:23], v[22:23], 0, v[40:41]
	global_store_dwordx4 v[22:23], v[36:39], off sc1
	s_waitcnt lgkmcnt(0)

.LBB0_835:
	s_andn2_b64 vcc, exec, s[8:9]
	s_cbranch_vccnz .LBB0_837
	s_add_i32 s8, s2, 0x7c00
	s_and_b32 s9, s8, 0xffff
	s_mul_i32 s9, s9, 0xaaab
	s_lshr_b32 s20, s9, 16
	s_lshr_b32 s9, s9, 22
	s_load_dwordx2 s[10:11], s[60:61], 0x80
	s_mulk_i32 s9, 0x60
	s_sub_i32 s8, s8, s9
	s_lshl_b32 s8, s8, 5
	s_and_b32 s8, s8, 0xffe0
	s_and_b32 s9, s20, 0xffc0
	s_lshl_b32 s20, s8, 2
	s_waitcnt lgkmcnt(0)
	s_add_u32 s10, s10, s20
	v_add_u32_e32 v64, s9, v3
	s_addc_u32 s11, s11, 0
	v_lshlrev_b32_e32 v0, 2, v2
	v_lshl_add_u64 v[22:23], s[10:11], 0, v[0:1]
	v_add_u32_e32 v0, 8, v64
	v_mad_i64_i32 v[36:37], s[10:11], v64, s40, v[22:23]
	v_mad_i64_i32 v[40:41], s[10:11], v0, s40, v[22:23]
	global_load_dwordx4 v[36:39], v[36:37], off nt
	v_add_u32_e32 v0, 16, v64
	global_load_dwordx4 v[40:43], v[40:41], off nt
	v_mad_i64_i32 v[44:45], s[10:11], v0, s40, v[22:23]
	global_load_dwordx4 v[44:47], v[44:45], off nt
	v_add_u32_e32 v0, 24, v64
	v_mad_i64_i32 v[48:49], s[10:11], v0, s40, v[22:23]
	global_load_dwordx4 v[48:51], v[48:49], off nt
	v_add_u32_e32 v0, 32, v64
	v_mad_i64_i32 v[52:53], s[10:11], v0, s40, v[22:23]
	global_load_dwordx4 v[52:55], v[52:53], off nt
	v_add_u32_e32 v0, 40, v64
	v_mad_i64_i32 v[56:57], s[10:11], v0, s40, v[22:23]
	global_load_dwordx4 v[56:59], v[56:57], off nt
	v_add_u32_e32 v0, 48, v64
	v_mad_i64_i32 v[60:61], s[10:11], v0, s40, v[22:23]
	global_load_dwordx4 v[60:63], v[60:61], off nt
	v_add_u32_e32 v0, 56, v64
	v_mad_i64_i32 v[22:23], s[10:11], v0, s40, v[22:23]
	global_load_dwordx4 v[64:67], v[22:23], off nt
	v_add_u32_e32 v0, v29, v5
	v_add_u32_e32 v22, 0x420, v0
	s_lshl_b32 s62, s9, 1
	s_waitcnt vmcnt(7)
	ds_write2_b32 v0, v36, v37 offset1:1
	ds_write2_b32 v0, v38, v39 offset0:2 offset1:3
	s_waitcnt vmcnt(6)
	ds_write2_b32 v22, v40, v41 offset1:1
	v_add_u32_e32 v22, 0x428, v0
	ds_write2_b32 v22, v42, v43 offset1:1
	v_add_u32_e32 v22, 0x840, v0
	s_waitcnt vmcnt(5)
	ds_write2_b32 v22, v44, v45 offset1:1
	v_add_u32_e32 v22, 0x848, v0
	ds_write2_b32 v22, v46, v47 offset1:1
	v_add_u32_e32 v22, 0xc60, v0
	s_waitcnt vmcnt(4)
	ds_write2_b32 v22, v48, v49 offset1:1
	v_add_u32_e32 v22, 0xc68, v0
	ds_write2_b32 v22, v50, v51 offset1:1
	v_add_u32_e32 v22, 0x1080, v0
	s_waitcnt vmcnt(3)
	ds_write2_b32 v22, v52, v53 offset1:1
	v_add_u32_e32 v22, 0x1088, v0
	ds_write2_b32 v22, v54, v55 offset1:1
	v_add_u32_e32 v22, 0x14a0, v0
	s_waitcnt vmcnt(2)
	ds_write2_b32 v22, v56, v57 offset1:1
	v_add_u32_e32 v22, 0x14a8, v0
	ds_write2_b32 v22, v58, v59 offset1:1
	v_add_u32_e32 v22, 0x18c0, v0
	s_waitcnt vmcnt(1)
	ds_write2_b32 v22, v60, v61 offset1:1
	v_add_u32_e32 v22, 0x18c8, v0
	ds_write2_b32 v22, v62, v63 offset1:1
	v_add_u32_e32 v22, 0x1ce0, v0
	v_add_u32_e32 v0, 0x1ce8, v0
	s_waitcnt vmcnt(0)
	ds_write2_b32 v22, v64, v65 offset1:1
	ds_write2_b32 v0, v66, v67 offset1:1
	s_waitcnt lgkmcnt(0)
	ds_read2_b32 v[42:43], v30 offset0:33 offset1:41
	ds_read2_b32 v[44:45], v30 offset1:8
	ds_read2_b32 v[46:47], v30 offset0:66 offset1:74
	ds_read2_b32 v[48:49], v30 offset0:99 offset1:107
	ds_read2_b32 v[50:51], v30 offset0:132 offset1:140
	ds_read2_b32 v[52:53], v30 offset0:165 offset1:173
	ds_read2_b32 v[54:55], v30 offset0:198 offset1:206
	ds_read2_b32 v[56:57], v30 offset0:231 offset1:239
	v_add_u32_e32 v40, s8, v3
	v_ashrrev_i32_e32 v41, 31, v40
	v_lshl_add_u64 v[22:23], v[20:21], 0, s[62:63]
	v_lshlrev_b64 v[40:41], 11, v[40:41]
	s_waitcnt lgkmcnt(6)
	v_cvt_pk_bf16_f32 v36, v44, v42
	s_waitcnt lgkmcnt(4)
	v_cvt_pk_bf16_f32 v37, v46, v48
	s_waitcnt lgkmcnt(2)
	v_cvt_pk_bf16_f32 v38, v50, v52
	s_waitcnt lgkmcnt(0)
	v_cvt_pk_bf16_f32 v39, v54, v56
	v_lshl_add_u64 v[40:41], v[22:23], 0, v[40:41]
	global_store_dwordx4 v[40:41], v[36:39], off sc1
	v_add_u32_e32 v40, s8, v24
	v_ashrrev_i32_e32 v41, 31, v40
	v_lshlrev_b64 v[40:41], 11, v[40:41]
	v_cvt_pk_bf16_f32 v36, v45, v43
	v_cvt_pk_bf16_f32 v37, v47, v49
	v_cvt_pk_bf16_f32 v38, v51, v53
	v_cvt_pk_bf16_f32 v39, v55, v57
	v_lshl_add_u64 v[40:41], v[22:23], 0, v[40:41]
	global_store_dwordx4 v[40:41], v[36:39], off sc1
	ds_read2_b32 v[42:43], v30 offset0:49 offset1:57
	ds_read2_b32 v[44:45], v30 offset0:16 offset1:24
	ds_read2_b32 v[46:47], v30 offset0:82 offset1:90
	ds_read2_b32 v[48:49], v30 offset0:115 offset1:123
	ds_read2_b32 v[50:51], v30 offset0:148 offset1:156
	ds_read2_b32 v[52:53], v30 offset0:181 offset1:189
	ds_read2_b32 v[54:55], v30 offset0:214 offset1:222
	ds_read2_b32 v[56:57], v30 offset0:247 offset1:255
	v_add_u32_e32 v40, s8, v25
	v_ashrrev_i32_e32 v41, 31, v40
	v_lshlrev_b64 v[40:41], 11, v[40:41]
	s_waitcnt lgkmcnt(6)
	v_cvt_pk_bf16_f32 v36, v44, v42
	s_waitcnt lgkmcnt(4)
	v_cvt_pk_bf16_f32 v37, v46, v48
	s_waitcnt lgkmcnt(2)
	v_cvt_pk_bf16_f32 v38, v50, v52
	s_waitcnt lgkmcnt(0)
	v_cvt_pk_bf16_f32 v39, v54, v56
	v_lshl_add_u64 v[40:41], v[22:23], 0, v[40:41]
	global_store_dwordx4 v[40:41], v[36:39], off sc1
	v_add_u32_e32 v40, s8, v26
	v_ashrrev_i32_e32 v41, 31, v40
	v_lshlrev_b64 v[40:41], 11, v[40:41]
	v_cvt_pk_bf16_f32 v36, v45, v43
	v_cvt_pk_bf16_f32 v37, v47, v49
	v_cvt_pk_bf16_f32 v38, v51, v53
	v_cvt_pk_bf16_f32 v39, v55, v57
	v_lshl_add_u64 v[22:23], v[22:23], 0, v[40:41]
	global_store_dwordx4 v[22:23], v[36:39], off sc1
	s_waitcnt lgkmcnt(0)

.LBB0_838:
	s_andn2_b64 vcc, exec, s[8:9]
	s_cbranch_vccnz .LBB0_803
	s_mul_hi_i32 s8, s2, 0x3e0f83e1
	s_lshr_b32 s9, s8, 31
	s_ashr_i32 s8, s8, 10
	s_add_i32 s24, s8, s9
	s_mul_i32 s8, s24, 0xffffef80
	s_add_i32 s10, s2, s8
	s_mul_i32 s8, s10, 0xba3
	s_lshr_b32 s9, s8, 31
	s_lshr_b32 s8, s8, 22
	s_add_i32 s8, s8, s9
	s_mulk_i32 s8, 0x580
	s_sub_i32 s22, s10, s8
	s_mul_i32 s9, s24, 0x1080000
	s_mul_hi_i32 s8, s24, 0x1080000
	s_add_u32 s20, s14, s9
	s_addc_u32 s21, s15, s8
	s_add_i32 s8, s10, 0x57f
	s_cmpk_gt_u32 s8, 0xafe
	s_mul_hi_i32 s23, s24, 0xb00000
	s_mul_i32 s24, s24, 0xb00000
	s_mov_b64 s[8:9], -1
	s_cbranch_scc0 .LBB0_845
	s_addk_i32 s10, 0xfa80
	s_cmpk_gt_u32 s10, 0x57f
	s_cbranch_scc0 .LBB0_842
	s_load_dwordx2 s[8:9], s[60:61], 0x78
	v_lshlrev_b32_e32 v0, 2, v2
	s_waitcnt lgkmcnt(0)
	s_add_u32 s11, s8, s24
	s_sext_i32_i16 s8, s22
	s_addc_u32 s25, s9, s23
	s_bfe_u32 s8, s8, 0x5001a
	s_add_i32 s8, s22, s8
	s_sext_i32_i16 s9, s8
	s_and_b32 s8, s8, 0xffe0
	s_sub_i32 s8, s22, s8
	s_sext_i32_i16 s8, s8
	s_lshl_b32 s9, s9, 1
	s_lshl_b32 s8, s8, 5
	s_and_b32 s10, s9, 0xffffffc0
	s_ashr_i32 s9, s8, 31
	s_lshl_b64 s[26:27], s[8:9], 2
	v_add_u32_e32 v22, s10, v3
	s_add_u32 s26, s11, s26
	s_addc_u32 s27, s25, s27
	v_ashrrev_i32_e32 v23, 31, v22
	v_lshl_add_u64 v[36:37], s[26:27], 0, v[0:1]
	v_lshlrev_b64 v[22:23], 12, v[22:23]
	v_lshl_add_u64 v[22:23], v[36:37], 0, v[22:23]
	s_mov_b32 s9, 0x8000
	v_add_co_u32_e32 v40, vcc, s9, v22
	s_mov_b32 s9, 0x10000
	s_nop 0
	v_addc_co_u32_e32 v41, vcc, 0, v23, vcc
	global_load_dwordx4 v[36:39], v[22:23], off nt
	v_add_co_u32_e32 v44, vcc, s9, v22
	global_load_dwordx4 v[40:43], v[40:41], off nt
	s_nop 0
	v_addc_co_u32_e32 v45, vcc, 0, v23, vcc
	global_load_dwordx4 v[44:47], v[44:45], off nt
	v_add_co_u32_e32 v48, vcc, s41, v22
	s_mov_b32 s9, 0x30000
	s_nop 0
	v_addc_co_u32_e32 v49, vcc, 0, v23, vcc
	global_load_dwordx4 v[48:51], v[48:49], off nt
	v_add_co_u32_e32 v52, vcc, s82, v22
	v_add_u32_e32 v0, v29, v5
	s_nop 0
	v_addc_co_u32_e32 v53, vcc, 0, v23, vcc
	global_load_dwordx4 v[52:55], v[52:53], off nt
	v_add_co_u32_e32 v56, vcc, s44, v22
	s_ashr_i32 s11, s10, 31
	s_nop 0
	v_addc_co_u32_e32 v57, vcc, 0, v23, vcc
	global_load_dwordx4 v[56:59], v[56:57], off nt
	v_add_co_u32_e32 v60, vcc, s9, v22
	s_mov_b32 s9, 0x38000
	s_nop 0
	v_addc_co_u32_e32 v61, vcc, 0, v23, vcc
	global_load_dwordx4 v[60:63], v[60:61], off nt
	v_add_co_u32_e32 v22, vcc, s9, v22
	s_lshl_b64 s[10:11], s[10:11], 1
	s_nop 0
	v_addc_co_u32_e32 v23, vcc, 0, v23, vcc
	global_load_dwordx4 v[64:67], v[22:23], off nt
	v_add_u32_e32 v22, 0x420, v0
	s_add_u32 s10, s20, s10
	s_addc_u32 s11, s21, s11
	s_movk_i32 s9, 0x1600
	s_waitcnt vmcnt(7)
	ds_write2_b32 v0, v36, v37 offset1:1
	ds_write2_b32 v0, v38, v39 offset0:2 offset1:3
	s_waitcnt vmcnt(6)
	ds_write2_b32 v22, v40, v41 offset1:1
	v_add_u32_e32 v22, 0x428, v0
	ds_write2_b32 v22, v42, v43 offset1:1
	v_add_u32_e32 v22, 0x840, v0
	s_waitcnt vmcnt(5)
	ds_write2_b32 v22, v44, v45 offset1:1
	v_add_u32_e32 v22, 0x848, v0
	ds_write2_b32 v22, v46, v47 offset1:1
	v_add_u32_e32 v22, 0xc60, v0
	s_waitcnt vmcnt(4)
	ds_write2_b32 v22, v48, v49 offset1:1
	v_add_u32_e32 v22, 0xc68, v0
	ds_write2_b32 v22, v50, v51 offset1:1
	v_add_u32_e32 v22, 0x1080, v0
	s_waitcnt vmcnt(3)
	ds_write2_b32 v22, v52, v53 offset1:1
	v_add_u32_e32 v22, 0x1088, v0
	ds_write2_b32 v22, v54, v55 offset1:1
	v_add_u32_e32 v22, 0x14a0, v0
	s_waitcnt vmcnt(2)
	ds_write2_b32 v22, v56, v57 offset1:1
	v_add_u32_e32 v22, 0x14a8, v0
	ds_write2_b32 v22, v58, v59 offset1:1
	v_add_u32_e32 v22, 0x18c0, v0
	s_waitcnt vmcnt(1)
	ds_write2_b32 v22, v60, v61 offset1:1
	v_add_u32_e32 v22, 0x18c8, v0
	ds_write2_b32 v22, v62, v63 offset1:1
	v_add_u32_e32 v22, 0x1ce0, v0
	v_add_u32_e32 v0, 0x1ce8, v0
	s_waitcnt vmcnt(0)
	ds_write2_b32 v22, v64, v65 offset1:1
	ds_write2_b32 v0, v66, v67 offset1:1
	s_waitcnt lgkmcnt(0)
	ds_read2_b32 v[40:41], v30 offset0:33 offset1:41
	ds_read2_b32 v[42:43], v30 offset1:8
	ds_read2_b32 v[44:45], v30 offset0:66 offset1:74
	ds_read2_b32 v[46:47], v30 offset0:99 offset1:107
	ds_read2_b32 v[48:49], v30 offset0:132 offset1:140
	ds_read2_b32 v[50:51], v30 offset0:165 offset1:173
	ds_read2_b32 v[52:53], v30 offset0:198 offset1:206
	ds_read2_b32 v[54:55], v30 offset0:231 offset1:239
	v_lshlrev_b32_e32 v0, 1, v4
	v_lshl_add_u64 v[22:23], s[10:11], 0, v[0:1]
	s_mov_b64 s[10:11], 0xb00000
	v_lshl_add_u64 v[22:23], v[22:23], 0, s[10:11]
	v_add_u32_e32 v0, s8, v3
	s_waitcnt lgkmcnt(6)
	v_cvt_pk_bf16_f32 v36, v42, v40
	s_waitcnt lgkmcnt(4)
	v_cvt_pk_bf16_f32 v37, v44, v46
	s_waitcnt lgkmcnt(2)
	v_cvt_pk_bf16_f32 v38, v48, v50
	s_waitcnt lgkmcnt(0)
	v_cvt_pk_bf16_f32 v39, v52, v54
	v_mad_i64_i32 v[56:57], s[10:11], v0, s9, v[22:23]
	v_add_u32_e32 v0, s8, v24
	global_store_dwordx4 v[56:57], v[36:39], off sc1
	s_nop 1
	v_cvt_pk_bf16_f32 v36, v43, v41
	v_cvt_pk_bf16_f32 v37, v45, v47
	v_cvt_pk_bf16_f32 v38, v49, v51
	v_cvt_pk_bf16_f32 v39, v53, v55
	v_mad_i64_i32 v[40:41], s[10:11], v0, s9, v[22:23]
	global_store_dwordx4 v[40:41], v[36:39], off sc1
	ds_read2_b32 v[40:41], v30 offset0:49 offset1:57
	ds_read2_b32 v[42:43], v30 offset0:16 offset1:24
	ds_read2_b32 v[44:45], v30 offset0:82 offset1:90
	ds_read2_b32 v[46:47], v30 offset0:115 offset1:123
	ds_read2_b32 v[48:49], v30 offset0:148 offset1:156
	ds_read2_b32 v[50:51], v30 offset0:181 offset1:189
	ds_read2_b32 v[52:53], v30 offset0:214 offset1:222
	ds_read2_b32 v[54:55], v30 offset0:247 offset1:255
	v_add_u32_e32 v0, s8, v25
	s_waitcnt lgkmcnt(6)
	v_cvt_pk_bf16_f32 v36, v42, v40
	s_waitcnt lgkmcnt(4)
	v_cvt_pk_bf16_f32 v37, v44, v46
	s_waitcnt lgkmcnt(2)
	v_cvt_pk_bf16_f32 v38, v48, v50
	s_waitcnt lgkmcnt(0)
	v_cvt_pk_bf16_f32 v39, v52, v54
	v_mad_i64_i32 v[56:57], s[10:11], v0, s9, v[22:23]
	v_add_u32_e32 v0, s8, v26
	global_store_dwordx4 v[56:57], v[36:39], off sc1
	v_mad_i64_i32 v[22:23], s[8:9], v0, s9, v[22:23]
	s_nop 0
	v_cvt_pk_bf16_f32 v36, v43, v41
	v_cvt_pk_bf16_f32 v37, v45, v47
	v_cvt_pk_bf16_f32 v38, v49, v51
	v_cvt_pk_bf16_f32 v39, v53, v55
	global_store_dwordx4 v[22:23], v[36:39], off sc1
	s_waitcnt lgkmcnt(0)
	s_mov_b64 s[8:9], 0
.LBB0_842:
	s_andn2_b64 vcc, exec, s[8:9]
	s_cbranch_vccnz .LBB0_844
	s_load_dwordx2 s[8:9], s[60:61], 0x70
	v_lshlrev_b32_e32 v0, 2, v2
	s_waitcnt lgkmcnt(0)
	s_add_u32 s10, s8, s24
	s_addc_u32 s9, s9, s23
	s_and_b32 s8, 0xffff, s22
	s_mul_i32 s8, s8, 0xba2f
	s_lshr_b32 s11, s8, 16
	s_lshr_b32 s8, s8, 22
	s_mulk_i32 s8, 0x58
	s_sub_i32 s8, s22, s8
	s_lshl_b32 s8, s8, 5
	s_and_b32 s8, s8, 0xffe0
	s_and_b32 s25, s11, 0xffc0
	s_lshl_b32 s11, s8, 2
	s_add_u32 s10, s10, s11
	v_add_u32_e32 v64, s25, v3
	s_addc_u32 s11, s9, 0
	v_lshl_add_u64 v[22:23], s[10:11], 0, v[0:1]
	s_movk_i32 s9, 0x2c00
	v_add_u32_e32 v0, 8, v64
	v_mad_i64_i32 v[36:37], s[10:11], v64, s9, v[22:23]
	v_mad_i64_i32 v[40:41], s[10:11], v0, s9, v[22:23]
	global_load_dwordx4 v[36:39], v[36:37], off nt
	v_add_u32_e32 v0, 16, v64
	global_load_dwordx4 v[40:43], v[40:41], off nt
	v_mad_i64_i32 v[44:45], s[10:11], v0, s9, v[22:23]
	global_load_dwordx4 v[44:47], v[44:45], off nt
	v_add_u32_e32 v0, 24, v64
	v_mad_i64_i32 v[48:49], s[10:11], v0, s9, v[22:23]
	global_load_dwordx4 v[48:51], v[48:49], off nt
	v_add_u32_e32 v0, 32, v64
	v_mad_i64_i32 v[52:53], s[10:11], v0, s9, v[22:23]
	global_load_dwordx4 v[52:55], v[52:53], off nt
	v_add_u32_e32 v0, 40, v64
	v_mad_i64_i32 v[56:57], s[10:11], v0, s9, v[22:23]
	global_load_dwordx4 v[56:59], v[56:57], off nt
	v_add_u32_e32 v0, 48, v64
	v_mad_i64_i32 v[60:61], s[10:11], v0, s9, v[22:23]
	global_load_dwordx4 v[60:63], v[60:61], off nt
	v_add_u32_e32 v0, 56, v64
	v_mad_i64_i32 v[22:23], s[10:11], v0, s9, v[22:23]
	global_load_dwordx4 v[64:67], v[22:23], off nt
	v_add_u32_e32 v0, v29, v5
	v_add_u32_e32 v22, 0x420, v0
	s_lshl_b32 s9, s25, 1
	s_add_u32 s10, s20, s9
	s_addc_u32 s11, s21, 0
	s_waitcnt vmcnt(7)
	ds_write2_b32 v0, v36, v37 offset1:1
	ds_write2_b32 v0, v38, v39 offset0:2 offset1:3
	s_waitcnt vmcnt(6)
	ds_write2_b32 v22, v40, v41 offset1:1
	v_add_u32_e32 v22, 0x428, v0
	ds_write2_b32 v22, v42, v43 offset1:1
	v_add_u32_e32 v22, 0x840, v0
	s_waitcnt vmcnt(5)
	ds_write2_b32 v22, v44, v45 offset1:1
	v_add_u32_e32 v22, 0x848, v0
	ds_write2_b32 v22, v46, v47 offset1:1
	v_add_u32_e32 v22, 0xc60, v0
	s_waitcnt vmcnt(4)
	ds_write2_b32 v22, v48, v49 offset1:1
	v_add_u32_e32 v22, 0xc68, v0
	ds_write2_b32 v22, v50, v51 offset1:1
	v_add_u32_e32 v22, 0x1080, v0
	s_waitcnt vmcnt(3)
	ds_write2_b32 v22, v52, v53 offset1:1
	v_add_u32_e32 v22, 0x1088, v0
	ds_write2_b32 v22, v54, v55 offset1:1
	v_add_u32_e32 v22, 0x14a0, v0
	s_waitcnt vmcnt(2)
	ds_write2_b32 v22, v56, v57 offset1:1
	v_add_u32_e32 v22, 0x14a8, v0
	ds_write2_b32 v22, v58, v59 offset1:1
	v_add_u32_e32 v22, 0x18c0, v0
	s_waitcnt vmcnt(1)
	ds_write2_b32 v22, v60, v61 offset1:1
	v_add_u32_e32 v22, 0x18c8, v0
	ds_write2_b32 v22, v62, v63 offset1:1
	v_add_u32_e32 v22, 0x1ce0, v0
	v_add_u32_e32 v0, 0x1ce8, v0
	s_waitcnt vmcnt(0)
	ds_write2_b32 v22, v64, v65 offset1:1
	ds_write2_b32 v0, v66, v67 offset1:1
	s_waitcnt lgkmcnt(0)
	v_lshlrev_b32_e32 v0, 1, v4
	ds_read2_b32 v[42:43], v30 offset0:33 offset1:41
	ds_read2_b32 v[44:45], v30 offset1:8
	ds_read2_b32 v[46:47], v30 offset0:66 offset1:74
	ds_read2_b32 v[48:49], v30 offset0:99 offset1:107
	ds_read2_b32 v[50:51], v30 offset0:132 offset1:140
	ds_read2_b32 v[52:53], v30 offset0:165 offset1:173
	ds_read2_b32 v[54:55], v30 offset0:198 offset1:206
	ds_read2_b32 v[56:57], v30 offset0:231 offset1:239
	v_lshl_add_u64 v[22:23], s[10:11], 0, v[0:1]
	v_add_lshl_u32 v0, v3, s8, 1
	v_and_or_b32 v40, v0, s43, v33
	v_ashrrev_i32_e32 v41, 31, v40
	v_lshlrev_b64 v[40:41], 11, v[40:41]
	s_waitcnt lgkmcnt(6)
	v_cvt_pk_bf16_f32 v36, v44, v42
	s_waitcnt lgkmcnt(4)
	v_cvt_pk_bf16_f32 v37, v46, v48
	s_waitcnt lgkmcnt(2)
	v_cvt_pk_bf16_f32 v38, v50, v52
	s_waitcnt lgkmcnt(0)
	v_cvt_pk_bf16_f32 v39, v54, v56
	v_lshl_add_u64 v[40:41], v[22:23], 0, v[40:41]
	v_add_lshl_u32 v0, v24, s8, 1
	global_store_dwordx4 v[40:41], v[36:39], off sc1
	v_and_or_b32 v40, v0, s43, v34
	v_ashrrev_i32_e32 v41, 31, v40
	v_lshlrev_b64 v[40:41], 11, v[40:41]
	v_cvt_pk_bf16_f32 v36, v45, v43
	v_cvt_pk_bf16_f32 v37, v47, v49
	v_cvt_pk_bf16_f32 v38, v51, v53
	v_cvt_pk_bf16_f32 v39, v55, v57
	v_lshl_add_u64 v[40:41], v[22:23], 0, v[40:41]
	global_store_dwordx4 v[40:41], v[36:39], off sc1
	ds_read2_b32 v[42:43], v30 offset0:16 offset1:24
	ds_read2_b32 v[44:45], v30 offset0:49 offset1:57
	ds_read2_b32 v[46:47], v30 offset0:82 offset1:90
	ds_read2_b32 v[48:49], v30 offset0:115 offset1:123
	ds_read2_b32 v[50:51], v30 offset0:148 offset1:156
	ds_read2_b32 v[52:53], v30 offset0:181 offset1:189
	ds_read2_b32 v[54:55], v30 offset0:214 offset1:222
	ds_read2_b32 v[56:57], v30 offset0:247 offset1:255
	v_add_lshl_u32 v0, v25, s8, 1
	v_and_or_b32 v40, v0, s43, v33
	v_ashrrev_i32_e32 v41, 31, v40
	v_lshlrev_b64 v[40:41], 11, v[40:41]
	s_waitcnt lgkmcnt(6)
	v_cvt_pk_bf16_f32 v36, v42, v44
	s_waitcnt lgkmcnt(4)
	v_cvt_pk_bf16_f32 v37, v46, v48
	s_waitcnt lgkmcnt(2)
	v_cvt_pk_bf16_f32 v38, v50, v52
	s_waitcnt lgkmcnt(0)
	v_cvt_pk_bf16_f32 v39, v54, v56
	v_lshl_add_u64 v[40:41], v[22:23], 0, v[40:41]
	v_add_lshl_u32 v0, v26, s8, 1
	global_store_dwordx4 v[40:41], v[36:39], off sc1
	v_and_or_b32 v40, v0, s43, v35
	v_ashrrev_i32_e32 v41, 31, v40
	v_lshlrev_b64 v[40:41], 11, v[40:41]
	v_cvt_pk_bf16_f32 v36, v43, v45
	v_cvt_pk_bf16_f32 v37, v47, v49
	v_cvt_pk_bf16_f32 v38, v51, v53
	v_cvt_pk_bf16_f32 v39, v55, v57
	v_lshl_add_u64 v[22:23], v[22:23], 0, v[40:41]
	global_store_dwordx4 v[22:23], v[36:39], off sc1
	s_waitcnt lgkmcnt(0)

.LBB0_845:
	s_andn2_b64 vcc, exec, s[8:9]
	s_cbranch_vccnz .LBB0_803
	s_load_dwordx2 s[8:9], s[60:61], 0x68
	v_lshlrev_b32_e32 v0, 2, v2
	s_waitcnt lgkmcnt(0)
	s_add_u32 s11, s8, s24
	s_sext_i32_i16 s8, s22
	s_mulk_i32 s8, 0xba3
	s_addc_u32 s24, s9, s23
	s_lshr_b32 s9, s8, 31
	s_ashr_i32 s8, s8, 18
	s_add_i32 s8, s8, s9
	s_sext_i32_i16 s9, s8
	s_mulk_i32 s8, 0x58
	s_sub_i32 s8, s22, s8
	s_sext_i32_i16 s8, s8
	s_lshl_b32 s8, s8, 5
	s_lshl_b32 s10, s9, 6
	s_ashr_i32 s9, s8, 31
	s_lshl_b64 s[22:23], s[8:9], 2
	s_add_u32 s22, s11, s22
	v_add_u32_e32 v64, s10, v3
	s_addc_u32 s23, s24, s23
	v_lshl_add_u64 v[22:23], s[22:23], 0, v[0:1]
	s_movk_i32 s9, 0x2c00
	v_add_u32_e32 v0, 8, v64
	v_mad_i64_i32 v[36:37], s[22:23], v64, s9, v[22:23]
	v_mad_i64_i32 v[40:41], s[22:23], v0, s9, v[22:23]
	global_load_dwordx4 v[36:39], v[36:37], off nt
	v_add_u32_e32 v0, 16, v64
	global_load_dwordx4 v[40:43], v[40:41], off nt
	v_mad_i64_i32 v[44:45], s[22:23], v0, s9, v[22:23]
	global_load_dwordx4 v[44:47], v[44:45], off nt
	v_add_u32_e32 v0, 24, v64
	v_mad_i64_i32 v[48:49], s[22:23], v0, s9, v[22:23]
	global_load_dwordx4 v[48:51], v[48:49], off nt
	v_add_u32_e32 v0, 32, v64
	v_mad_i64_i32 v[52:53], s[22:23], v0, s9, v[22:23]
	global_load_dwordx4 v[52:55], v[52:53], off nt
	v_add_u32_e32 v0, 40, v64
	v_mad_i64_i32 v[56:57], s[22:23], v0, s9, v[22:23]
	global_load_dwordx4 v[56:59], v[56:57], off nt
	v_add_u32_e32 v0, 48, v64
	v_mad_i64_i32 v[60:61], s[22:23], v0, s9, v[22:23]
	global_load_dwordx4 v[60:63], v[60:61], off nt
	v_add_u32_e32 v0, 56, v64
	v_mad_i64_i32 v[22:23], s[22:23], v0, s9, v[22:23]
	global_load_dwordx4 v[64:67], v[22:23], off nt
	v_add_u32_e32 v0, v29, v5
	v_add_u32_e32 v22, 0x420, v0
	s_ashr_i32 s11, s10, 31
	s_lshl_b64 s[10:11], s[10:11], 1
	s_add_u32 s10, s20, s10
	s_addc_u32 s11, s21, s11
	s_waitcnt vmcnt(7)
	ds_write2_b32 v0, v36, v37 offset1:1
	ds_write2_b32 v0, v38, v39 offset0:2 offset1:3
	s_waitcnt vmcnt(6)
	ds_write2_b32 v22, v40, v41 offset1:1
	v_add_u32_e32 v22, 0x428, v0
	ds_write2_b32 v22, v42, v43 offset1:1
	v_add_u32_e32 v22, 0x840, v0
	s_waitcnt vmcnt(5)
	ds_write2_b32 v22, v44, v45 offset1:1
	v_add_u32_e32 v22, 0x848, v0
	ds_write2_b32 v22, v46, v47 offset1:1
	v_add_u32_e32 v22, 0xc60, v0
	s_waitcnt vmcnt(4)
	ds_write2_b32 v22, v48, v49 offset1:1
	v_add_u32_e32 v22, 0xc68, v0
	ds_write2_b32 v22, v50, v51 offset1:1
	v_add_u32_e32 v22, 0x1080, v0
	s_waitcnt vmcnt(3)
	ds_write2_b32 v22, v52, v53 offset1:1
	v_add_u32_e32 v22, 0x1088, v0
	ds_write2_b32 v22, v54, v55 offset1:1
	v_add_u32_e32 v22, 0x14a0, v0
	s_waitcnt vmcnt(2)
	ds_write2_b32 v22, v56, v57 offset1:1
	v_add_u32_e32 v22, 0x14a8, v0
	ds_write2_b32 v22, v58, v59 offset1:1
	v_add_u32_e32 v22, 0x18c0, v0
	s_waitcnt vmcnt(1)
	ds_write2_b32 v22, v60, v61 offset1:1
	v_add_u32_e32 v22, 0x18c8, v0
	ds_write2_b32 v22, v62, v63 offset1:1
	v_add_u32_e32 v22, 0x1ce0, v0
	v_add_u32_e32 v0, 0x1ce8, v0
	s_waitcnt vmcnt(0)
	ds_write2_b32 v22, v64, v65 offset1:1
	ds_write2_b32 v0, v66, v67 offset1:1
	s_waitcnt lgkmcnt(0)
	v_lshlrev_b32_e32 v0, 1, v4
	ds_read2_b32 v[42:43], v30 offset0:33 offset1:41
	ds_read2_b32 v[44:45], v30 offset1:8
	ds_read2_b32 v[46:47], v30 offset0:66 offset1:74
	ds_read2_b32 v[48:49], v30 offset0:99 offset1:107
	ds_read2_b32 v[50:51], v30 offset0:132 offset1:140
	ds_read2_b32 v[52:53], v30 offset0:165 offset1:173
	ds_read2_b32 v[54:55], v30 offset0:198 offset1:206
	ds_read2_b32 v[56:57], v30 offset0:231 offset1:239
	v_lshl_add_u64 v[22:23], s[10:11], 0, v[0:1]
	v_add_lshl_u32 v0, s8, v3, 1
	v_and_or_b32 v40, v0, s43, v27
	v_ashrrev_i32_e32 v41, 31, v40
	v_lshlrev_b64 v[40:41], 11, v[40:41]
	s_waitcnt lgkmcnt(6)
	v_cvt_pk_bf16_f32 v36, v44, v42
	s_waitcnt lgkmcnt(4)
	v_cvt_pk_bf16_f32 v37, v46, v48
	s_waitcnt lgkmcnt(2)
	v_cvt_pk_bf16_f32 v38, v50, v52
	s_waitcnt lgkmcnt(0)
	v_cvt_pk_bf16_f32 v39, v54, v56
	v_lshl_add_u64 v[40:41], v[22:23], 0, v[40:41]
	v_add_lshl_u32 v0, s8, v24, 1
	global_store_dwordx4 v[40:41], v[36:39], off sc1
	v_and_or_b32 v40, v0, s43, v31
	v_ashrrev_i32_e32 v41, 31, v40
	v_lshlrev_b64 v[40:41], 11, v[40:41]
	v_cvt_pk_bf16_f32 v36, v45, v43
	v_cvt_pk_bf16_f32 v37, v47, v49
	v_cvt_pk_bf16_f32 v38, v51, v53
	v_cvt_pk_bf16_f32 v39, v55, v57
	v_lshl_add_u64 v[40:41], v[22:23], 0, v[40:41]
	global_store_dwordx4 v[40:41], v[36:39], off sc1
	ds_read2_b32 v[42:43], v30 offset0:16 offset1:24
	ds_read2_b32 v[44:45], v30 offset0:49 offset1:57
	ds_read2_b32 v[46:47], v30 offset0:82 offset1:90
	ds_read2_b32 v[48:49], v30 offset0:115 offset1:123
	ds_read2_b32 v[50:51], v30 offset0:148 offset1:156
	ds_read2_b32 v[52:53], v30 offset0:181 offset1:189
	ds_read2_b32 v[54:55], v30 offset0:214 offset1:222
	ds_read2_b32 v[56:57], v30 offset0:247 offset1:255
	v_add_lshl_u32 v0, s8, v25, 1
	v_and_or_b32 v40, v0, s43, v27
	v_ashrrev_i32_e32 v41, 31, v40
	v_lshlrev_b64 v[40:41], 11, v[40:41]
	s_waitcnt lgkmcnt(6)
	v_cvt_pk_bf16_f32 v36, v42, v44
	s_waitcnt lgkmcnt(4)
	v_cvt_pk_bf16_f32 v37, v46, v48
	s_waitcnt lgkmcnt(2)
	v_cvt_pk_bf16_f32 v38, v50, v52
	s_waitcnt lgkmcnt(0)
	v_cvt_pk_bf16_f32 v39, v54, v56
	v_lshl_add_u64 v[40:41], v[22:23], 0, v[40:41]
	v_add_lshl_u32 v0, s8, v26, 1
	global_store_dwordx4 v[40:41], v[36:39], off sc1
	v_and_or_b32 v40, v0, s43, v32
	v_ashrrev_i32_e32 v41, 31, v40
	v_lshlrev_b64 v[40:41], 11, v[40:41]
	v_cvt_pk_bf16_f32 v36, v43, v45
	v_cvt_pk_bf16_f32 v37, v47, v49
	v_cvt_pk_bf16_f32 v38, v51, v53
	v_cvt_pk_bf16_f32 v39, v55, v57
	v_lshl_add_u64 v[22:23], v[22:23], 0, v[40:41]
	global_store_dwordx4 v[22:23], v[36:39], off sc1
	s_waitcnt lgkmcnt(0)
	s_branch .LBB0_803

.LBB0_850:
	s_cmp_gt_i32 s1, 0x83ff
	s_mov_b64 s[2:3], -1
	s_cbranch_scc0 .LBB0_884
	s_cmpk_gt_u32 s1, 0x89ff
	s_cbranch_scc0 .LBB0_881
	s_cmpk_gt_u32 s1, 0x8bff
	s_cbranch_scc0 .LBB0_878
	s_cmpk_gt_u32 s1, 0x8dff
	s_cbranch_scc0 .LBB0_875
	s_cmpk_gt_u32 s1, 0x8fff
	s_cbranch_scc0 .LBB0_872
	s_cmpk_gt_u32 s1, 0x93ff
	s_cbranch_scc0 .LBB0_869
	s_cmpk_gt_u32 s1, 0x95ff
	s_cbranch_scc0 .LBB0_866
	s_cmpk_gt_u32 s1, 0x9bff
	s_cbranch_scc0 .LBB0_863
	s_cmpk_gt_u32 s1, 0x9dff
	s_cbranch_scc0 .LBB0_860
	s_add_i32 s2, s1, 0xffff6200
	s_lshr_b32 s62, s2, 8
	s_load_dwordx2 s[2:3], s[60:61], 0x30
	s_lshl_b64 s[8:9], s[62:63], 21
	v_lshlrev_b32_e32 v0, 2, v2
	s_waitcnt lgkmcnt(0)
	s_add_u32 s8, s2, s8
	s_addc_u32 s9, s3, s9
	s_lshl_b64 s[2:3], s[62:63], 20
	s_add_u32 s17, s6, s2
	s_addc_u32 s3, s10, s3
	s_and_b32 s2, s15, 0x3e0
	s_and_b32 s18, s13, 0x1c0
	s_lshl_b32 s19, s2, 2
	v_add_u32_e32 v22, s18, v3
	s_add_u32 s8, s8, s19
	s_addc_u32 s9, s9, 0
	v_ashrrev_i32_e32 v23, 31, v22
	v_lshl_add_u64 v[36:37], s[8:9], 0, v[0:1]
	v_lshlrev_b64 v[22:23], 12, v[22:23]
	v_lshl_add_u64 v[22:23], v[36:37], 0, v[22:23]
	s_mov_b32 s8, 0x8000
	v_add_co_u32_e32 v40, vcc, s8, v22
	s_mov_b32 s8, 0x10000
	s_nop 0
	v_addc_co_u32_e32 v41, vcc, 0, v23, vcc
	global_load_dwordx4 v[36:39], v[22:23], off nt
	v_add_co_u32_e32 v44, vcc, s8, v22
	global_load_dwordx4 v[40:43], v[40:41], off nt
	s_nop 0
	v_addc_co_u32_e32 v45, vcc, 0, v23, vcc
	global_load_dwordx4 v[44:47], v[44:45], off nt
	v_add_co_u32_e32 v48, vcc, s41, v22
	s_mov_b32 s8, 0x30000
	s_nop 0
	v_addc_co_u32_e32 v49, vcc, 0, v23, vcc
	global_load_dwordx4 v[48:51], v[48:49], off nt
	v_add_co_u32_e32 v52, vcc, s82, v22
	v_add_u32_e32 v0, v29, v5
	s_nop 0
	v_addc_co_u32_e32 v53, vcc, 0, v23, vcc
	global_load_dwordx4 v[52:55], v[52:53], off nt
	v_add_co_u32_e32 v56, vcc, s44, v22
	s_nop 1
	v_addc_co_u32_e32 v57, vcc, 0, v23, vcc
	global_load_dwordx4 v[56:59], v[56:57], off nt
	v_add_co_u32_e32 v60, vcc, s8, v22
	s_mov_b32 s8, 0x38000
	s_nop 0
	v_addc_co_u32_e32 v61, vcc, 0, v23, vcc
	global_load_dwordx4 v[60:63], v[60:61], off nt
	v_add_co_u32_e32 v22, vcc, s8, v22
	s_lshl_b32 s8, s18, 1
	s_nop 0
	v_addc_co_u32_e32 v23, vcc, 0, v23, vcc
	global_load_dwordx4 v[64:67], v[22:23], off nt
	v_add_u32_e32 v22, 0x420, v0
	s_add_u32 s8, s17, s8
	s_addc_u32 s9, s3, 0
	s_waitcnt vmcnt(7)
	ds_write2_b32 v0, v36, v37 offset1:1
	ds_write2_b32 v0, v38, v39 offset0:2 offset1:3
	s_waitcnt vmcnt(6)
	ds_write2_b32 v22, v40, v41 offset1:1
	v_add_u32_e32 v22, 0x428, v0
	ds_write2_b32 v22, v42, v43 offset1:1
	v_add_u32_e32 v22, 0x840, v0
	s_waitcnt vmcnt(5)
	ds_write2_b32 v22, v44, v45 offset1:1
	v_add_u32_e32 v22, 0x848, v0
	ds_write2_b32 v22, v46, v47 offset1:1
	v_add_u32_e32 v22, 0xc60, v0
	v_add_u32_e32 v40, s2, v3
	s_waitcnt vmcnt(4)
	ds_write2_b32 v22, v48, v49 offset1:1
	v_add_u32_e32 v22, 0xc68, v0
	ds_write2_b32 v22, v50, v51 offset1:1
	v_add_u32_e32 v22, 0x1080, v0
	v_ashrrev_i32_e32 v41, 31, v40
	v_lshlrev_b64 v[40:41], 10, v[40:41]
	s_waitcnt vmcnt(3)
	ds_write2_b32 v22, v52, v53 offset1:1
	v_add_u32_e32 v22, 0x1088, v0
	ds_write2_b32 v22, v54, v55 offset1:1
	v_add_u32_e32 v22, 0x14a0, v0
	s_waitcnt vmcnt(2)
	ds_write2_b32 v22, v56, v57 offset1:1
	v_add_u32_e32 v22, 0x14a8, v0
	ds_write2_b32 v22, v58, v59 offset1:1
	v_add_u32_e32 v22, 0x18c0, v0
	s_waitcnt vmcnt(1)
	ds_write2_b32 v22, v60, v61 offset1:1
	v_add_u32_e32 v22, 0x18c8, v0
	ds_write2_b32 v22, v62, v63 offset1:1
	v_add_u32_e32 v22, 0x1ce0, v0
	v_add_u32_e32 v0, 0x1ce8, v0
	s_waitcnt vmcnt(0)
	ds_write2_b32 v22, v64, v65 offset1:1
	ds_write2_b32 v0, v66, v67 offset1:1
	s_waitcnt lgkmcnt(0)
	ds_read2_b32 v[42:43], v28 offset0:33 offset1:41
	ds_read2_b32 v[44:45], v28 offset1:8
	ds_read2_b32 v[46:47], v28 offset0:66 offset1:74
	ds_read2_b32 v[48:49], v28 offset0:99 offset1:107
	ds_read2_b32 v[50:51], v28 offset0:132 offset1:140
	ds_read2_b32 v[52:53], v28 offset0:165 offset1:173
	ds_read2_b32 v[54:55], v28 offset0:198 offset1:206
	ds_read2_b32 v[56:57], v28 offset0:231 offset1:239
	v_lshlrev_b32_e32 v0, 1, v4
	v_lshl_add_u64 v[22:23], s[8:9], 0, v[0:1]
	s_waitcnt lgkmcnt(6)
	v_cvt_pk_bf16_f32 v36, v44, v42
	s_waitcnt lgkmcnt(4)
	v_cvt_pk_bf16_f32 v37, v46, v48
	s_waitcnt lgkmcnt(2)
	v_cvt_pk_bf16_f32 v38, v50, v52
	s_waitcnt lgkmcnt(0)
	v_cvt_pk_bf16_f32 v39, v54, v56
	v_lshl_add_u64 v[40:41], v[22:23], 0, v[40:41]
	global_store_dwordx4 v[40:41], v[36:39], off sc1
	v_add_u32_e32 v40, s2, v24
	v_ashrrev_i32_e32 v41, 31, v40
	v_lshlrev_b64 v[40:41], 10, v[40:41]
	v_cvt_pk_bf16_f32 v36, v45, v43
	v_cvt_pk_bf16_f32 v37, v47, v49
	v_cvt_pk_bf16_f32 v38, v51, v53
	v_cvt_pk_bf16_f32 v39, v55, v57
	v_lshl_add_u64 v[40:41], v[22:23], 0, v[40:41]
	global_store_dwordx4 v[40:41], v[36:39], off sc1
	ds_read2_b32 v[42:43], v28 offset0:49 offset1:57
	ds_read2_b32 v[44:45], v28 offset0:16 offset1:24
	ds_read2_b32 v[46:47], v28 offset0:82 offset1:90
	ds_read2_b32 v[48:49], v28 offset0:115 offset1:123
	ds_read2_b32 v[50:51], v28 offset0:148 offset1:156
	ds_read2_b32 v[52:53], v28 offset0:181 offset1:189
	ds_read2_b32 v[54:55], v28 offset0:214 offset1:222
	ds_read2_b32 v[56:57], v28 offset0:247 offset1:255
	v_add_u32_e32 v40, s2, v25
	v_ashrrev_i32_e32 v41, 31, v40
	v_lshlrev_b64 v[40:41], 10, v[40:41]
	s_waitcnt lgkmcnt(6)
	v_cvt_pk_bf16_f32 v36, v44, v42
	s_waitcnt lgkmcnt(4)
	v_cvt_pk_bf16_f32 v37, v46, v48
	s_waitcnt lgkmcnt(2)
	v_cvt_pk_bf16_f32 v38, v50, v52
	s_waitcnt lgkmcnt(0)
	v_cvt_pk_bf16_f32 v39, v54, v56
	v_lshl_add_u64 v[40:41], v[22:23], 0, v[40:41]
	global_store_dwordx4 v[40:41], v[36:39], off sc1
	v_add_u32_e32 v40, s2, v26
	v_ashrrev_i32_e32 v41, 31, v40
	v_lshlrev_b64 v[40:41], 10, v[40:41]
	v_cvt_pk_bf16_f32 v36, v45, v43
	v_cvt_pk_bf16_f32 v37, v47, v49
	v_cvt_pk_bf16_f32 v38, v51, v53
	v_cvt_pk_bf16_f32 v39, v55, v57
	v_lshl_add_u64 v[22:23], v[22:23], 0, v[40:41]
	global_store_dwordx4 v[22:23], v[36:39], off sc1
	s_waitcnt lgkmcnt(0)
	s_mov_b64 s[2:3], 0
.LBB0_860:
	s_andn2_b64 vcc, exec, s[2:3]
	s_cbranch_vccnz .LBB0_862
	s_load_dwordx2 s[8:9], s[60:61], 0xf8
	s_add_i32 s2, s13, 0xc800
	s_and_b32 s3, s2, 0x1ffc0
	s_and_b32 s2, s15, 0x3e0
	s_lshl_b32 s17, s2, 2
	v_add_u32_e32 v22, s3, v3
	s_waitcnt lgkmcnt(0)
	s_add_u32 s8, s8, s17
	s_addc_u32 s9, s9, 0
	v_lshlrev_b32_e32 v0, 2, v2
	v_ashrrev_i32_e32 v23, 31, v22
	v_lshl_add_u64 v[36:37], s[8:9], 0, v[0:1]
	v_lshlrev_b64 v[22:23], 12, v[22:23]
	v_lshl_add_u64 v[22:23], v[36:37], 0, v[22:23]
	s_mov_b32 s8, 0x8000
	v_add_co_u32_e32 v40, vcc, s8, v22
	s_mov_b32 s8, 0x10000
	s_nop 0
	v_addc_co_u32_e32 v41, vcc, 0, v23, vcc
	global_load_dwordx4 v[36:39], v[22:23], off nt
	v_add_co_u32_e32 v44, vcc, s8, v22
	global_load_dwordx4 v[40:43], v[40:41], off nt
	s_nop 0
	v_addc_co_u32_e32 v45, vcc, 0, v23, vcc
	global_load_dwordx4 v[44:47], v[44:45], off nt
	v_add_co_u32_e32 v48, vcc, s41, v22
	s_mov_b32 s8, 0x30000
	s_nop 0
	v_addc_co_u32_e32 v49, vcc, 0, v23, vcc
	global_load_dwordx4 v[48:51], v[48:49], off nt
	v_add_co_u32_e32 v52, vcc, s82, v22
	v_add_u32_e32 v0, v29, v5
	s_nop 0
	v_addc_co_u32_e32 v53, vcc, 0, v23, vcc
	global_load_dwordx4 v[52:55], v[52:53], off nt
	v_add_co_u32_e32 v56, vcc, s44, v22
	s_lshl_b32 s62, s3, 1
	s_nop 0
	v_addc_co_u32_e32 v57, vcc, 0, v23, vcc
	global_load_dwordx4 v[56:59], v[56:57], off nt
	v_add_co_u32_e32 v60, vcc, s8, v22
	s_mov_b32 s8, 0x38000
	s_nop 0
	v_addc_co_u32_e32 v61, vcc, 0, v23, vcc
	global_load_dwordx4 v[60:63], v[60:61], off nt
	v_add_co_u32_e32 v22, vcc, s8, v22
	s_nop 1
	v_addc_co_u32_e32 v23, vcc, 0, v23, vcc
	global_load_dwordx4 v[64:67], v[22:23], off nt
	v_add_u32_e32 v22, 0x420, v0
	s_waitcnt vmcnt(7)
	ds_write2_b32 v0, v36, v37 offset1:1
	ds_write2_b32 v0, v38, v39 offset0:2 offset1:3
	s_waitcnt vmcnt(6)
	ds_write2_b32 v22, v40, v41 offset1:1
	v_add_u32_e32 v22, 0x428, v0
	ds_write2_b32 v22, v42, v43 offset1:1
	v_add_u32_e32 v22, 0x840, v0
	s_waitcnt vmcnt(5)
	ds_write2_b32 v22, v44, v45 offset1:1
	v_add_u32_e32 v22, 0x848, v0
	ds_write2_b32 v22, v46, v47 offset1:1
	v_add_u32_e32 v22, 0xc60, v0
	v_add_u32_e32 v40, s2, v3
	s_waitcnt vmcnt(4)
	ds_write2_b32 v22, v48, v49 offset1:1
	v_add_u32_e32 v22, 0xc68, v0
	ds_write2_b32 v22, v50, v51 offset1:1
	v_add_u32_e32 v22, 0x1080, v0
	v_ashrrev_i32_e32 v41, 31, v40
	v_lshlrev_b64 v[40:41], 11, v[40:41]
	s_waitcnt vmcnt(3)
	ds_write2_b32 v22, v52, v53 offset1:1
	v_add_u32_e32 v22, 0x1088, v0
	ds_write2_b32 v22, v54, v55 offset1:1
	v_add_u32_e32 v22, 0x14a0, v0
	s_waitcnt vmcnt(2)
	ds_write2_b32 v22, v56, v57 offset1:1
	v_add_u32_e32 v22, 0x14a8, v0
	ds_write2_b32 v22, v58, v59 offset1:1
	v_add_u32_e32 v22, 0x18c0, v0
	s_waitcnt vmcnt(1)
	ds_write2_b32 v22, v60, v61 offset1:1
	v_add_u32_e32 v22, 0x18c8, v0
	ds_write2_b32 v22, v62, v63 offset1:1
	v_add_u32_e32 v22, 0x1ce0, v0
	v_add_u32_e32 v0, 0x1ce8, v0
	s_waitcnt vmcnt(0)
	ds_write2_b32 v22, v64, v65 offset1:1
	ds_write2_b32 v0, v66, v67 offset1:1
	s_waitcnt lgkmcnt(0)
	ds_read2_b32 v[42:43], v28 offset0:33 offset1:41
	ds_read2_b32 v[44:45], v28 offset1:8
	ds_read2_b32 v[46:47], v28 offset0:66 offset1:74
	ds_read2_b32 v[48:49], v28 offset0:99 offset1:107
	ds_read2_b32 v[50:51], v28 offset0:132 offset1:140
	ds_read2_b32 v[52:53], v28 offset0:165 offset1:173
	ds_read2_b32 v[54:55], v28 offset0:198 offset1:206
	ds_read2_b32 v[56:57], v28 offset0:231 offset1:239
	v_lshl_add_u64 v[22:23], v[6:7], 0, s[62:63]
	s_waitcnt lgkmcnt(6)
	v_cvt_pk_bf16_f32 v36, v44, v42
	s_waitcnt lgkmcnt(4)
	v_cvt_pk_bf16_f32 v37, v46, v48
	s_waitcnt lgkmcnt(2)
	v_cvt_pk_bf16_f32 v38, v50, v52
	s_waitcnt lgkmcnt(0)
	v_cvt_pk_bf16_f32 v39, v54, v56
	v_lshl_add_u64 v[40:41], v[22:23], 0, v[40:41]
	global_store_dwordx4 v[40:41], v[36:39], off sc1
	v_add_u32_e32 v40, s2, v24
	v_ashrrev_i32_e32 v41, 31, v40
	v_lshlrev_b64 v[40:41], 11, v[40:41]
	v_cvt_pk_bf16_f32 v36, v45, v43
	v_cvt_pk_bf16_f32 v37, v47, v49
	v_cvt_pk_bf16_f32 v38, v51, v53
	v_cvt_pk_bf16_f32 v39, v55, v57
	v_lshl_add_u64 v[40:41], v[22:23], 0, v[40:41]
	global_store_dwordx4 v[40:41], v[36:39], off sc1
	ds_read2_b32 v[42:43], v28 offset0:49 offset1:57
	ds_read2_b32 v[44:45], v28 offset0:16 offset1:24
	ds_read2_b32 v[46:47], v28 offset0:82 offset1:90
	ds_read2_b32 v[48:49], v28 offset0:115 offset1:123
	ds_read2_b32 v[50:51], v28 offset0:148 offset1:156
	ds_read2_b32 v[52:53], v28 offset0:181 offset1:189
	ds_read2_b32 v[54:55], v28 offset0:214 offset1:222
	ds_read2_b32 v[56:57], v28 offset0:247 offset1:255
	v_add_u32_e32 v40, s2, v25
	v_ashrrev_i32_e32 v41, 31, v40
	v_lshlrev_b64 v[40:41], 11, v[40:41]
	s_waitcnt lgkmcnt(6)
	v_cvt_pk_bf16_f32 v36, v44, v42
	s_waitcnt lgkmcnt(4)
	v_cvt_pk_bf16_f32 v37, v46, v48
	s_waitcnt lgkmcnt(2)
	v_cvt_pk_bf16_f32 v38, v50, v52
	s_waitcnt lgkmcnt(0)
	v_cvt_pk_bf16_f32 v39, v54, v56
	v_lshl_add_u64 v[40:41], v[22:23], 0, v[40:41]
	global_store_dwordx4 v[40:41], v[36:39], off sc1
	v_add_u32_e32 v40, s2, v26
	v_ashrrev_i32_e32 v41, 31, v40
	v_lshlrev_b64 v[40:41], 11, v[40:41]
	v_cvt_pk_bf16_f32 v36, v45, v43
	v_cvt_pk_bf16_f32 v37, v47, v49
	v_cvt_pk_bf16_f32 v38, v51, v53
	v_cvt_pk_bf16_f32 v39, v55, v57
	v_lshl_add_u64 v[22:23], v[22:23], 0, v[40:41]
	global_store_dwordx4 v[22:23], v[36:39], off sc1
	s_waitcnt lgkmcnt(0)

.LBB0_863:
	s_andn2_b64 vcc, exec, s[2:3]
	s_cbranch_vccnz .LBB0_865
	s_add_i32 s2, s1, 0x6a00
	s_and_b32 s3, s2, 0xffff
	s_mul_i32 s3, s3, 0xaaab
	s_lshr_b32 s17, s3, 16
	s_lshr_b32 s3, s3, 22
	s_load_dwordx2 s[8:9], s[60:61], 0xf0
	s_mulk_i32 s3, 0x60
	s_sub_i32 s2, s2, s3
	s_lshl_b32 s2, s2, 5
	s_and_b32 s2, s2, 0xffe0
	s_and_b32 s3, s17, 0xffc0
	s_lshl_b32 s17, s2, 2
	s_waitcnt lgkmcnt(0)
	s_add_u32 s8, s8, s17
	v_add_u32_e32 v35, s3, v3
	s_addc_u32 s9, s9, 0
	v_lshlrev_b32_e32 v0, 2, v2
	v_lshl_add_u64 v[22:23], s[8:9], 0, v[0:1]
	v_add_u32_e32 v0, 8, v35
	v_mad_i64_i32 v[36:37], s[8:9], v35, s40, v[22:23]
	v_mad_i64_i32 v[40:41], s[8:9], v0, s40, v[22:23]
	global_load_dwordx4 v[36:39], v[36:37], off nt
	v_add_u32_e32 v0, 16, v35
	global_load_dwordx4 v[40:43], v[40:41], off nt
	v_mad_i64_i32 v[44:45], s[8:9], v0, s40, v[22:23]
	global_load_dwordx4 v[44:47], v[44:45], off nt
	v_add_u32_e32 v0, 24, v35
	v_mad_i64_i32 v[48:49], s[8:9], v0, s40, v[22:23]
	global_load_dwordx4 v[48:51], v[48:49], off nt
	v_add_u32_e32 v0, 32, v35
	v_mad_i64_i32 v[52:53], s[8:9], v0, s40, v[22:23]
	global_load_dwordx4 v[52:55], v[52:53], off nt
	v_add_u32_e32 v0, 40, v35
	v_mad_i64_i32 v[56:57], s[8:9], v0, s40, v[22:23]
	global_load_dwordx4 v[56:59], v[56:57], off nt
	v_add_u32_e32 v0, 48, v35
	v_mad_i64_i32 v[60:61], s[8:9], v0, s40, v[22:23]
	global_load_dwordx4 v[60:63], v[60:61], off nt
	v_add_u32_e32 v0, 56, v35
	v_mad_i64_i32 v[22:23], s[8:9], v0, s40, v[22:23]
	global_load_dwordx4 v[64:67], v[22:23], off nt
	v_add_u32_e32 v0, v29, v5
	v_add_u32_e32 v22, 0x420, v0
	s_lshl_b32 s62, s3, 1
	s_waitcnt vmcnt(7)
	ds_write2_b32 v0, v36, v37 offset1:1
	ds_write2_b32 v0, v38, v39 offset0:2 offset1:3
	s_waitcnt vmcnt(6)
	ds_write2_b32 v22, v40, v41 offset1:1
	v_add_u32_e32 v22, 0x428, v0
	ds_write2_b32 v22, v42, v43 offset1:1
	v_add_u32_e32 v22, 0x840, v0
	s_waitcnt vmcnt(5)
	ds_write2_b32 v22, v44, v45 offset1:1
	v_add_u32_e32 v22, 0x848, v0
	ds_write2_b32 v22, v46, v47 offset1:1
	v_add_u32_e32 v22, 0xc60, v0
	s_waitcnt vmcnt(4)
	ds_write2_b32 v22, v48, v49 offset1:1
	v_add_u32_e32 v22, 0xc68, v0
	ds_write2_b32 v22, v50, v51 offset1:1
	v_add_u32_e32 v22, 0x1080, v0
	s_waitcnt vmcnt(3)
	ds_write2_b32 v22, v52, v53 offset1:1
	v_add_u32_e32 v22, 0x1088, v0
	ds_write2_b32 v22, v54, v55 offset1:1
	v_add_u32_e32 v22, 0x14a0, v0
	s_waitcnt vmcnt(2)
	ds_write2_b32 v22, v56, v57 offset1:1
	v_add_u32_e32 v22, 0x14a8, v0
	ds_write2_b32 v22, v58, v59 offset1:1
	v_add_u32_e32 v22, 0x18c0, v0
	s_waitcnt vmcnt(1)
	ds_write2_b32 v22, v60, v61 offset1:1
	v_add_u32_e32 v22, 0x18c8, v0
	ds_write2_b32 v22, v62, v63 offset1:1
	v_add_u32_e32 v22, 0x1ce0, v0
	v_add_u32_e32 v0, 0x1ce8, v0
	s_waitcnt vmcnt(0)
	ds_write2_b32 v22, v64, v65 offset1:1
	ds_write2_b32 v0, v66, v67 offset1:1
	s_waitcnt lgkmcnt(0)
	ds_read2_b32 v[42:43], v28 offset0:33 offset1:41
	ds_read2_b32 v[44:45], v28 offset1:8
	ds_read2_b32 v[46:47], v28 offset0:66 offset1:74
	ds_read2_b32 v[48:49], v28 offset0:99 offset1:107
	ds_read2_b32 v[50:51], v28 offset0:132 offset1:140
	ds_read2_b32 v[52:53], v28 offset0:165 offset1:173
	ds_read2_b32 v[54:55], v28 offset0:198 offset1:206
	ds_read2_b32 v[56:57], v28 offset0:231 offset1:239
	v_add_u32_e32 v40, s2, v3
	v_ashrrev_i32_e32 v41, 31, v40
	v_lshl_add_u64 v[22:23], v[8:9], 0, s[62:63]
	v_lshlrev_b64 v[40:41], 11, v[40:41]
	s_waitcnt lgkmcnt(6)
	v_cvt_pk_bf16_f32 v36, v44, v42
	s_waitcnt lgkmcnt(4)
	v_cvt_pk_bf16_f32 v37, v46, v48
	s_waitcnt lgkmcnt(2)
	v_cvt_pk_bf16_f32 v38, v50, v52
	s_waitcnt lgkmcnt(0)
	v_cvt_pk_bf16_f32 v39, v54, v56
	v_lshl_add_u64 v[40:41], v[22:23], 0, v[40:41]
	global_store_dwordx4 v[40:41], v[36:39], off sc1
	v_add_u32_e32 v40, s2, v24
	v_ashrrev_i32_e32 v41, 31, v40
	v_lshlrev_b64 v[40:41], 11, v[40:41]
	v_cvt_pk_bf16_f32 v36, v45, v43
	v_cvt_pk_bf16_f32 v37, v47, v49
	v_cvt_pk_bf16_f32 v38, v51, v53
	v_cvt_pk_bf16_f32 v39, v55, v57
	v_lshl_add_u64 v[40:41], v[22:23], 0, v[40:41]
	global_store_dwordx4 v[40:41], v[36:39], off sc1
	ds_read2_b32 v[42:43], v28 offset0:49 offset1:57
	ds_read2_b32 v[44:45], v28 offset0:16 offset1:24
	ds_read2_b32 v[46:47], v28 offset0:82 offset1:90
	ds_read2_b32 v[48:49], v28 offset0:115 offset1:123
	ds_read2_b32 v[50:51], v28 offset0:148 offset1:156
	ds_read2_b32 v[52:53], v28 offset0:181 offset1:189
	ds_read2_b32 v[54:55], v28 offset0:214 offset1:222
	ds_read2_b32 v[56:57], v28 offset0:247 offset1:255
	v_add_u32_e32 v40, s2, v25
	v_ashrrev_i32_e32 v41, 31, v40
	v_lshlrev_b64 v[40:41], 11, v[40:41]
	s_waitcnt lgkmcnt(6)
	v_cvt_pk_bf16_f32 v36, v44, v42
	s_waitcnt lgkmcnt(4)
	v_cvt_pk_bf16_f32 v37, v46, v48
	s_waitcnt lgkmcnt(2)
	v_cvt_pk_bf16_f32 v38, v50, v52
	s_waitcnt lgkmcnt(0)
	v_cvt_pk_bf16_f32 v39, v54, v56
	v_lshl_add_u64 v[40:41], v[22:23], 0, v[40:41]
	global_store_dwordx4 v[40:41], v[36:39], off sc1
	v_add_u32_e32 v40, s2, v26
	v_ashrrev_i32_e32 v41, 31, v40
	v_lshlrev_b64 v[40:41], 11, v[40:41]
	v_cvt_pk_bf16_f32 v36, v45, v43
	v_cvt_pk_bf16_f32 v37, v47, v49
	v_cvt_pk_bf16_f32 v38, v51, v53
	v_cvt_pk_bf16_f32 v39, v55, v57
	v_lshl_add_u64 v[22:23], v[22:23], 0, v[40:41]
	global_store_dwordx4 v[22:23], v[36:39], off sc1
	s_waitcnt lgkmcnt(0)

.LBB0_866:
	s_andn2_b64 vcc, exec, s[2:3]
	s_cbranch_vccnz .LBB0_868
	s_load_dwordx2 s[8:9], s[60:61], 0xe8
	s_add_i32 s2, s13, 0xd800
	s_and_b32 s3, s2, 0x1ffc0
	s_and_b32 s2, s15, 0x3e0
	s_lshl_b32 s17, s2, 2
	v_add_u32_e32 v22, s3, v3
	s_waitcnt lgkmcnt(0)
	s_add_u32 s8, s8, s17
	s_addc_u32 s9, s9, 0
	v_lshlrev_b32_e32 v0, 2, v2
	v_ashrrev_i32_e32 v23, 31, v22
	v_lshl_add_u64 v[36:37], s[8:9], 0, v[0:1]
	v_lshlrev_b64 v[22:23], 12, v[22:23]
	v_lshl_add_u64 v[22:23], v[36:37], 0, v[22:23]
	s_mov_b32 s8, 0x8000
	v_add_co_u32_e32 v40, vcc, s8, v22
	s_mov_b32 s8, 0x10000
	s_nop 0
	v_addc_co_u32_e32 v41, vcc, 0, v23, vcc
	global_load_dwordx4 v[36:39], v[22:23], off nt
	v_add_co_u32_e32 v44, vcc, s8, v22
	global_load_dwordx4 v[40:43], v[40:41], off nt
	s_nop 0
	v_addc_co_u32_e32 v45, vcc, 0, v23, vcc
	global_load_dwordx4 v[44:47], v[44:45], off nt
	v_add_co_u32_e32 v48, vcc, s41, v22
	s_mov_b32 s8, 0x30000
	s_nop 0
	v_addc_co_u32_e32 v49, vcc, 0, v23, vcc
	global_load_dwordx4 v[48:51], v[48:49], off nt
	v_add_co_u32_e32 v52, vcc, s82, v22
	v_add_u32_e32 v0, v29, v5
	s_nop 0
	v_addc_co_u32_e32 v53, vcc, 0, v23, vcc
	global_load_dwordx4 v[52:55], v[52:53], off nt
	v_add_co_u32_e32 v56, vcc, s44, v22
	s_lshl_b32 s62, s3, 1
	s_nop 0
	v_addc_co_u32_e32 v57, vcc, 0, v23, vcc
	global_load_dwordx4 v[56:59], v[56:57], off nt
	v_add_co_u32_e32 v60, vcc, s8, v22
	s_mov_b32 s8, 0x38000
	s_nop 0
	v_addc_co_u32_e32 v61, vcc, 0, v23, vcc
	global_load_dwordx4 v[60:63], v[60:61], off nt
	v_add_co_u32_e32 v22, vcc, s8, v22
	s_nop 1
	v_addc_co_u32_e32 v23, vcc, 0, v23, vcc
	global_load_dwordx4 v[64:67], v[22:23], off nt
	v_add_u32_e32 v22, 0x420, v0
	s_waitcnt vmcnt(7)
	ds_write2_b32 v0, v36, v37 offset1:1
	ds_write2_b32 v0, v38, v39 offset0:2 offset1:3
	s_waitcnt vmcnt(6)
	ds_write2_b32 v22, v40, v41 offset1:1
	v_add_u32_e32 v22, 0x428, v0
	ds_write2_b32 v22, v42, v43 offset1:1
	v_add_u32_e32 v22, 0x840, v0
	s_waitcnt vmcnt(5)
	ds_write2_b32 v22, v44, v45 offset1:1
	v_add_u32_e32 v22, 0x848, v0
	ds_write2_b32 v22, v46, v47 offset1:1
	v_add_u32_e32 v22, 0xc60, v0
	v_add_u32_e32 v40, s2, v3
	s_waitcnt vmcnt(4)
	ds_write2_b32 v22, v48, v49 offset1:1
	v_add_u32_e32 v22, 0xc68, v0
	ds_write2_b32 v22, v50, v51 offset1:1
	v_add_u32_e32 v22, 0x1080, v0
	v_ashrrev_i32_e32 v41, 31, v40
	v_lshlrev_b64 v[40:41], 11, v[40:41]
	s_waitcnt vmcnt(3)
	ds_write2_b32 v22, v52, v53 offset1:1
	v_add_u32_e32 v22, 0x1088, v0
	ds_write2_b32 v22, v54, v55 offset1:1
	v_add_u32_e32 v22, 0x14a0, v0
	s_waitcnt vmcnt(2)
	ds_write2_b32 v22, v56, v57 offset1:1
	v_add_u32_e32 v22, 0x14a8, v0
	ds_write2_b32 v22, v58, v59 offset1:1
	v_add_u32_e32 v22, 0x18c0, v0
	s_waitcnt vmcnt(1)
	ds_write2_b32 v22, v60, v61 offset1:1
	v_add_u32_e32 v22, 0x18c8, v0
	ds_write2_b32 v22, v62, v63 offset1:1
	v_add_u32_e32 v22, 0x1ce0, v0
	v_add_u32_e32 v0, 0x1ce8, v0
	s_waitcnt vmcnt(0)
	ds_write2_b32 v22, v64, v65 offset1:1
	ds_write2_b32 v0, v66, v67 offset1:1
	s_waitcnt lgkmcnt(0)
	ds_read2_b32 v[42:43], v28 offset0:33 offset1:41
	ds_read2_b32 v[44:45], v28 offset1:8
	ds_read2_b32 v[46:47], v28 offset0:66 offset1:74
	ds_read2_b32 v[48:49], v28 offset0:99 offset1:107
	ds_read2_b32 v[50:51], v28 offset0:132 offset1:140
	ds_read2_b32 v[52:53], v28 offset0:165 offset1:173
	ds_read2_b32 v[54:55], v28 offset0:198 offset1:206
	ds_read2_b32 v[56:57], v28 offset0:231 offset1:239
	v_lshl_add_u64 v[22:23], v[10:11], 0, s[62:63]
	s_waitcnt lgkmcnt(6)
	v_cvt_pk_bf16_f32 v36, v44, v42
	s_waitcnt lgkmcnt(4)
	v_cvt_pk_bf16_f32 v37, v46, v48
	s_waitcnt lgkmcnt(2)
	v_cvt_pk_bf16_f32 v38, v50, v52
	s_waitcnt lgkmcnt(0)
	v_cvt_pk_bf16_f32 v39, v54, v56
	v_lshl_add_u64 v[40:41], v[22:23], 0, v[40:41]
	global_store_dwordx4 v[40:41], v[36:39], off sc1
	v_add_u32_e32 v40, s2, v24
	v_ashrrev_i32_e32 v41, 31, v40
	v_lshlrev_b64 v[40:41], 11, v[40:41]
	v_cvt_pk_bf16_f32 v36, v45, v43
	v_cvt_pk_bf16_f32 v37, v47, v49
	v_cvt_pk_bf16_f32 v38, v51, v53
	v_cvt_pk_bf16_f32 v39, v55, v57
	v_lshl_add_u64 v[40:41], v[22:23], 0, v[40:41]
	global_store_dwordx4 v[40:41], v[36:39], off sc1
	ds_read2_b32 v[42:43], v28 offset0:49 offset1:57
	ds_read2_b32 v[44:45], v28 offset0:16 offset1:24
	ds_read2_b32 v[46:47], v28 offset0:82 offset1:90
	ds_read2_b32 v[48:49], v28 offset0:115 offset1:123
	ds_read2_b32 v[50:51], v28 offset0:148 offset1:156
	ds_read2_b32 v[52:53], v28 offset0:181 offset1:189
	ds_read2_b32 v[54:55], v28 offset0:214 offset1:222
	ds_read2_b32 v[56:57], v28 offset0:247 offset1:255
	v_add_u32_e32 v40, s2, v25
	v_ashrrev_i32_e32 v41, 31, v40
	v_lshlrev_b64 v[40:41], 11, v[40:41]
	s_waitcnt lgkmcnt(6)
	v_cvt_pk_bf16_f32 v36, v44, v42
	s_waitcnt lgkmcnt(4)
	v_cvt_pk_bf16_f32 v37, v46, v48
	s_waitcnt lgkmcnt(2)
	v_cvt_pk_bf16_f32 v38, v50, v52
	s_waitcnt lgkmcnt(0)
	v_cvt_pk_bf16_f32 v39, v54, v56
	v_lshl_add_u64 v[40:41], v[22:23], 0, v[40:41]
	global_store_dwordx4 v[40:41], v[36:39], off sc1
	v_add_u32_e32 v40, s2, v26
	v_ashrrev_i32_e32 v41, 31, v40
	v_lshlrev_b64 v[40:41], 11, v[40:41]
	v_cvt_pk_bf16_f32 v36, v45, v43
	v_cvt_pk_bf16_f32 v37, v47, v49
	v_cvt_pk_bf16_f32 v38, v51, v53
	v_cvt_pk_bf16_f32 v39, v55, v57
	v_lshl_add_u64 v[22:23], v[22:23], 0, v[40:41]
	global_store_dwordx4 v[22:23], v[36:39], off sc1
	s_waitcnt lgkmcnt(0)

.LBB0_869:
	s_andn2_b64 vcc, exec, s[2:3]
	s_cbranch_vccnz .LBB0_871
	s_load_dwordx2 s[8:9], s[60:61], 0xc0
	s_add_i32 s2, s1, 0x7000
	s_and_b32 s3, s2, 0xffc0
	s_and_b32 s2, s15, 0x7e0
	s_lshl_b32 s17, s2, 2
	v_add_u32_e32 v22, s3, v3
	s_waitcnt lgkmcnt(0)
	s_add_u32 s8, s8, s17
	s_addc_u32 s9, s9, 0
	v_lshlrev_b32_e32 v0, 2, v2
	v_ashrrev_i32_e32 v23, 31, v22
	v_lshl_add_u64 v[36:37], s[8:9], 0, v[0:1]
	v_lshlrev_b64 v[22:23], 13, v[22:23]
	v_lshl_add_u64 v[22:23], v[36:37], 0, v[22:23]
	s_mov_b32 s8, 0x10000
	v_add_co_u32_e32 v40, vcc, s8, v22
	global_load_dwordx4 v[36:39], v[22:23], off nt
	s_nop 0
	v_addc_co_u32_e32 v41, vcc, 0, v23, vcc
	global_load_dwordx4 v[40:43], v[40:41], off nt
	v_add_co_u32_e32 v44, vcc, s82, v22
	s_mov_b32 s8, 0x30000
	s_nop 0
	v_addc_co_u32_e32 v45, vcc, 0, v23, vcc
	global_load_dwordx4 v[44:47], v[44:45], off nt
	v_add_co_u32_e32 v48, vcc, s8, v22
	s_mov_b32 s8, 0x50000
	s_nop 0
	v_addc_co_u32_e32 v49, vcc, 0, v23, vcc
	global_load_dwordx4 v[48:51], v[48:49], off nt
	v_add_co_u32_e32 v52, vcc, s83, v22
	v_add_u32_e32 v0, v29, v5
	s_nop 0
	v_addc_co_u32_e32 v53, vcc, 0, v23, vcc
	global_load_dwordx4 v[52:55], v[52:53], off nt
	v_add_co_u32_e32 v56, vcc, s8, v22
	s_mov_b32 s8, 0x70000
	s_nop 0
	v_addc_co_u32_e32 v57, vcc, 0, v23, vcc
	global_load_dwordx4 v[56:59], v[56:57], off nt
	v_add_co_u32_e32 v60, vcc, s88, v22
	s_lshl_b32 s62, s3, 1
	s_nop 0
	v_addc_co_u32_e32 v61, vcc, 0, v23, vcc
	global_load_dwordx4 v[60:63], v[60:61], off nt
	v_add_co_u32_e32 v22, vcc, s8, v22
	s_nop 1
	v_addc_co_u32_e32 v23, vcc, 0, v23, vcc
	global_load_dwordx4 v[64:67], v[22:23], off nt
	v_add_u32_e32 v22, 0x420, v0
	s_waitcnt vmcnt(7)
	ds_write2_b32 v0, v36, v37 offset1:1
	ds_write2_b32 v0, v38, v39 offset0:2 offset1:3
	s_waitcnt vmcnt(6)
	ds_write2_b32 v22, v40, v41 offset1:1
	v_add_u32_e32 v22, 0x428, v0
	ds_write2_b32 v22, v42, v43 offset1:1
	v_add_u32_e32 v22, 0x840, v0
	v_add_u32_e32 v40, s2, v3
	v_ashrrev_i32_e32 v41, 31, v40
	s_waitcnt vmcnt(5)
	ds_write2_b32 v22, v44, v45 offset1:1
	v_add_u32_e32 v22, 0x848, v0
	ds_write2_b32 v22, v46, v47 offset1:1
	v_add_u32_e32 v22, 0xc60, v0
	v_lshlrev_b64 v[40:41], 11, v[40:41]
	s_waitcnt vmcnt(4)
	ds_write2_b32 v22, v48, v49 offset1:1
	v_add_u32_e32 v22, 0xc68, v0
	ds_write2_b32 v22, v50, v51 offset1:1
	v_add_u32_e32 v22, 0x1080, v0
	s_waitcnt vmcnt(3)
	ds_write2_b32 v22, v52, v53 offset1:1
	v_add_u32_e32 v22, 0x1088, v0
	ds_write2_b32 v22, v54, v55 offset1:1
	v_add_u32_e32 v22, 0x14a0, v0
	s_waitcnt vmcnt(2)
	ds_write2_b32 v22, v56, v57 offset1:1
	v_add_u32_e32 v22, 0x14a8, v0
	ds_write2_b32 v22, v58, v59 offset1:1
	v_add_u32_e32 v22, 0x18c0, v0
	s_waitcnt vmcnt(1)
	ds_write2_b32 v22, v60, v61 offset1:1
	v_add_u32_e32 v22, 0x18c8, v0
	ds_write2_b32 v22, v62, v63 offset1:1
	v_add_u32_e32 v22, 0x1ce0, v0
	v_add_u32_e32 v0, 0x1ce8, v0
	s_waitcnt vmcnt(0)
	ds_write2_b32 v22, v64, v65 offset1:1
	ds_write2_b32 v0, v66, v67 offset1:1
	s_waitcnt lgkmcnt(0)
	ds_read2_b32 v[42:43], v28 offset0:33 offset1:41
	ds_read2_b32 v[44:45], v28 offset1:8
	ds_read2_b32 v[46:47], v28 offset0:66 offset1:74
	ds_read2_b32 v[48:49], v28 offset0:99 offset1:107
	ds_read2_b32 v[50:51], v28 offset0:132 offset1:140
	ds_read2_b32 v[52:53], v28 offset0:165 offset1:173
	ds_read2_b32 v[54:55], v28 offset0:198 offset1:206
	ds_read2_b32 v[56:57], v28 offset0:231 offset1:239
	v_lshl_add_u64 v[22:23], v[12:13], 0, s[62:63]
	s_waitcnt lgkmcnt(6)
	v_cvt_pk_bf16_f32 v36, v44, v42
	s_waitcnt lgkmcnt(4)
	v_cvt_pk_bf16_f32 v37, v46, v48
	s_waitcnt lgkmcnt(2)
	v_cvt_pk_bf16_f32 v38, v50, v52
	s_waitcnt lgkmcnt(0)
	v_cvt_pk_bf16_f32 v39, v54, v56
	v_lshl_add_u64 v[40:41], v[22:23], 0, v[40:41]
	global_store_dwordx4 v[40:41], v[36:39], off sc1
	v_add_u32_e32 v40, s2, v24
	v_ashrrev_i32_e32 v41, 31, v40
	v_lshlrev_b64 v[40:41], 11, v[40:41]
	v_cvt_pk_bf16_f32 v36, v45, v43
	v_cvt_pk_bf16_f32 v37, v47, v49
	v_cvt_pk_bf16_f32 v38, v51, v53
	v_cvt_pk_bf16_f32 v39, v55, v57
	v_lshl_add_u64 v[40:41], v[22:23], 0, v[40:41]
	global_store_dwordx4 v[40:41], v[36:39], off sc1
	ds_read2_b32 v[42:43], v28 offset0:49 offset1:57
	ds_read2_b32 v[44:45], v28 offset0:16 offset1:24
	ds_read2_b32 v[46:47], v28 offset0:82 offset1:90
	ds_read2_b32 v[48:49], v28 offset0:115 offset1:123
	ds_read2_b32 v[50:51], v28 offset0:148 offset1:156
	ds_read2_b32 v[52:53], v28 offset0:181 offset1:189
	ds_read2_b32 v[54:55], v28 offset0:214 offset1:222
	ds_read2_b32 v[56:57], v28 offset0:247 offset1:255
	v_add_u32_e32 v40, s2, v25
	v_ashrrev_i32_e32 v41, 31, v40
	v_lshlrev_b64 v[40:41], 11, v[40:41]
	s_waitcnt lgkmcnt(6)
	v_cvt_pk_bf16_f32 v36, v44, v42
	s_waitcnt lgkmcnt(4)
	v_cvt_pk_bf16_f32 v37, v46, v48
	s_waitcnt lgkmcnt(2)
	v_cvt_pk_bf16_f32 v38, v50, v52
	s_waitcnt lgkmcnt(0)
	v_cvt_pk_bf16_f32 v39, v54, v56
	v_lshl_add_u64 v[40:41], v[22:23], 0, v[40:41]
	global_store_dwordx4 v[40:41], v[36:39], off sc1
	v_add_u32_e32 v40, s2, v26
	v_ashrrev_i32_e32 v41, 31, v40
	v_lshlrev_b64 v[40:41], 11, v[40:41]
	v_cvt_pk_bf16_f32 v36, v45, v43
	v_cvt_pk_bf16_f32 v37, v47, v49
	v_cvt_pk_bf16_f32 v38, v51, v53
	v_cvt_pk_bf16_f32 v39, v55, v57
	v_lshl_add_u64 v[22:23], v[22:23], 0, v[40:41]
	global_store_dwordx4 v[22:23], v[36:39], off sc1
	s_waitcnt lgkmcnt(0)

.LBB0_872:
	s_andn2_b64 vcc, exec, s[2:3]
	s_cbranch_vccnz .LBB0_874
	s_load_dwordx2 s[8:9], s[60:61], 0xb0
	s_add_i32 s2, s13, 0xe400
	s_and_b32 s3, s2, 0x1ffc0
	s_and_b32 s2, s15, 0x3e0
	s_lshl_b32 s17, s2, 2
	v_add_u32_e32 v22, s3, v3
	s_waitcnt lgkmcnt(0)
	s_add_u32 s8, s8, s17
	s_addc_u32 s9, s9, 0
	v_lshlrev_b32_e32 v0, 2, v2
	v_ashrrev_i32_e32 v23, 31, v22
	v_lshl_add_u64 v[36:37], s[8:9], 0, v[0:1]
	v_lshlrev_b64 v[22:23], 12, v[22:23]
	v_lshl_add_u64 v[22:23], v[36:37], 0, v[22:23]
	s_mov_b32 s8, 0x8000
	v_add_co_u32_e32 v40, vcc, s8, v22
	s_mov_b32 s8, 0x10000
	s_nop 0
	v_addc_co_u32_e32 v41, vcc, 0, v23, vcc
	global_load_dwordx4 v[36:39], v[22:23], off nt
	v_add_co_u32_e32 v44, vcc, s8, v22
	global_load_dwordx4 v[40:43], v[40:41], off nt
	s_nop 0
	v_addc_co_u32_e32 v45, vcc, 0, v23, vcc
	global_load_dwordx4 v[44:47], v[44:45], off nt
	v_add_co_u32_e32 v48, vcc, s41, v22
	s_mov_b32 s8, 0x30000
	s_nop 0
	v_addc_co_u32_e32 v49, vcc, 0, v23, vcc
	global_load_dwordx4 v[48:51], v[48:49], off nt
	v_add_co_u32_e32 v52, vcc, s82, v22
	v_add_u32_e32 v0, v29, v5
	s_nop 0
	v_addc_co_u32_e32 v53, vcc, 0, v23, vcc
	global_load_dwordx4 v[52:55], v[52:53], off nt
	v_add_co_u32_e32 v56, vcc, s44, v22
	s_lshl_b32 s62, s3, 1
	s_nop 0
	v_addc_co_u32_e32 v57, vcc, 0, v23, vcc
	global_load_dwordx4 v[56:59], v[56:57], off nt
	v_add_co_u32_e32 v60, vcc, s8, v22
	s_mov_b32 s8, 0x38000
	s_nop 0
	v_addc_co_u32_e32 v61, vcc, 0, v23, vcc
	global_load_dwordx4 v[60:63], v[60:61], off nt
	v_add_co_u32_e32 v22, vcc, s8, v22
	s_nop 1
	v_addc_co_u32_e32 v23, vcc, 0, v23, vcc
	global_load_dwordx4 v[64:67], v[22:23], off nt
	v_add_u32_e32 v22, 0x420, v0
	s_waitcnt vmcnt(7)
	ds_write2_b32 v0, v36, v37 offset1:1
	ds_write2_b32 v0, v38, v39 offset0:2 offset1:3
	s_waitcnt vmcnt(6)
	ds_write2_b32 v22, v40, v41 offset1:1
	v_add_u32_e32 v22, 0x428, v0
	ds_write2_b32 v22, v42, v43 offset1:1
	v_add_u32_e32 v22, 0x840, v0
	s_waitcnt vmcnt(5)
	ds_write2_b32 v22, v44, v45 offset1:1
	v_add_u32_e32 v22, 0x848, v0
	ds_write2_b32 v22, v46, v47 offset1:1
	v_add_u32_e32 v22, 0xc60, v0
	v_add_u32_e32 v40, s2, v3
	s_waitcnt vmcnt(4)
	ds_write2_b32 v22, v48, v49 offset1:1
	v_add_u32_e32 v22, 0xc68, v0
	ds_write2_b32 v22, v50, v51 offset1:1
	v_add_u32_e32 v22, 0x1080, v0
	v_ashrrev_i32_e32 v41, 31, v40
	v_lshlrev_b64 v[40:41], 11, v[40:41]
	s_waitcnt vmcnt(3)
	ds_write2_b32 v22, v52, v53 offset1:1
	v_add_u32_e32 v22, 0x1088, v0
	ds_write2_b32 v22, v54, v55 offset1:1
	v_add_u32_e32 v22, 0x14a0, v0
	s_waitcnt vmcnt(2)
	ds_write2_b32 v22, v56, v57 offset1:1
	v_add_u32_e32 v22, 0x14a8, v0
	ds_write2_b32 v22, v58, v59 offset1:1
	v_add_u32_e32 v22, 0x18c0, v0
	s_waitcnt vmcnt(1)
	ds_write2_b32 v22, v60, v61 offset1:1
	v_add_u32_e32 v22, 0x18c8, v0
	ds_write2_b32 v22, v62, v63 offset1:1
	v_add_u32_e32 v22, 0x1ce0, v0
	v_add_u32_e32 v0, 0x1ce8, v0
	s_waitcnt vmcnt(0)
	ds_write2_b32 v22, v64, v65 offset1:1
	ds_write2_b32 v0, v66, v67 offset1:1
	s_waitcnt lgkmcnt(0)
	ds_read2_b32 v[42:43], v28 offset0:33 offset1:41
	ds_read2_b32 v[44:45], v28 offset1:8
	ds_read2_b32 v[46:47], v28 offset0:66 offset1:74
	ds_read2_b32 v[48:49], v28 offset0:99 offset1:107
	ds_read2_b32 v[50:51], v28 offset0:132 offset1:140
	ds_read2_b32 v[52:53], v28 offset0:165 offset1:173
	ds_read2_b32 v[54:55], v28 offset0:198 offset1:206
	ds_read2_b32 v[56:57], v28 offset0:231 offset1:239
	v_lshl_add_u64 v[22:23], v[14:15], 0, s[62:63]
	s_waitcnt lgkmcnt(6)
	v_cvt_pk_bf16_f32 v36, v44, v42
	s_waitcnt lgkmcnt(4)
	v_cvt_pk_bf16_f32 v37, v46, v48
	s_waitcnt lgkmcnt(2)
	v_cvt_pk_bf16_f32 v38, v50, v52
	s_waitcnt lgkmcnt(0)
	v_cvt_pk_bf16_f32 v39, v54, v56
	v_lshl_add_u64 v[40:41], v[22:23], 0, v[40:41]
	global_store_dwordx4 v[40:41], v[36:39], off sc1
	v_add_u32_e32 v40, s2, v24
	v_ashrrev_i32_e32 v41, 31, v40
	v_lshlrev_b64 v[40:41], 11, v[40:41]
	v_cvt_pk_bf16_f32 v36, v45, v43
	v_cvt_pk_bf16_f32 v37, v47, v49
	v_cvt_pk_bf16_f32 v38, v51, v53
	v_cvt_pk_bf16_f32 v39, v55, v57
	v_lshl_add_u64 v[40:41], v[22:23], 0, v[40:41]
	global_store_dwordx4 v[40:41], v[36:39], off sc1
	ds_read2_b32 v[42:43], v28 offset0:49 offset1:57
	ds_read2_b32 v[44:45], v28 offset0:16 offset1:24
	ds_read2_b32 v[46:47], v28 offset0:82 offset1:90
	ds_read2_b32 v[48:49], v28 offset0:115 offset1:123
	ds_read2_b32 v[50:51], v28 offset0:148 offset1:156
	ds_read2_b32 v[52:53], v28 offset0:181 offset1:189
	ds_read2_b32 v[54:55], v28 offset0:214 offset1:222
	ds_read2_b32 v[56:57], v28 offset0:247 offset1:255
	v_add_u32_e32 v40, s2, v25
	v_ashrrev_i32_e32 v41, 31, v40
	v_lshlrev_b64 v[40:41], 11, v[40:41]
	s_waitcnt lgkmcnt(6)
	v_cvt_pk_bf16_f32 v36, v44, v42
	s_waitcnt lgkmcnt(4)
	v_cvt_pk_bf16_f32 v37, v46, v48
	s_waitcnt lgkmcnt(2)
	v_cvt_pk_bf16_f32 v38, v50, v52
	s_waitcnt lgkmcnt(0)
	v_cvt_pk_bf16_f32 v39, v54, v56
	v_lshl_add_u64 v[40:41], v[22:23], 0, v[40:41]
	global_store_dwordx4 v[40:41], v[36:39], off sc1
	v_add_u32_e32 v40, s2, v26
	v_ashrrev_i32_e32 v41, 31, v40
	v_lshlrev_b64 v[40:41], 11, v[40:41]
	v_cvt_pk_bf16_f32 v36, v45, v43
	v_cvt_pk_bf16_f32 v37, v47, v49
	v_cvt_pk_bf16_f32 v38, v51, v53
	v_cvt_pk_bf16_f32 v39, v55, v57
	v_lshl_add_u64 v[22:23], v[22:23], 0, v[40:41]
	global_store_dwordx4 v[22:23], v[36:39], off sc1
	s_waitcnt lgkmcnt(0)

.LBB0_875:
	s_andn2_b64 vcc, exec, s[2:3]
	s_cbranch_vccnz .LBB0_877
	s_load_dwordx2 s[8:9], s[60:61], 0xa8
	s_add_i32 s2, s13, 0xe800
	s_and_b32 s3, s2, 0x1ffc0
	s_and_b32 s2, s15, 0x3e0
	s_lshl_b32 s17, s2, 2
	v_add_u32_e32 v22, s3, v3
	s_waitcnt lgkmcnt(0)
	s_add_u32 s8, s8, s17
	s_addc_u32 s9, s9, 0
	v_lshlrev_b32_e32 v0, 2, v2
	v_ashrrev_i32_e32 v23, 31, v22
	v_lshl_add_u64 v[36:37], s[8:9], 0, v[0:1]
	v_lshlrev_b64 v[22:23], 12, v[22:23]
	v_lshl_add_u64 v[22:23], v[36:37], 0, v[22:23]
	s_mov_b32 s8, 0x8000
	v_add_co_u32_e32 v40, vcc, s8, v22
	s_mov_b32 s8, 0x10000
	s_nop 0
	v_addc_co_u32_e32 v41, vcc, 0, v23, vcc
	global_load_dwordx4 v[36:39], v[22:23], off nt
	v_add_co_u32_e32 v44, vcc, s8, v22
	global_load_dwordx4 v[40:43], v[40:41], off nt
	s_nop 0
	v_addc_co_u32_e32 v45, vcc, 0, v23, vcc
	global_load_dwordx4 v[44:47], v[44:45], off nt
	v_add_co_u32_e32 v48, vcc, s41, v22
	s_mov_b32 s8, 0x30000
	s_nop 0
	v_addc_co_u32_e32 v49, vcc, 0, v23, vcc
	global_load_dwordx4 v[48:51], v[48:49], off nt
	v_add_co_u32_e32 v52, vcc, s82, v22
	v_add_u32_e32 v0, v29, v5
	s_nop 0
	v_addc_co_u32_e32 v53, vcc, 0, v23, vcc
	global_load_dwordx4 v[52:55], v[52:53], off nt
	v_add_co_u32_e32 v56, vcc, s44, v22
	s_lshl_b32 s62, s3, 1
	s_nop 0
	v_addc_co_u32_e32 v57, vcc, 0, v23, vcc
	global_load_dwordx4 v[56:59], v[56:57], off nt
	v_add_co_u32_e32 v60, vcc, s8, v22
	s_mov_b32 s8, 0x38000
	s_nop 0
	v_addc_co_u32_e32 v61, vcc, 0, v23, vcc
	global_load_dwordx4 v[60:63], v[60:61], off nt
	v_add_co_u32_e32 v22, vcc, s8, v22
	s_nop 1
	v_addc_co_u32_e32 v23, vcc, 0, v23, vcc
	global_load_dwordx4 v[64:67], v[22:23], off nt
	v_add_u32_e32 v22, 0x420, v0
	s_waitcnt vmcnt(7)
	ds_write2_b32 v0, v36, v37 offset1:1
	ds_write2_b32 v0, v38, v39 offset0:2 offset1:3
	s_waitcnt vmcnt(6)
	ds_write2_b32 v22, v40, v41 offset1:1
	v_add_u32_e32 v22, 0x428, v0
	ds_write2_b32 v22, v42, v43 offset1:1
	v_add_u32_e32 v22, 0x840, v0
	s_waitcnt vmcnt(5)
	ds_write2_b32 v22, v44, v45 offset1:1
	v_add_u32_e32 v22, 0x848, v0
	ds_write2_b32 v22, v46, v47 offset1:1
	v_add_u32_e32 v22, 0xc60, v0
	v_add_u32_e32 v40, s2, v3
	s_waitcnt vmcnt(4)
	ds_write2_b32 v22, v48, v49 offset1:1
	v_add_u32_e32 v22, 0xc68, v0
	ds_write2_b32 v22, v50, v51 offset1:1
	v_add_u32_e32 v22, 0x1080, v0
	v_ashrrev_i32_e32 v41, 31, v40
	v_lshlrev_b64 v[40:41], 11, v[40:41]
	s_waitcnt vmcnt(3)
	ds_write2_b32 v22, v52, v53 offset1:1
	v_add_u32_e32 v22, 0x1088, v0
	ds_write2_b32 v22, v54, v55 offset1:1
	v_add_u32_e32 v22, 0x14a0, v0
	s_waitcnt vmcnt(2)
	ds_write2_b32 v22, v56, v57 offset1:1
	v_add_u32_e32 v22, 0x14a8, v0
	ds_write2_b32 v22, v58, v59 offset1:1
	v_add_u32_e32 v22, 0x18c0, v0
	s_waitcnt vmcnt(1)
	ds_write2_b32 v22, v60, v61 offset1:1
	v_add_u32_e32 v22, 0x18c8, v0
	ds_write2_b32 v22, v62, v63 offset1:1
	v_add_u32_e32 v22, 0x1ce0, v0
	v_add_u32_e32 v0, 0x1ce8, v0
	s_waitcnt vmcnt(0)
	ds_write2_b32 v22, v64, v65 offset1:1
	ds_write2_b32 v0, v66, v67 offset1:1
	s_waitcnt lgkmcnt(0)
	ds_read2_b32 v[42:43], v28 offset0:33 offset1:41
	ds_read2_b32 v[44:45], v28 offset1:8
	ds_read2_b32 v[46:47], v28 offset0:66 offset1:74
	ds_read2_b32 v[48:49], v28 offset0:99 offset1:107
	ds_read2_b32 v[50:51], v28 offset0:132 offset1:140
	ds_read2_b32 v[52:53], v28 offset0:165 offset1:173
	ds_read2_b32 v[54:55], v28 offset0:198 offset1:206
	ds_read2_b32 v[56:57], v28 offset0:231 offset1:239
	v_lshl_add_u64 v[22:23], v[16:17], 0, s[62:63]
	s_waitcnt lgkmcnt(6)
	v_cvt_pk_bf16_f32 v36, v44, v42
	s_waitcnt lgkmcnt(4)
	v_cvt_pk_bf16_f32 v37, v46, v48
	s_waitcnt lgkmcnt(2)
	v_cvt_pk_bf16_f32 v38, v50, v52
	s_waitcnt lgkmcnt(0)
	v_cvt_pk_bf16_f32 v39, v54, v56
	v_lshl_add_u64 v[40:41], v[22:23], 0, v[40:41]
	global_store_dwordx4 v[40:41], v[36:39], off sc1
	v_add_u32_e32 v40, s2, v24
	v_ashrrev_i32_e32 v41, 31, v40
	v_lshlrev_b64 v[40:41], 11, v[40:41]
	v_cvt_pk_bf16_f32 v36, v45, v43
	v_cvt_pk_bf16_f32 v37, v47, v49
	v_cvt_pk_bf16_f32 v38, v51, v53
	v_cvt_pk_bf16_f32 v39, v55, v57
	v_lshl_add_u64 v[40:41], v[22:23], 0, v[40:41]
	global_store_dwordx4 v[40:41], v[36:39], off sc1
	ds_read2_b32 v[42:43], v28 offset0:49 offset1:57
	ds_read2_b32 v[44:45], v28 offset0:16 offset1:24
	ds_read2_b32 v[46:47], v28 offset0:82 offset1:90
	ds_read2_b32 v[48:49], v28 offset0:115 offset1:123
	ds_read2_b32 v[50:51], v28 offset0:148 offset1:156
	ds_read2_b32 v[52:53], v28 offset0:181 offset1:189
	ds_read2_b32 v[54:55], v28 offset0:214 offset1:222
	ds_read2_b32 v[56:57], v28 offset0:247 offset1:255
	v_add_u32_e32 v40, s2, v25
	v_ashrrev_i32_e32 v41, 31, v40
	v_lshlrev_b64 v[40:41], 11, v[40:41]
	s_waitcnt lgkmcnt(6)
	v_cvt_pk_bf16_f32 v36, v44, v42
	s_waitcnt lgkmcnt(4)
	v_cvt_pk_bf16_f32 v37, v46, v48
	s_waitcnt lgkmcnt(2)
	v_cvt_pk_bf16_f32 v38, v50, v52
	s_waitcnt lgkmcnt(0)
	v_cvt_pk_bf16_f32 v39, v54, v56
	v_lshl_add_u64 v[40:41], v[22:23], 0, v[40:41]
	global_store_dwordx4 v[40:41], v[36:39], off sc1
	v_add_u32_e32 v40, s2, v26
	v_ashrrev_i32_e32 v41, 31, v40
	v_lshlrev_b64 v[40:41], 11, v[40:41]
	v_cvt_pk_bf16_f32 v36, v45, v43
	v_cvt_pk_bf16_f32 v37, v47, v49
	v_cvt_pk_bf16_f32 v38, v51, v53
	v_cvt_pk_bf16_f32 v39, v55, v57
	v_lshl_add_u64 v[22:23], v[22:23], 0, v[40:41]
	global_store_dwordx4 v[22:23], v[36:39], off sc1
	s_waitcnt lgkmcnt(0)

.LBB0_878:
	s_andn2_b64 vcc, exec, s[2:3]
	s_cbranch_vccnz .LBB0_880
	s_load_dwordx2 s[8:9], s[60:61], 0x98
	s_add_i32 s2, s13, 0xec00
	s_and_b32 s3, s2, 0x1ffc0
	s_and_b32 s2, s15, 0x3e0
	s_lshl_b32 s17, s2, 2
	v_add_u32_e32 v22, s3, v3
	s_waitcnt lgkmcnt(0)
	s_add_u32 s8, s8, s17
	s_addc_u32 s9, s9, 0
	v_lshlrev_b32_e32 v0, 2, v2
	v_ashrrev_i32_e32 v23, 31, v22
	v_lshl_add_u64 v[36:37], s[8:9], 0, v[0:1]
	v_lshlrev_b64 v[22:23], 12, v[22:23]
	v_lshl_add_u64 v[22:23], v[36:37], 0, v[22:23]
	s_mov_b32 s8, 0x8000
	v_add_co_u32_e32 v40, vcc, s8, v22
	s_mov_b32 s8, 0x10000
	s_nop 0
	v_addc_co_u32_e32 v41, vcc, 0, v23, vcc
	global_load_dwordx4 v[36:39], v[22:23], off nt
	v_add_co_u32_e32 v44, vcc, s8, v22
	global_load_dwordx4 v[40:43], v[40:41], off nt
	s_nop 0
	v_addc_co_u32_e32 v45, vcc, 0, v23, vcc
	global_load_dwordx4 v[44:47], v[44:45], off nt
	v_add_co_u32_e32 v48, vcc, s41, v22
	s_mov_b32 s8, 0x30000
	s_nop 0
	v_addc_co_u32_e32 v49, vcc, 0, v23, vcc
	global_load_dwordx4 v[48:51], v[48:49], off nt
	v_add_co_u32_e32 v52, vcc, s82, v22
	v_add_u32_e32 v0, v29, v5
	s_nop 0
	v_addc_co_u32_e32 v53, vcc, 0, v23, vcc
	global_load_dwordx4 v[52:55], v[52:53], off nt
	v_add_co_u32_e32 v56, vcc, s44, v22
	s_lshl_b32 s62, s3, 1
	s_nop 0
	v_addc_co_u32_e32 v57, vcc, 0, v23, vcc
	global_load_dwordx4 v[56:59], v[56:57], off nt
	v_add_co_u32_e32 v60, vcc, s8, v22
	s_mov_b32 s8, 0x38000
	s_nop 0
	v_addc_co_u32_e32 v61, vcc, 0, v23, vcc
	global_load_dwordx4 v[60:63], v[60:61], off nt
	v_add_co_u32_e32 v22, vcc, s8, v22
	s_nop 1
	v_addc_co_u32_e32 v23, vcc, 0, v23, vcc
	global_load_dwordx4 v[64:67], v[22:23], off nt
	v_add_u32_e32 v22, 0x420, v0
	s_waitcnt vmcnt(7)
	ds_write2_b32 v0, v36, v37 offset1:1
	ds_write2_b32 v0, v38, v39 offset0:2 offset1:3
	s_waitcnt vmcnt(6)
	ds_write2_b32 v22, v40, v41 offset1:1
	v_add_u32_e32 v22, 0x428, v0
	ds_write2_b32 v22, v42, v43 offset1:1
	v_add_u32_e32 v22, 0x840, v0
	s_waitcnt vmcnt(5)
	ds_write2_b32 v22, v44, v45 offset1:1
	v_add_u32_e32 v22, 0x848, v0
	ds_write2_b32 v22, v46, v47 offset1:1
	v_add_u32_e32 v22, 0xc60, v0
	v_add_u32_e32 v40, s2, v3
	s_waitcnt vmcnt(4)
	ds_write2_b32 v22, v48, v49 offset1:1
	v_add_u32_e32 v22, 0xc68, v0
	ds_write2_b32 v22, v50, v51 offset1:1
	v_add_u32_e32 v22, 0x1080, v0
	v_ashrrev_i32_e32 v41, 31, v40
	v_lshlrev_b64 v[40:41], 11, v[40:41]
	s_waitcnt vmcnt(3)
	ds_write2_b32 v22, v52, v53 offset1:1
	v_add_u32_e32 v22, 0x1088, v0
	ds_write2_b32 v22, v54, v55 offset1:1
	v_add_u32_e32 v22, 0x14a0, v0
	s_waitcnt vmcnt(2)
	ds_write2_b32 v22, v56, v57 offset1:1
	v_add_u32_e32 v22, 0x14a8, v0
	ds_write2_b32 v22, v58, v59 offset1:1
	v_add_u32_e32 v22, 0x18c0, v0
	s_waitcnt vmcnt(1)
	ds_write2_b32 v22, v60, v61 offset1:1
	v_add_u32_e32 v22, 0x18c8, v0
	ds_write2_b32 v22, v62, v63 offset1:1
	v_add_u32_e32 v22, 0x1ce0, v0
	v_add_u32_e32 v0, 0x1ce8, v0
	s_waitcnt vmcnt(0)
	ds_write2_b32 v22, v64, v65 offset1:1
	ds_write2_b32 v0, v66, v67 offset1:1
	s_waitcnt lgkmcnt(0)
	ds_read2_b32 v[42:43], v28 offset0:33 offset1:41
	ds_read2_b32 v[44:45], v28 offset1:8
	ds_read2_b32 v[46:47], v28 offset0:66 offset1:74
	ds_read2_b32 v[48:49], v28 offset0:99 offset1:107
	ds_read2_b32 v[50:51], v28 offset0:132 offset1:140
	ds_read2_b32 v[52:53], v28 offset0:165 offset1:173
	ds_read2_b32 v[54:55], v28 offset0:198 offset1:206
	ds_read2_b32 v[56:57], v28 offset0:231 offset1:239
	v_lshl_add_u64 v[22:23], v[18:19], 0, s[62:63]
	s_waitcnt lgkmcnt(6)
	v_cvt_pk_bf16_f32 v36, v44, v42
	s_waitcnt lgkmcnt(4)
	v_cvt_pk_bf16_f32 v37, v46, v48
	s_waitcnt lgkmcnt(2)
	v_cvt_pk_bf16_f32 v38, v50, v52
	s_waitcnt lgkmcnt(0)
	v_cvt_pk_bf16_f32 v39, v54, v56
	v_lshl_add_u64 v[40:41], v[22:23], 0, v[40:41]
	global_store_dwordx4 v[40:41], v[36:39], off sc1
	v_add_u32_e32 v40, s2, v24
	v_ashrrev_i32_e32 v41, 31, v40
	v_lshlrev_b64 v[40:41], 11, v[40:41]
	v_cvt_pk_bf16_f32 v36, v45, v43
	v_cvt_pk_bf16_f32 v37, v47, v49
	v_cvt_pk_bf16_f32 v38, v51, v53
	v_cvt_pk_bf16_f32 v39, v55, v57
	v_lshl_add_u64 v[40:41], v[22:23], 0, v[40:41]
	global_store_dwordx4 v[40:41], v[36:39], off sc1
	ds_read2_b32 v[42:43], v28 offset0:49 offset1:57
	ds_read2_b32 v[44:45], v28 offset0:16 offset1:24
	ds_read2_b32 v[46:47], v28 offset0:82 offset1:90
	ds_read2_b32 v[48:49], v28 offset0:115 offset1:123
	ds_read2_b32 v[50:51], v28 offset0:148 offset1:156
	ds_read2_b32 v[52:53], v28 offset0:181 offset1:189
	ds_read2_b32 v[54:55], v28 offset0:214 offset1:222
	ds_read2_b32 v[56:57], v28 offset0:247 offset1:255
	v_add_u32_e32 v40, s2, v25
	v_ashrrev_i32_e32 v41, 31, v40
	v_lshlrev_b64 v[40:41], 11, v[40:41]
	s_waitcnt lgkmcnt(6)
	v_cvt_pk_bf16_f32 v36, v44, v42
	s_waitcnt lgkmcnt(4)
	v_cvt_pk_bf16_f32 v37, v46, v48
	s_waitcnt lgkmcnt(2)
	v_cvt_pk_bf16_f32 v38, v50, v52
	s_waitcnt lgkmcnt(0)
	v_cvt_pk_bf16_f32 v39, v54, v56
	v_lshl_add_u64 v[40:41], v[22:23], 0, v[40:41]
	global_store_dwordx4 v[40:41], v[36:39], off sc1
	v_add_u32_e32 v40, s2, v26
	v_ashrrev_i32_e32 v41, 31, v40
	v_lshlrev_b64 v[40:41], 11, v[40:41]
	v_cvt_pk_bf16_f32 v36, v45, v43
	v_cvt_pk_bf16_f32 v37, v47, v49
	v_cvt_pk_bf16_f32 v38, v51, v53
	v_cvt_pk_bf16_f32 v39, v55, v57
	v_lshl_add_u64 v[22:23], v[22:23], 0, v[40:41]
	global_store_dwordx4 v[22:23], v[36:39], off sc1
	s_waitcnt lgkmcnt(0)

.LBB0_881:
	s_andn2_b64 vcc, exec, s[2:3]
	s_cbranch_vccnz .LBB0_883
	s_add_i32 s2, s1, 0x7c00
	s_and_b32 s3, s2, 0xffff
	s_mul_i32 s3, s3, 0xaaab
	s_lshr_b32 s17, s3, 16
	s_lshr_b32 s3, s3, 22
	s_load_dwordx2 s[8:9], s[60:61], 0x80
	s_mulk_i32 s3, 0x60
	s_sub_i32 s2, s2, s3
	s_lshl_b32 s2, s2, 5
	s_and_b32 s2, s2, 0xffe0
	s_and_b32 s3, s17, 0xffc0
	s_lshl_b32 s17, s2, 2
	s_waitcnt lgkmcnt(0)
	s_add_u32 s8, s8, s17
	v_add_u32_e32 v35, s3, v3
	s_addc_u32 s9, s9, 0
	v_lshlrev_b32_e32 v0, 2, v2
	v_lshl_add_u64 v[22:23], s[8:9], 0, v[0:1]
	v_add_u32_e32 v0, 8, v35
	v_mad_i64_i32 v[36:37], s[8:9], v35, s40, v[22:23]
	v_mad_i64_i32 v[40:41], s[8:9], v0, s40, v[22:23]
	global_load_dwordx4 v[36:39], v[36:37], off nt
	v_add_u32_e32 v0, 16, v35
	global_load_dwordx4 v[40:43], v[40:41], off nt
	v_mad_i64_i32 v[44:45], s[8:9], v0, s40, v[22:23]
	global_load_dwordx4 v[44:47], v[44:45], off nt
	v_add_u32_e32 v0, 24, v35
	v_mad_i64_i32 v[48:49], s[8:9], v0, s40, v[22:23]
	global_load_dwordx4 v[48:51], v[48:49], off nt
	v_add_u32_e32 v0, 32, v35
	v_mad_i64_i32 v[52:53], s[8:9], v0, s40, v[22:23]
	global_load_dwordx4 v[52:55], v[52:53], off nt
	v_add_u32_e32 v0, 40, v35
	v_mad_i64_i32 v[56:57], s[8:9], v0, s40, v[22:23]
	global_load_dwordx4 v[56:59], v[56:57], off nt
	v_add_u32_e32 v0, 48, v35
	v_mad_i64_i32 v[60:61], s[8:9], v0, s40, v[22:23]
	global_load_dwordx4 v[60:63], v[60:61], off nt
	v_add_u32_e32 v0, 56, v35
	v_mad_i64_i32 v[22:23], s[8:9], v0, s40, v[22:23]
	global_load_dwordx4 v[64:67], v[22:23], off nt
	v_add_u32_e32 v0, v29, v5
	v_add_u32_e32 v22, 0x420, v0
	s_lshl_b32 s62, s3, 1
	s_waitcnt vmcnt(7)
	ds_write2_b32 v0, v36, v37 offset1:1
	ds_write2_b32 v0, v38, v39 offset0:2 offset1:3
	s_waitcnt vmcnt(6)
	ds_write2_b32 v22, v40, v41 offset1:1
	v_add_u32_e32 v22, 0x428, v0
	ds_write2_b32 v22, v42, v43 offset1:1
	v_add_u32_e32 v22, 0x840, v0
	s_waitcnt vmcnt(5)
	ds_write2_b32 v22, v44, v45 offset1:1
	v_add_u32_e32 v22, 0x848, v0
	ds_write2_b32 v22, v46, v47 offset1:1
	v_add_u32_e32 v22, 0xc60, v0
	s_waitcnt vmcnt(4)
	ds_write2_b32 v22, v48, v49 offset1:1
	v_add_u32_e32 v22, 0xc68, v0
	ds_write2_b32 v22, v50, v51 offset1:1
	v_add_u32_e32 v22, 0x1080, v0
	s_waitcnt vmcnt(3)
	ds_write2_b32 v22, v52, v53 offset1:1
	v_add_u32_e32 v22, 0x1088, v0
	ds_write2_b32 v22, v54, v55 offset1:1
	v_add_u32_e32 v22, 0x14a0, v0
	s_waitcnt vmcnt(2)
	ds_write2_b32 v22, v56, v57 offset1:1
	v_add_u32_e32 v22, 0x14a8, v0
	ds_write2_b32 v22, v58, v59 offset1:1
	v_add_u32_e32 v22, 0x18c0, v0
	s_waitcnt vmcnt(1)
	ds_write2_b32 v22, v60, v61 offset1:1
	v_add_u32_e32 v22, 0x18c8, v0
	ds_write2_b32 v22, v62, v63 offset1:1
	v_add_u32_e32 v22, 0x1ce0, v0
	v_add_u32_e32 v0, 0x1ce8, v0
	s_waitcnt vmcnt(0)
	ds_write2_b32 v22, v64, v65 offset1:1
	ds_write2_b32 v0, v66, v67 offset1:1
	s_waitcnt lgkmcnt(0)
	ds_read2_b32 v[42:43], v28 offset0:33 offset1:41
	ds_read2_b32 v[44:45], v28 offset1:8
	ds_read2_b32 v[46:47], v28 offset0:66 offset1:74
	ds_read2_b32 v[48:49], v28 offset0:99 offset1:107
	ds_read2_b32 v[50:51], v28 offset0:132 offset1:140
	ds_read2_b32 v[52:53], v28 offset0:165 offset1:173
	ds_read2_b32 v[54:55], v28 offset0:198 offset1:206
	ds_read2_b32 v[56:57], v28 offset0:231 offset1:239
	v_add_u32_e32 v40, s2, v3
	v_ashrrev_i32_e32 v41, 31, v40
	v_lshl_add_u64 v[22:23], v[20:21], 0, s[62:63]
	v_lshlrev_b64 v[40:41], 11, v[40:41]
	s_waitcnt lgkmcnt(6)
	v_cvt_pk_bf16_f32 v36, v44, v42
	s_waitcnt lgkmcnt(4)
	v_cvt_pk_bf16_f32 v37, v46, v48
	s_waitcnt lgkmcnt(2)
	v_cvt_pk_bf16_f32 v38, v50, v52
	s_waitcnt lgkmcnt(0)
	v_cvt_pk_bf16_f32 v39, v54, v56
	v_lshl_add_u64 v[40:41], v[22:23], 0, v[40:41]
	global_store_dwordx4 v[40:41], v[36:39], off sc1
	v_add_u32_e32 v40, s2, v24
	v_ashrrev_i32_e32 v41, 31, v40
	v_lshlrev_b64 v[40:41], 11, v[40:41]
	v_cvt_pk_bf16_f32 v36, v45, v43
	v_cvt_pk_bf16_f32 v37, v47, v49
	v_cvt_pk_bf16_f32 v38, v51, v53
	v_cvt_pk_bf16_f32 v39, v55, v57
	v_lshl_add_u64 v[40:41], v[22:23], 0, v[40:41]
	global_store_dwordx4 v[40:41], v[36:39], off sc1
	ds_read2_b32 v[42:43], v28 offset0:49 offset1:57
	ds_read2_b32 v[44:45], v28 offset0:16 offset1:24
	ds_read2_b32 v[46:47], v28 offset0:82 offset1:90
	ds_read2_b32 v[48:49], v28 offset0:115 offset1:123
	ds_read2_b32 v[50:51], v28 offset0:148 offset1:156
	ds_read2_b32 v[52:53], v28 offset0:181 offset1:189
	ds_read2_b32 v[54:55], v28 offset0:214 offset1:222
	ds_read2_b32 v[56:57], v28 offset0:247 offset1:255
	v_add_u32_e32 v40, s2, v25
	v_ashrrev_i32_e32 v41, 31, v40
	v_lshlrev_b64 v[40:41], 11, v[40:41]
	s_waitcnt lgkmcnt(6)
	v_cvt_pk_bf16_f32 v36, v44, v42
	s_waitcnt lgkmcnt(4)
	v_cvt_pk_bf16_f32 v37, v46, v48
	s_waitcnt lgkmcnt(2)
	v_cvt_pk_bf16_f32 v38, v50, v52
	s_waitcnt lgkmcnt(0)
	v_cvt_pk_bf16_f32 v39, v54, v56
	v_lshl_add_u64 v[40:41], v[22:23], 0, v[40:41]
	global_store_dwordx4 v[40:41], v[36:39], off sc1
	v_add_u32_e32 v40, s2, v26
	v_ashrrev_i32_e32 v41, 31, v40
	v_lshlrev_b64 v[40:41], 11, v[40:41]
	v_cvt_pk_bf16_f32 v36, v45, v43
	v_cvt_pk_bf16_f32 v37, v47, v49
	v_cvt_pk_bf16_f32 v38, v51, v53
	v_cvt_pk_bf16_f32 v39, v55, v57
	v_lshl_add_u64 v[22:23], v[22:23], 0, v[40:41]
	global_store_dwordx4 v[22:23], v[36:39], off sc1
	s_waitcnt lgkmcnt(0)

.LBB0_884:
	s_andn2_b64 vcc, exec, s[2:3]
	s_cbranch_vccnz .LBB0_849
	s_mul_hi_i32 s2, s1, 0x3e0f83e1
	s_lshr_b32 s3, s2, 31
	s_ashr_i32 s2, s2, 10
	s_add_i32 s21, s2, s3
	s_mul_i32 s2, s21, 0xffffef80
	s_add_i32 s8, s1, s2
	s_mul_i32 s2, s8, 0xba3
	s_lshr_b32 s3, s2, 31
	s_lshr_b32 s2, s2, 22
	s_add_i32 s2, s2, s3
	s_mulk_i32 s2, 0x580
	s_sub_i32 s19, s8, s2
	s_mul_i32 s3, s21, 0x1080000
	s_mul_hi_i32 s2, s21, 0x1080000
	s_add_u32 s17, s11, s3
	s_addc_u32 s18, s12, s2
	s_add_i32 s2, s8, 0x57f
	s_cmpk_gt_u32 s2, 0xafe
	s_mul_hi_i32 s20, s21, 0xb00000
	s_mul_i32 s21, s21, 0xb00000
	s_mov_b64 s[2:3], -1
	s_cbranch_scc0 .LBB0_891
	s_addk_i32 s8, 0xfa80
	s_cmpk_gt_u32 s8, 0x57f
	s_cbranch_scc0 .LBB0_888
	s_load_dwordx2 s[2:3], s[60:61], 0x78
	v_lshlrev_b32_e32 v0, 2, v2
	s_waitcnt lgkmcnt(0)
	s_add_u32 s9, s2, s21
	s_sext_i32_i16 s2, s19
	s_addc_u32 s24, s3, s20
	s_bfe_u32 s2, s2, 0x5001a
	s_add_i32 s2, s19, s2
	s_sext_i32_i16 s3, s2
	s_and_b32 s2, s2, 0xffe0
	s_sub_i32 s2, s19, s2
	s_sext_i32_i16 s2, s2
	s_lshl_b32 s3, s3, 1
	s_lshl_b32 s2, s2, 5
	s_and_b32 s8, s3, 0xffffffc0
	s_ashr_i32 s3, s2, 31
	s_lshl_b64 s[22:23], s[2:3], 2
	v_add_u32_e32 v22, s8, v3
	s_add_u32 s22, s9, s22
	s_addc_u32 s23, s24, s23
	v_ashrrev_i32_e32 v23, 31, v22
	v_lshl_add_u64 v[36:37], s[22:23], 0, v[0:1]
	v_lshlrev_b64 v[22:23], 12, v[22:23]
	v_lshl_add_u64 v[22:23], v[36:37], 0, v[22:23]
	s_mov_b32 s3, 0x8000
	v_add_co_u32_e32 v40, vcc, s3, v22
	s_mov_b32 s3, 0x10000
	s_nop 0
	v_addc_co_u32_e32 v41, vcc, 0, v23, vcc
	global_load_dwordx4 v[36:39], v[22:23], off nt
	v_add_co_u32_e32 v44, vcc, s3, v22
	global_load_dwordx4 v[40:43], v[40:41], off nt
	s_nop 0
	v_addc_co_u32_e32 v45, vcc, 0, v23, vcc
	global_load_dwordx4 v[44:47], v[44:45], off nt
	v_add_co_u32_e32 v48, vcc, s41, v22
	s_mov_b32 s3, 0x30000
	s_nop 0
	v_addc_co_u32_e32 v49, vcc, 0, v23, vcc
	global_load_dwordx4 v[48:51], v[48:49], off nt
	v_add_co_u32_e32 v52, vcc, s82, v22
	v_add_u32_e32 v0, v29, v5
	s_nop 0
	v_addc_co_u32_e32 v53, vcc, 0, v23, vcc
	global_load_dwordx4 v[52:55], v[52:53], off nt
	v_add_co_u32_e32 v56, vcc, s44, v22
	s_ashr_i32 s9, s8, 31
	s_nop 0
	v_addc_co_u32_e32 v57, vcc, 0, v23, vcc
	global_load_dwordx4 v[56:59], v[56:57], off nt
	v_add_co_u32_e32 v60, vcc, s3, v22
	s_mov_b32 s3, 0x38000
	s_nop 0
	v_addc_co_u32_e32 v61, vcc, 0, v23, vcc
	global_load_dwordx4 v[60:63], v[60:61], off nt
	v_add_co_u32_e32 v22, vcc, s3, v22
	s_lshl_b64 s[8:9], s[8:9], 1
	s_nop 0
	v_addc_co_u32_e32 v23, vcc, 0, v23, vcc
	global_load_dwordx4 v[64:67], v[22:23], off nt
	v_add_u32_e32 v22, 0x420, v0
	s_add_u32 s8, s17, s8
	s_addc_u32 s9, s18, s9
	s_movk_i32 s3, 0x1600
	s_waitcnt vmcnt(7)
	ds_write2_b32 v0, v36, v37 offset1:1
	ds_write2_b32 v0, v38, v39 offset0:2 offset1:3
	s_waitcnt vmcnt(6)
	ds_write2_b32 v22, v40, v41 offset1:1
	v_add_u32_e32 v22, 0x428, v0
	ds_write2_b32 v22, v42, v43 offset1:1
	v_add_u32_e32 v22, 0x840, v0
	s_waitcnt vmcnt(5)
	ds_write2_b32 v22, v44, v45 offset1:1
	v_add_u32_e32 v22, 0x848, v0
	ds_write2_b32 v22, v46, v47 offset1:1
	v_add_u32_e32 v22, 0xc60, v0
	s_waitcnt vmcnt(4)
	ds_write2_b32 v22, v48, v49 offset1:1
	v_add_u32_e32 v22, 0xc68, v0
	ds_write2_b32 v22, v50, v51 offset1:1
	v_add_u32_e32 v22, 0x1080, v0
	s_waitcnt vmcnt(3)
	ds_write2_b32 v22, v52, v53 offset1:1
	v_add_u32_e32 v22, 0x1088, v0
	ds_write2_b32 v22, v54, v55 offset1:1
	v_add_u32_e32 v22, 0x14a0, v0
	s_waitcnt vmcnt(2)
	ds_write2_b32 v22, v56, v57 offset1:1
	v_add_u32_e32 v22, 0x14a8, v0
	ds_write2_b32 v22, v58, v59 offset1:1
	v_add_u32_e32 v22, 0x18c0, v0
	s_waitcnt vmcnt(1)
	ds_write2_b32 v22, v60, v61 offset1:1
	v_add_u32_e32 v22, 0x18c8, v0
	ds_write2_b32 v22, v62, v63 offset1:1
	v_add_u32_e32 v22, 0x1ce0, v0
	v_add_u32_e32 v0, 0x1ce8, v0
	s_waitcnt vmcnt(0)
	ds_write2_b32 v22, v64, v65 offset1:1
	ds_write2_b32 v0, v66, v67 offset1:1
	s_waitcnt lgkmcnt(0)
	ds_read2_b32 v[40:41], v28 offset0:33 offset1:41
	ds_read2_b32 v[42:43], v28 offset1:8
	ds_read2_b32 v[44:45], v28 offset0:66 offset1:74
	ds_read2_b32 v[46:47], v28 offset0:99 offset1:107
	ds_read2_b32 v[48:49], v28 offset0:132 offset1:140
	ds_read2_b32 v[50:51], v28 offset0:165 offset1:173
	ds_read2_b32 v[52:53], v28 offset0:198 offset1:206
	ds_read2_b32 v[54:55], v28 offset0:231 offset1:239
	v_lshlrev_b32_e32 v0, 1, v4
	v_lshl_add_u64 v[22:23], s[8:9], 0, v[0:1]
	s_mov_b64 s[8:9], 0xb00000
	v_lshl_add_u64 v[22:23], v[22:23], 0, s[8:9]
	v_add_u32_e32 v0, s2, v3
	s_waitcnt lgkmcnt(6)
	v_cvt_pk_bf16_f32 v36, v42, v40
	s_waitcnt lgkmcnt(4)
	v_cvt_pk_bf16_f32 v37, v44, v46
	s_waitcnt lgkmcnt(2)
	v_cvt_pk_bf16_f32 v38, v48, v50
	s_waitcnt lgkmcnt(0)
	v_cvt_pk_bf16_f32 v39, v52, v54
	v_mad_i64_i32 v[56:57], s[8:9], v0, s3, v[22:23]
	v_add_u32_e32 v0, s2, v24
	global_store_dwordx4 v[56:57], v[36:39], off sc1
	s_nop 1
	v_cvt_pk_bf16_f32 v36, v43, v41
	v_cvt_pk_bf16_f32 v37, v45, v47
	v_cvt_pk_bf16_f32 v38, v49, v51
	v_cvt_pk_bf16_f32 v39, v53, v55
	v_mad_i64_i32 v[40:41], s[8:9], v0, s3, v[22:23]
	global_store_dwordx4 v[40:41], v[36:39], off sc1
	ds_read2_b32 v[40:41], v28 offset0:49 offset1:57
	ds_read2_b32 v[42:43], v28 offset0:16 offset1:24
	ds_read2_b32 v[44:45], v28 offset0:82 offset1:90
	ds_read2_b32 v[46:47], v28 offset0:115 offset1:123
	ds_read2_b32 v[48:49], v28 offset0:148 offset1:156
	ds_read2_b32 v[50:51], v28 offset0:181 offset1:189
	ds_read2_b32 v[52:53], v28 offset0:214 offset1:222
	ds_read2_b32 v[54:55], v28 offset0:247 offset1:255
	v_add_u32_e32 v0, s2, v25
	s_waitcnt lgkmcnt(6)
	v_cvt_pk_bf16_f32 v36, v42, v40
	s_waitcnt lgkmcnt(4)
	v_cvt_pk_bf16_f32 v37, v44, v46
	s_waitcnt lgkmcnt(2)
	v_cvt_pk_bf16_f32 v38, v48, v50
	s_waitcnt lgkmcnt(0)
	v_cvt_pk_bf16_f32 v39, v52, v54
	v_mad_i64_i32 v[56:57], s[8:9], v0, s3, v[22:23]
	v_add_u32_e32 v0, s2, v26
	global_store_dwordx4 v[56:57], v[36:39], off sc1
	v_mad_i64_i32 v[22:23], s[2:3], v0, s3, v[22:23]
	s_nop 0
	v_cvt_pk_bf16_f32 v36, v43, v41
	v_cvt_pk_bf16_f32 v37, v45, v47
	v_cvt_pk_bf16_f32 v38, v49, v51
	v_cvt_pk_bf16_f32 v39, v53, v55
	global_store_dwordx4 v[22:23], v[36:39], off sc1
	s_waitcnt lgkmcnt(0)
	s_mov_b64 s[2:3], 0
.LBB0_888:
	s_andn2_b64 vcc, exec, s[2:3]
	s_cbranch_vccnz .LBB0_890
	s_load_dwordx2 s[2:3], s[60:61], 0x70
	v_lshlrev_b32_e32 v0, 2, v2
	s_waitcnt lgkmcnt(0)
	s_add_u32 s8, s2, s21
	s_addc_u32 s3, s3, s20
	s_and_b32 s2, 0xffff, s19
	s_mul_i32 s2, s2, 0xba2f
	s_lshr_b32 s9, s2, 16
	s_lshr_b32 s2, s2, 22
	s_mulk_i32 s2, 0x58
	s_sub_i32 s2, s19, s2
	s_lshl_b32 s2, s2, 5
	s_and_b32 s2, s2, 0xffe0
	s_and_b32 s22, s9, 0xffc0
	s_lshl_b32 s9, s2, 2
	s_add_u32 s8, s8, s9
	v_add_u32_e32 v35, s22, v3
	s_addc_u32 s9, s3, 0
	v_lshl_add_u64 v[22:23], s[8:9], 0, v[0:1]
	s_movk_i32 s3, 0x2c00
	v_add_u32_e32 v0, 8, v35
	v_mad_i64_i32 v[36:37], s[8:9], v35, s3, v[22:23]
	v_mad_i64_i32 v[40:41], s[8:9], v0, s3, v[22:23]
	global_load_dwordx4 v[36:39], v[36:37], off nt
	v_add_u32_e32 v0, 16, v35
	global_load_dwordx4 v[40:43], v[40:41], off nt
	v_mad_i64_i32 v[44:45], s[8:9], v0, s3, v[22:23]
	global_load_dwordx4 v[44:47], v[44:45], off nt
	v_add_u32_e32 v0, 24, v35
	v_mad_i64_i32 v[48:49], s[8:9], v0, s3, v[22:23]
	global_load_dwordx4 v[48:51], v[48:49], off nt
	v_add_u32_e32 v0, 32, v35
	v_mad_i64_i32 v[52:53], s[8:9], v0, s3, v[22:23]
	global_load_dwordx4 v[52:55], v[52:53], off nt
	v_add_u32_e32 v0, 40, v35
	v_mad_i64_i32 v[56:57], s[8:9], v0, s3, v[22:23]
	global_load_dwordx4 v[56:59], v[56:57], off nt
	v_add_u32_e32 v0, 48, v35
	v_mad_i64_i32 v[60:61], s[8:9], v0, s3, v[22:23]
	global_load_dwordx4 v[60:63], v[60:61], off nt
	v_add_u32_e32 v0, 56, v35
	v_mad_i64_i32 v[22:23], s[8:9], v0, s3, v[22:23]
	global_load_dwordx4 v[64:67], v[22:23], off nt
	v_add_u32_e32 v0, v29, v5
	v_add_u32_e32 v22, 0x420, v0
	s_lshl_b32 s3, s22, 1
	s_add_u32 s8, s17, s3
	s_addc_u32 s9, s18, 0
	s_waitcnt vmcnt(7)
	ds_write2_b32 v0, v36, v37 offset1:1
	ds_write2_b32 v0, v38, v39 offset0:2 offset1:3
	s_waitcnt vmcnt(6)
	ds_write2_b32 v22, v40, v41 offset1:1
	v_add_u32_e32 v22, 0x428, v0
	ds_write2_b32 v22, v42, v43 offset1:1
	v_add_u32_e32 v22, 0x840, v0
	s_waitcnt vmcnt(5)
	ds_write2_b32 v22, v44, v45 offset1:1
	v_add_u32_e32 v22, 0x848, v0
	ds_write2_b32 v22, v46, v47 offset1:1
	v_add_u32_e32 v22, 0xc60, v0
	s_waitcnt vmcnt(4)
	ds_write2_b32 v22, v48, v49 offset1:1
	v_add_u32_e32 v22, 0xc68, v0
	ds_write2_b32 v22, v50, v51 offset1:1
	v_add_u32_e32 v22, 0x1080, v0
	s_waitcnt vmcnt(3)
	ds_write2_b32 v22, v52, v53 offset1:1
	v_add_u32_e32 v22, 0x1088, v0
	ds_write2_b32 v22, v54, v55 offset1:1
	v_add_u32_e32 v22, 0x14a0, v0
	s_waitcnt vmcnt(2)
	ds_write2_b32 v22, v56, v57 offset1:1
	v_add_u32_e32 v22, 0x14a8, v0
	ds_write2_b32 v22, v58, v59 offset1:1
	v_add_u32_e32 v22, 0x18c0, v0
	s_waitcnt vmcnt(1)
	ds_write2_b32 v22, v60, v61 offset1:1
	v_add_u32_e32 v22, 0x18c8, v0
	ds_write2_b32 v22, v62, v63 offset1:1
	v_add_u32_e32 v22, 0x1ce0, v0
	v_add_u32_e32 v0, 0x1ce8, v0
	s_waitcnt vmcnt(0)
	ds_write2_b32 v22, v64, v65 offset1:1
	ds_write2_b32 v0, v66, v67 offset1:1
	s_waitcnt lgkmcnt(0)
	v_lshlrev_b32_e32 v0, 1, v4
	ds_read2_b32 v[42:43], v28 offset0:33 offset1:41
	ds_read2_b32 v[44:45], v28 offset1:8
	ds_read2_b32 v[46:47], v28 offset0:66 offset1:74
	ds_read2_b32 v[48:49], v28 offset0:99 offset1:107
	ds_read2_b32 v[50:51], v28 offset0:132 offset1:140
	ds_read2_b32 v[52:53], v28 offset0:165 offset1:173
	ds_read2_b32 v[54:55], v28 offset0:198 offset1:206
	ds_read2_b32 v[56:57], v28 offset0:231 offset1:239
	v_lshl_add_u64 v[22:23], s[8:9], 0, v[0:1]
	v_add_lshl_u32 v0, v3, s2, 1
	v_and_or_b32 v40, v0, s43, v32
	v_ashrrev_i32_e32 v41, 31, v40
	v_lshlrev_b64 v[40:41], 11, v[40:41]
	s_waitcnt lgkmcnt(6)
	v_cvt_pk_bf16_f32 v36, v44, v42
	s_waitcnt lgkmcnt(4)
	v_cvt_pk_bf16_f32 v37, v46, v48
	s_waitcnt lgkmcnt(2)
	v_cvt_pk_bf16_f32 v38, v50, v52
	s_waitcnt lgkmcnt(0)
	v_cvt_pk_bf16_f32 v39, v54, v56
	v_lshl_add_u64 v[40:41], v[22:23], 0, v[40:41]
	v_add_lshl_u32 v0, v24, s2, 1
	global_store_dwordx4 v[40:41], v[36:39], off sc1
	v_and_or_b32 v40, v0, s43, v33
	v_ashrrev_i32_e32 v41, 31, v40
	v_lshlrev_b64 v[40:41], 11, v[40:41]
	v_cvt_pk_bf16_f32 v36, v45, v43
	v_cvt_pk_bf16_f32 v37, v47, v49
	v_cvt_pk_bf16_f32 v38, v51, v53
	v_cvt_pk_bf16_f32 v39, v55, v57
	v_lshl_add_u64 v[40:41], v[22:23], 0, v[40:41]
	global_store_dwordx4 v[40:41], v[36:39], off sc1
	ds_read2_b32 v[42:43], v28 offset0:16 offset1:24
	ds_read2_b32 v[44:45], v28 offset0:49 offset1:57
	ds_read2_b32 v[46:47], v28 offset0:82 offset1:90
	ds_read2_b32 v[48:49], v28 offset0:115 offset1:123
	ds_read2_b32 v[50:51], v28 offset0:148 offset1:156
	ds_read2_b32 v[52:53], v28 offset0:181 offset1:189
	ds_read2_b32 v[54:55], v28 offset0:214 offset1:222
	ds_read2_b32 v[56:57], v28 offset0:247 offset1:255
	v_add_lshl_u32 v0, v25, s2, 1
	v_and_or_b32 v40, v0, s43, v32
	v_ashrrev_i32_e32 v41, 31, v40
	v_lshlrev_b64 v[40:41], 11, v[40:41]
	s_waitcnt lgkmcnt(6)
	v_cvt_pk_bf16_f32 v36, v42, v44
	s_waitcnt lgkmcnt(4)
	v_cvt_pk_bf16_f32 v37, v46, v48
	s_waitcnt lgkmcnt(2)
	v_cvt_pk_bf16_f32 v38, v50, v52
	s_waitcnt lgkmcnt(0)
	v_cvt_pk_bf16_f32 v39, v54, v56
	v_lshl_add_u64 v[40:41], v[22:23], 0, v[40:41]
	v_add_lshl_u32 v0, v26, s2, 1
	global_store_dwordx4 v[40:41], v[36:39], off sc1
	v_and_or_b32 v40, v0, s43, v34
	v_ashrrev_i32_e32 v41, 31, v40
	v_lshlrev_b64 v[40:41], 11, v[40:41]
	v_cvt_pk_bf16_f32 v36, v43, v45
	v_cvt_pk_bf16_f32 v37, v47, v49
	v_cvt_pk_bf16_f32 v38, v51, v53
	v_cvt_pk_bf16_f32 v39, v55, v57
	v_lshl_add_u64 v[22:23], v[22:23], 0, v[40:41]
	global_store_dwordx4 v[22:23], v[36:39], off sc1
	s_waitcnt lgkmcnt(0)

.LBB0_891:
	s_andn2_b64 vcc, exec, s[2:3]
	s_cbranch_vccnz .LBB0_849
	s_load_dwordx2 s[2:3], s[60:61], 0x68
	v_lshlrev_b32_e32 v0, 2, v2
	s_waitcnt lgkmcnt(0)
	s_add_u32 s9, s2, s21
	s_sext_i32_i16 s2, s19
	s_mulk_i32 s2, 0xba3
	s_addc_u32 s22, s3, s20
	s_lshr_b32 s3, s2, 31
	s_ashr_i32 s2, s2, 18
	s_add_i32 s2, s2, s3
	s_sext_i32_i16 s3, s2
	s_mulk_i32 s2, 0x58
	s_sub_i32 s2, s19, s2
	s_sext_i32_i16 s2, s2
	s_lshl_b32 s2, s2, 5
	s_lshl_b32 s8, s3, 6
	s_ashr_i32 s3, s2, 31
	s_lshl_b64 s[20:21], s[2:3], 2
	s_add_u32 s20, s9, s20
	v_add_u32_e32 v35, s8, v3
	s_addc_u32 s21, s22, s21
	v_lshl_add_u64 v[22:23], s[20:21], 0, v[0:1]
	s_movk_i32 s3, 0x2c00
	v_add_u32_e32 v0, 8, v35
	v_mad_i64_i32 v[36:37], s[20:21], v35, s3, v[22:23]
	v_mad_i64_i32 v[40:41], s[20:21], v0, s3, v[22:23]
	global_load_dwordx4 v[36:39], v[36:37], off nt
	v_add_u32_e32 v0, 16, v35
	global_load_dwordx4 v[40:43], v[40:41], off nt
	v_mad_i64_i32 v[44:45], s[20:21], v0, s3, v[22:23]
	global_load_dwordx4 v[44:47], v[44:45], off nt
	v_add_u32_e32 v0, 24, v35
	v_mad_i64_i32 v[48:49], s[20:21], v0, s3, v[22:23]
	global_load_dwordx4 v[48:51], v[48:49], off nt
	v_add_u32_e32 v0, 32, v35
	v_mad_i64_i32 v[52:53], s[20:21], v0, s3, v[22:23]
	global_load_dwordx4 v[52:55], v[52:53], off nt
	v_add_u32_e32 v0, 40, v35
	v_mad_i64_i32 v[56:57], s[20:21], v0, s3, v[22:23]
	global_load_dwordx4 v[56:59], v[56:57], off nt
	v_add_u32_e32 v0, 48, v35
	v_mad_i64_i32 v[60:61], s[20:21], v0, s3, v[22:23]
	global_load_dwordx4 v[60:63], v[60:61], off nt
	v_add_u32_e32 v0, 56, v35
	v_mad_i64_i32 v[22:23], s[20:21], v0, s3, v[22:23]
	global_load_dwordx4 v[64:67], v[22:23], off nt
	v_add_u32_e32 v0, v29, v5
	v_add_u32_e32 v22, 0x420, v0
	s_ashr_i32 s9, s8, 31
	s_lshl_b64 s[8:9], s[8:9], 1
	s_add_u32 s8, s17, s8
	s_addc_u32 s9, s18, s9
	s_waitcnt vmcnt(7)
	ds_write2_b32 v0, v36, v37 offset1:1
	ds_write2_b32 v0, v38, v39 offset0:2 offset1:3
	s_waitcnt vmcnt(6)
	ds_write2_b32 v22, v40, v41 offset1:1
	v_add_u32_e32 v22, 0x428, v0
	ds_write2_b32 v22, v42, v43 offset1:1
	v_add_u32_e32 v22, 0x840, v0
	s_waitcnt vmcnt(5)
	ds_write2_b32 v22, v44, v45 offset1:1
	v_add_u32_e32 v22, 0x848, v0
	ds_write2_b32 v22, v46, v47 offset1:1
	v_add_u32_e32 v22, 0xc60, v0
	s_waitcnt vmcnt(4)
	ds_write2_b32 v22, v48, v49 offset1:1
	v_add_u32_e32 v22, 0xc68, v0
	ds_write2_b32 v22, v50, v51 offset1:1
	v_add_u32_e32 v22, 0x1080, v0
	s_waitcnt vmcnt(3)
	ds_write2_b32 v22, v52, v53 offset1:1
	v_add_u32_e32 v22, 0x1088, v0
	ds_write2_b32 v22, v54, v55 offset1:1
	v_add_u32_e32 v22, 0x14a0, v0
	s_waitcnt vmcnt(2)
	ds_write2_b32 v22, v56, v57 offset1:1
	v_add_u32_e32 v22, 0x14a8, v0
	ds_write2_b32 v22, v58, v59 offset1:1
	v_add_u32_e32 v22, 0x18c0, v0
	s_waitcnt vmcnt(1)
	ds_write2_b32 v22, v60, v61 offset1:1
	v_add_u32_e32 v22, 0x18c8, v0
	ds_write2_b32 v22, v62, v63 offset1:1
	v_add_u32_e32 v22, 0x1ce0, v0
	v_add_u32_e32 v0, 0x1ce8, v0
	s_waitcnt vmcnt(0)
	ds_write2_b32 v22, v64, v65 offset1:1
	ds_write2_b32 v0, v66, v67 offset1:1
	s_waitcnt lgkmcnt(0)
	v_lshlrev_b32_e32 v0, 1, v4
	ds_read2_b32 v[42:43], v28 offset0:33 offset1:41
	ds_read2_b32 v[44:45], v28 offset1:8
	ds_read2_b32 v[46:47], v28 offset0:66 offset1:74
	ds_read2_b32 v[48:49], v28 offset0:99 offset1:107
	ds_read2_b32 v[50:51], v28 offset0:132 offset1:140
	ds_read2_b32 v[52:53], v28 offset0:165 offset1:173
	ds_read2_b32 v[54:55], v28 offset0:198 offset1:206
	ds_read2_b32 v[56:57], v28 offset0:231 offset1:239
	v_lshl_add_u64 v[22:23], s[8:9], 0, v[0:1]
	v_add_lshl_u32 v0, s2, v3, 1
	v_and_or_b32 v40, v0, s43, v27
	v_ashrrev_i32_e32 v41, 31, v40
	v_lshlrev_b64 v[40:41], 11, v[40:41]
	s_waitcnt lgkmcnt(6)
	v_cvt_pk_bf16_f32 v36, v44, v42
	s_waitcnt lgkmcnt(4)
	v_cvt_pk_bf16_f32 v37, v46, v48
	s_waitcnt lgkmcnt(2)
	v_cvt_pk_bf16_f32 v38, v50, v52
	s_waitcnt lgkmcnt(0)
	v_cvt_pk_bf16_f32 v39, v54, v56
	v_lshl_add_u64 v[40:41], v[22:23], 0, v[40:41]
	v_add_lshl_u32 v0, s2, v24, 1
	global_store_dwordx4 v[40:41], v[36:39], off sc1
	v_and_or_b32 v40, v0, s43, v30
	v_ashrrev_i32_e32 v41, 31, v40
	v_lshlrev_b64 v[40:41], 11, v[40:41]
	v_cvt_pk_bf16_f32 v36, v45, v43
	v_cvt_pk_bf16_f32 v37, v47, v49
	v_cvt_pk_bf16_f32 v38, v51, v53
	v_cvt_pk_bf16_f32 v39, v55, v57
	v_lshl_add_u64 v[40:41], v[22:23], 0, v[40:41]
	global_store_dwordx4 v[40:41], v[36:39], off sc1
	ds_read2_b32 v[42:43], v28 offset0:16 offset1:24
	ds_read2_b32 v[44:45], v28 offset0:49 offset1:57
	ds_read2_b32 v[46:47], v28 offset0:82 offset1:90
	ds_read2_b32 v[48:49], v28 offset0:115 offset1:123
	ds_read2_b32 v[50:51], v28 offset0:148 offset1:156
	ds_read2_b32 v[52:53], v28 offset0:181 offset1:189
	ds_read2_b32 v[54:55], v28 offset0:214 offset1:222
	ds_read2_b32 v[56:57], v28 offset0:247 offset1:255
	v_add_lshl_u32 v0, s2, v25, 1
	v_and_or_b32 v40, v0, s43, v27
	v_ashrrev_i32_e32 v41, 31, v40
	v_lshlrev_b64 v[40:41], 11, v[40:41]
	s_waitcnt lgkmcnt(6)
	v_cvt_pk_bf16_f32 v36, v42, v44
	s_waitcnt lgkmcnt(4)
	v_cvt_pk_bf16_f32 v37, v46, v48
	s_waitcnt lgkmcnt(2)
	v_cvt_pk_bf16_f32 v38, v50, v52
	s_waitcnt lgkmcnt(0)
	v_cvt_pk_bf16_f32 v39, v54, v56
	v_lshl_add_u64 v[40:41], v[22:23], 0, v[40:41]
	v_add_lshl_u32 v0, s2, v26, 1
	global_store_dwordx4 v[40:41], v[36:39], off sc1
	v_and_or_b32 v40, v0, s43, v31
	v_ashrrev_i32_e32 v41, 31, v40
	v_lshlrev_b64 v[40:41], 11, v[40:41]
	v_cvt_pk_bf16_f32 v36, v43, v45
	v_cvt_pk_bf16_f32 v37, v47, v49
	v_cvt_pk_bf16_f32 v38, v51, v53
	v_cvt_pk_bf16_f32 v39, v55, v57
	v_lshl_add_u64 v[22:23], v[22:23], 0, v[40:41]
	global_store_dwordx4 v[22:23], v[36:39], off sc1
	s_waitcnt lgkmcnt(0)
	s_branch .LBB0_849
